# MFMA order inside every 32-MFMA K-loop segment: the two k-steps of each accumulator are issued back to back (order n,m,k), so the second MFMA takes its C input through the matrix pipe's accumulate-cha
# speedup vs baseline: 1.0193x; 1.0179x over previous
; #define PG8_STAGE(bufoff, gbase, voff) do { _Pragma("unroll") for (int _i = 0; _i < 2; ++_i) \
;         __builtin_amdgcn_global_load_lds((const unsigned*)((const char*)(gbase) + (voff)[_i]), (PG8_LAS unsigned*)(lds + (bufoff) + ldsw + _i * 8192), 16, 0, 0); } while (0)
; #define PG8_LDA(dst, b, h) do { _Pragma("unroll") for (int m = 0; m < 4; ++m) _Pragma("unroll") for (int k = 0; k < 2; ++k) dst[m][k] = *(const PG8_LAS bf16x8*)(lds + PG8_SA(b, h) + aoff + m * 2048 + k * 1024); } while (0)
; #define PG8_LDB(dst, b, h) do { _Pragma("unroll") for (int n = 0; n < 2; ++n) _Pragma("unroll") for (int k = 0; k < 2; ++k) dst[n][k] = *(const PG8_LAS bf16x8*)(lds + PG8_SB(b, h) + boff + n * 2048 + k * 1024); } while (0)
; #define PG8_MMA(ai, bj, At, Bt) do { __builtin_amdgcn_s_setprio(1); _Pragma("unroll") for (int m = 0; m < 4; ++m) _Pragma("unroll") for (int n = 0; n < 2; ++n) _Pragma("unroll") for (int k = 0; k < 2; ++k) \
;         acc[ai][bj][m][n] = __builtin_amdgcn_mfma_f32_16x16x32_bf16(Bt[n][k], At[m][k], acc[ai][bj][m][n], 0, 0, 0); __builtin_amdgcn_s_setprio(0); } while (0)
; #define PG8_WAIT_V(n) asm volatile("s_waitcnt vmcnt(" #n ")" ::: "memory")
; #define PG8_WAIT_L(n) asm volatile("s_waitcnt lgkmcnt(" #n ")" ::: "memory")
; #define PG8_BAR __builtin_amdgcn_s_barrier()
; #define PG8_SCHED __builtin_amdgcn_sched_barrier(0)
; template <class Epi, class Sched, bool ALIGN_EPI = false, bool SP2 = false>
; __device__ __forceinline__ void gemm_phase(PG8_LAS unsigned char* lds, const Gemm g, const Sched& S, const Epi& E) {
;     ...
;             PG8_LDB(B0, 0, 0); PG8_LDB(B1, 0, 1); PG8_SCHED; PG8_LDA(At, 0, 0); PG8_STAGE(PG8_SA(1, 1), a1 + hstep, voffA);
;             PG8_WAIT_V(8); PG8_WAIT_L(0); PG8_BAR; PG8_MMA(0, 0, At, B0); PG8_MMA(0, 1, At, B1); PG8_BAR; PG8_SCHED;
;             PG8_LDA(At, 0, 1); PG8_STAGE(PG8_SB(0, 0), b2, voffB); PG8_STAGE(PG8_SB(0, 1), b2 + hstep, voffB); PG8_STAGE(PG8_SA(0, 0), a2, voffA);
;             PG8_WAIT_V(8); PG8_WAIT_L(0); PG8_BAR; PG8_MMA(1, 0, At, B0); PG8_MMA(1, 1, At, B1); PG8_BAR; PG8_SCHED;
.Labo_peel:
	ds_read_b128 v[68:71], v254
	ds_read_b128 v[72:75], v254 offset:1024
	ds_read_b128 v[76:79], v254 offset:2048
	ds_read_b128 v[80:83], v254 offset:3072
	ds_read_b128 v[174:177], v254 offset:16384
	ds_read_b128 v[182:185], v254 offset:17408
	ds_read_b128 v[186:189], v254 offset:18432
	ds_read_b128 v[210:213], v254 offset:19456
	s_add_u32 s2, s0, 0xfffc0080
	s_addc_u32 s3, s1, -1
	s_cmp_eq_u32 s56, 12
	s_cselect_b32 s5, s27, s3
	s_cselect_b32 s4, s52, s2
	s_cselect_b32 s3, s25, s55
	s_cselect_b32 s2, s53, s54
	s_add_i32 m0, s29, 0xc000
	ds_read_b128 v[214:217], v179
	ds_read_b128 v[218:221], v179 offset:1024
	ds_read_b128 v[222:225], v179 offset:2048
	ds_read_b128 v[226:229], v179 offset:3072
	ds_read_b128 v[230:233], v179 offset:4096
	ds_read_b128 v[234:237], v179 offset:5120
	ds_read_b128 v[238:241], v179 offset:6144
	ds_read_b128 v[242:245], v179 offset:7168
	global_load_lds_dwordx4 v170, s[0:1]
	s_add_i32 m0, s29, 0xe000
	s_nop 0
	global_load_lds_dwordx4 v172, s[0:1]
	s_waitcnt vmcnt(8)
	s_waitcnt lgkmcnt(0)
	s_barrier
	s_setprio 1
	v_mfma_f32_16x16x32_bf16 v[140:143], v[68:71], v[214:217], 0
	v_mfma_f32_16x16x32_bf16 v[140:143], v[72:75], v[218:221], v[140:143]
	v_mfma_f32_16x16x32_bf16 v[124:127], v[68:71], v[222:225], 0
	v_mfma_f32_16x16x32_bf16 v[124:127], v[72:75], v[226:229], v[124:127]
	v_mfma_f32_16x16x32_bf16 v[108:111], v[68:71], v[230:233], 0
	v_mfma_f32_16x16x32_bf16 v[108:111], v[72:75], v[234:237], v[108:111]
	v_mfma_f32_16x16x32_bf16 v[92:95], v[68:71], v[238:241], 0
	v_mfma_f32_16x16x32_bf16 v[92:95], v[72:75], v[242:245], v[92:95]
	v_mfma_f32_16x16x32_bf16 v[136:139], v[76:79], v[214:217], 0
	v_mfma_f32_16x16x32_bf16 v[136:139], v[80:83], v[218:221], v[136:139]
	v_mfma_f32_16x16x32_bf16 v[120:123], v[76:79], v[222:225], 0
	v_mfma_f32_16x16x32_bf16 v[120:123], v[80:83], v[226:229], v[120:123]
	v_mfma_f32_16x16x32_bf16 v[104:107], v[76:79], v[230:233], 0
	v_mfma_f32_16x16x32_bf16 v[104:107], v[80:83], v[234:237], v[104:107]
	v_mfma_f32_16x16x32_bf16 v[88:91], v[76:79], v[238:241], 0
	v_mfma_f32_16x16x32_bf16 v[88:91], v[80:83], v[242:245], v[88:91]
	v_mfma_f32_16x16x32_bf16 v[132:135], v[174:177], v[214:217], 0
	v_mfma_f32_16x16x32_bf16 v[132:135], v[182:185], v[218:221], v[132:135]
	v_mfma_f32_16x16x32_bf16 v[116:119], v[174:177], v[222:225], 0
	v_mfma_f32_16x16x32_bf16 v[116:119], v[182:185], v[226:229], v[116:119]
	v_mfma_f32_16x16x32_bf16 v[100:103], v[174:177], v[230:233], 0
	v_mfma_f32_16x16x32_bf16 v[100:103], v[182:185], v[234:237], v[100:103]
	v_mfma_f32_16x16x32_bf16 v[84:87], v[174:177], v[238:241], 0
	v_mfma_f32_16x16x32_bf16 v[84:87], v[182:185], v[242:245], v[84:87]
	v_mfma_f32_16x16x32_bf16 v[128:131], v[186:189], v[214:217], 0
	v_mfma_f32_16x16x32_bf16 v[128:131], v[210:213], v[218:221], v[128:131]
	v_mfma_f32_16x16x32_bf16 v[112:115], v[186:189], v[222:225], 0
	v_mfma_f32_16x16x32_bf16 v[112:115], v[210:213], v[226:229], v[112:115]
	v_mfma_f32_16x16x32_bf16 v[96:99], v[186:189], v[230:233], 0
	v_mfma_f32_16x16x32_bf16 v[96:99], v[210:213], v[234:237], v[96:99]
	v_mfma_f32_16x16x32_bf16 v[64:67], v[186:189], v[238:241], 0
	v_mfma_f32_16x16x32_bf16 v[64:67], v[210:213], v[242:245], v[64:67]
	s_setprio 0
	s_barrier
	s_mov_b32 m0, s30
	s_add_u32 s58, s2, 0x40000
	s_addc_u32 s59, s3, 0
	ds_read_b128 v[214:217], v179 offset:16384
	ds_read_b128 v[218:221], v179 offset:17408
	ds_read_b128 v[222:225], v179 offset:18432
	ds_read_b128 v[226:229], v179 offset:19456
	ds_read_b128 v[230:233], v179 offset:20480
	ds_read_b128 v[234:237], v179 offset:21504
	ds_read_b128 v[238:241], v179 offset:22528
	ds_read_b128 v[242:245], v179 offset:23552
	global_load_lds_dwordx4 v166, s[2:3]
	s_mov_b32 m0, s31
	s_nop 0
	global_load_lds_dwordx4 v162, s[2:3]
	s_mov_b32 m0, s33
	s_nop 0
	global_load_lds_dwordx4 v166, s[58:59]
	s_mov_b32 m0, s34
	s_nop 0
	global_load_lds_dwordx4 v162, s[58:59]
	s_mov_b32 m0, s29
	s_nop 0
	global_load_lds_dwordx4 v168, s[4:5]
	s_mov_b32 m0, s35
	s_nop 0
	global_load_lds_dwordx4 v164, s[4:5]
	s_waitcnt vmcnt(8)
	s_waitcnt lgkmcnt(0)
	s_barrier
	s_setprio 1
	v_mfma_f32_16x16x32_bf16 v[60:63], v[68:71], v[214:217], 0
	v_mfma_f32_16x16x32_bf16 v[60:63], v[72:75], v[218:221], v[60:63]
	v_mfma_f32_16x16x32_bf16 v[44:47], v[68:71], v[222:225], 0
	v_mfma_f32_16x16x32_bf16 v[44:47], v[72:75], v[226:229], v[44:47]
	v_mfma_f32_16x16x32_bf16 v[28:31], v[68:71], v[230:233], 0
	v_mfma_f32_16x16x32_bf16 v[28:31], v[72:75], v[234:237], v[28:31]
	v_mfma_f32_16x16x32_bf16 v[12:15], v[68:71], v[238:241], 0
	v_mfma_f32_16x16x32_bf16 v[12:15], v[72:75], v[242:245], v[12:15]
	v_mfma_f32_16x16x32_bf16 v[56:59], v[76:79], v[214:217], 0
	v_mfma_f32_16x16x32_bf16 v[56:59], v[80:83], v[218:221], v[56:59]
	v_mfma_f32_16x16x32_bf16 v[40:43], v[76:79], v[222:225], 0
	v_mfma_f32_16x16x32_bf16 v[40:43], v[80:83], v[226:229], v[40:43]
	v_mfma_f32_16x16x32_bf16 v[24:27], v[76:79], v[230:233], 0
	v_mfma_f32_16x16x32_bf16 v[24:27], v[80:83], v[234:237], v[24:27]
	v_mfma_f32_16x16x32_bf16 v[8:11], v[76:79], v[238:241], 0
	v_mfma_f32_16x16x32_bf16 v[8:11], v[80:83], v[242:245], v[8:11]
	v_mfma_f32_16x16x32_bf16 v[52:55], v[174:177], v[214:217], 0
	v_mfma_f32_16x16x32_bf16 v[52:55], v[182:185], v[218:221], v[52:55]
	v_mfma_f32_16x16x32_bf16 v[36:39], v[174:177], v[222:225], 0
	v_mfma_f32_16x16x32_bf16 v[36:39], v[182:185], v[226:229], v[36:39]
	v_mfma_f32_16x16x32_bf16 v[20:23], v[174:177], v[230:233], 0
	v_mfma_f32_16x16x32_bf16 v[20:23], v[182:185], v[234:237], v[20:23]
	v_mfma_f32_16x16x32_bf16 v[4:7], v[174:177], v[238:241], 0
	v_mfma_f32_16x16x32_bf16 v[4:7], v[182:185], v[242:245], v[4:7]
	v_mfma_f32_16x16x32_bf16 v[48:51], v[186:189], v[214:217], 0
	v_mfma_f32_16x16x32_bf16 v[48:51], v[210:213], v[218:221], v[48:51]
	v_mfma_f32_16x16x32_bf16 v[32:35], v[186:189], v[222:225], 0
	v_mfma_f32_16x16x32_bf16 v[32:35], v[210:213], v[226:229], v[32:35]
	v_mfma_f32_16x16x32_bf16 v[16:19], v[186:189], v[230:233], 0
	v_mfma_f32_16x16x32_bf16 v[16:19], v[210:213], v[234:237], v[16:19]
	v_mfma_f32_16x16x32_bf16 v[0:3], v[186:189], v[238:241], 0
	v_mfma_f32_16x16x32_bf16 v[0:3], v[210:213], v[242:245], v[0:3]
	s_setprio 0
	s_barrier
; #define PG8_STAGE(bufoff, gbase, voff) do { _Pragma("unroll") for (int _i = 0; _i < 2; ++_i) \
;         __builtin_amdgcn_global_load_lds((const unsigned*)((const char*)(gbase) + (voff)[_i]), (PG8_LAS unsigned*)(lds + (bufoff) + ldsw + _i * 8192), 16, 0, 0); } while (0)
; #define PG8_LDA(dst, b, h) do { _Pragma("unroll") for (int m = 0; m < 4; ++m) _Pragma("unroll") for (int k = 0; k < 2; ++k) dst[m][k] = *(const PG8_LAS bf16x8*)(lds + PG8_SA(b, h) + aoff + m * 2048 + k * 1024); } while (0)
; #define PG8_LDB(dst, b, h) do { _Pragma("unroll") for (int n = 0; n < 2; ++n) _Pragma("unroll") for (int k = 0; k < 2; ++k) dst[n][k] = *(const PG8_LAS bf16x8*)(lds + PG8_SB(b, h) + boff + n * 2048 + k * 1024); } while (0)
; #define PG8_MMA(ai, bj, At, Bt) do { __builtin_amdgcn_s_setprio(1); _Pragma("unroll") for (int m = 0; m < 4; ++m) _Pragma("unroll") for (int n = 0; n < 2; ++n) _Pragma("unroll") for (int k = 0; k < 2; ++k) \
;         acc[ai][bj][m][n] = __builtin_amdgcn_mfma_f32_16x16x32_bf16(Bt[n][k], At[m][k], acc[ai][bj][m][n], 0, 0, 0); __builtin_amdgcn_s_setprio(0); } while (0)
; #define PG8_WAIT_V(n) asm volatile("s_waitcnt vmcnt(" #n ")" ::: "memory")
; #define PG8_WAIT_L(n) asm volatile("s_waitcnt lgkmcnt(" #n ")" ::: "memory")
; #define PG8_BAR __builtin_amdgcn_s_barrier()
; #define PG8_SCHED __builtin_amdgcn_sched_barrier(0)
; template <class Epi, class Sched, bool ALIGN_EPI = false, bool SP2 = false>
; __device__ __forceinline__ void gemm_phase(PG8_LAS unsigned char* lds, const Gemm g, const Sched& S, const Epi& E) {
;     ...
;             PG8_LDB(B0, 1, 0); PG8_LDB(B1, 1, 1); PG8_SCHED; PG8_LDA(At, 1, 0); PG8_STAGE(PG8_SA(0, 1), a2 + hstep, voffA);
;             PG8_WAIT_V(8); PG8_WAIT_L(0); PG8_BAR; PG8_MMA(0, 0, At, B0); PG8_MMA(0, 1, At, B1); PG8_BAR; PG8_SCHED;
;             PG8_LDA(At, 1, 1); PG8_STAGE(PG8_SB(1, 0), b3, voffB); PG8_STAGE(PG8_SB(1, 1), b3 + hstep, voffB); PG8_STAGE(PG8_SA(1, 0), a3, voffA);
;             PG8_WAIT_V(8); PG8_WAIT_L(0); PG8_BAR; PG8_MMA(1, 0, At, B0); PG8_MMA(1, 1, At, B1); PG8_BAR; PG8_SCHED;
	ds_read_b128 v[68:71], v254 offset:32768
	ds_read_b128 v[72:75], v254 offset:33792
	ds_read_b128 v[76:79], v254 offset:34816
	ds_read_b128 v[80:83], v254 offset:35840
	ds_read_b128 v[174:177], v254 offset:49152
	ds_read_b128 v[182:185], v254 offset:50176
	ds_read_b128 v[186:189], v254 offset:51200
	ds_read_b128 v[210:213], v254 offset:52224
	s_add_u32 s4, s4, 0x40000
	s_addc_u32 s5, s5, 0
	s_mov_b32 m0, s40
	ds_read_b128 v[214:217], v179 offset:32768
	ds_read_b128 v[218:221], v179 offset:33792
	ds_read_b128 v[222:225], v179 offset:34816
	ds_read_b128 v[226:229], v179 offset:35840
	ds_read_b128 v[230:233], v179 offset:36864
	ds_read_b128 v[234:237], v179 offset:37888
	ds_read_b128 v[238:241], v179 offset:38912
	ds_read_b128 v[242:245], v179 offset:39936
	global_load_lds_dwordx4 v168, s[4:5]
	s_mov_b32 m0, s41
	s_nop 0
	global_load_lds_dwordx4 v164, s[4:5]
	s_waitcnt vmcnt(8)
	s_waitcnt lgkmcnt(0)
	s_barrier
	s_setprio 1
	v_mfma_f32_16x16x32_bf16 v[140:143], v[68:71], v[214:217], v[140:143]
	v_mfma_f32_16x16x32_bf16 v[140:143], v[72:75], v[218:221], v[140:143]
	v_mfma_f32_16x16x32_bf16 v[124:127], v[68:71], v[222:225], v[124:127]
	v_mfma_f32_16x16x32_bf16 v[124:127], v[72:75], v[226:229], v[124:127]
	v_mfma_f32_16x16x32_bf16 v[108:111], v[68:71], v[230:233], v[108:111]
	v_mfma_f32_16x16x32_bf16 v[108:111], v[72:75], v[234:237], v[108:111]
	v_mfma_f32_16x16x32_bf16 v[92:95], v[68:71], v[238:241], v[92:95]
	v_mfma_f32_16x16x32_bf16 v[92:95], v[72:75], v[242:245], v[92:95]
	v_mfma_f32_16x16x32_bf16 v[136:139], v[76:79], v[214:217], v[136:139]
	v_mfma_f32_16x16x32_bf16 v[136:139], v[80:83], v[218:221], v[136:139]
	v_mfma_f32_16x16x32_bf16 v[120:123], v[76:79], v[222:225], v[120:123]
	v_mfma_f32_16x16x32_bf16 v[120:123], v[80:83], v[226:229], v[120:123]
	v_mfma_f32_16x16x32_bf16 v[104:107], v[76:79], v[230:233], v[104:107]
	v_mfma_f32_16x16x32_bf16 v[104:107], v[80:83], v[234:237], v[104:107]
	v_mfma_f32_16x16x32_bf16 v[88:91], v[76:79], v[238:241], v[88:91]
	v_mfma_f32_16x16x32_bf16 v[88:91], v[80:83], v[242:245], v[88:91]
	v_mfma_f32_16x16x32_bf16 v[132:135], v[174:177], v[214:217], v[132:135]
	v_mfma_f32_16x16x32_bf16 v[132:135], v[182:185], v[218:221], v[132:135]
	v_mfma_f32_16x16x32_bf16 v[116:119], v[174:177], v[222:225], v[116:119]
	v_mfma_f32_16x16x32_bf16 v[116:119], v[182:185], v[226:229], v[116:119]
	v_mfma_f32_16x16x32_bf16 v[100:103], v[174:177], v[230:233], v[100:103]
	v_mfma_f32_16x16x32_bf16 v[100:103], v[182:185], v[234:237], v[100:103]
	v_mfma_f32_16x16x32_bf16 v[84:87], v[174:177], v[238:241], v[84:87]
	v_mfma_f32_16x16x32_bf16 v[84:87], v[182:185], v[242:245], v[84:87]
	v_mfma_f32_16x16x32_bf16 v[128:131], v[186:189], v[214:217], v[128:131]
	v_mfma_f32_16x16x32_bf16 v[128:131], v[210:213], v[218:221], v[128:131]
	v_mfma_f32_16x16x32_bf16 v[112:115], v[186:189], v[222:225], v[112:115]
	v_mfma_f32_16x16x32_bf16 v[112:115], v[210:213], v[226:229], v[112:115]
	v_mfma_f32_16x16x32_bf16 v[96:99], v[186:189], v[230:233], v[96:99]
	v_mfma_f32_16x16x32_bf16 v[96:99], v[210:213], v[234:237], v[96:99]
	v_mfma_f32_16x16x32_bf16 v[64:67], v[186:189], v[238:241], v[64:67]
	v_mfma_f32_16x16x32_bf16 v[64:67], v[210:213], v[242:245], v[64:67]
	s_setprio 0
	s_barrier
	s_mov_b32 m0, s45
	s_add_u32 s2, s2, 0x40080
	s_addc_u32 s3, s3, 0
	ds_read_b128 v[214:217], v179 offset:49152
	ds_read_b128 v[218:221], v179 offset:50176
	ds_read_b128 v[222:225], v179 offset:51200
	ds_read_b128 v[226:229], v179 offset:52224
	ds_read_b128 v[230:233], v179 offset:53248
	ds_read_b128 v[234:237], v179 offset:54272
	ds_read_b128 v[238:241], v179 offset:55296
	ds_read_b128 v[242:245], v179 offset:56320
	s_add_u32 s98, s2, 0xfffc0000
	s_addc_u32 s99, s3, -1
	global_load_lds_dwordx4 v166, s[98:99]
	s_mov_b32 m0, s46
	s_nop 0
	global_load_lds_dwordx4 v162, s[98:99]
	s_mov_b32 m0, s49
	s_nop 0
	global_load_lds_dwordx4 v166, s[2:3]
	s_mov_b32 m0, s50
	s_nop 0
	global_load_lds_dwordx4 v162, s[2:3]
	s_mov_b32 m0, s47
	s_nop 0
	s_add_u32 s100, s4, 0xfffc0080
	s_addc_u32 s101, s5, -1
	global_load_lds_dwordx4 v168, s[100:101]
	s_mov_b32 m0, s48
	s_nop 0
	global_load_lds_dwordx4 v164, s[100:101]
	s_waitcnt vmcnt(8)
	s_waitcnt lgkmcnt(0)
	s_barrier
	s_setprio 1
	v_mfma_f32_16x16x32_bf16 v[60:63], v[68:71], v[214:217], v[60:63]
	v_mfma_f32_16x16x32_bf16 v[60:63], v[72:75], v[218:221], v[60:63]
	v_mfma_f32_16x16x32_bf16 v[44:47], v[68:71], v[222:225], v[44:47]
	v_mfma_f32_16x16x32_bf16 v[44:47], v[72:75], v[226:229], v[44:47]
	v_mfma_f32_16x16x32_bf16 v[28:31], v[68:71], v[230:233], v[28:31]
	v_mfma_f32_16x16x32_bf16 v[28:31], v[72:75], v[234:237], v[28:31]
	v_mfma_f32_16x16x32_bf16 v[12:15], v[68:71], v[238:241], v[12:15]
	v_mfma_f32_16x16x32_bf16 v[12:15], v[72:75], v[242:245], v[12:15]
	v_mfma_f32_16x16x32_bf16 v[56:59], v[76:79], v[214:217], v[56:59]
	v_mfma_f32_16x16x32_bf16 v[56:59], v[80:83], v[218:221], v[56:59]
	v_mfma_f32_16x16x32_bf16 v[40:43], v[76:79], v[222:225], v[40:43]
	v_mfma_f32_16x16x32_bf16 v[40:43], v[80:83], v[226:229], v[40:43]
	v_mfma_f32_16x16x32_bf16 v[24:27], v[76:79], v[230:233], v[24:27]
	v_mfma_f32_16x16x32_bf16 v[24:27], v[80:83], v[234:237], v[24:27]
	v_mfma_f32_16x16x32_bf16 v[8:11], v[76:79], v[238:241], v[8:11]
	v_mfma_f32_16x16x32_bf16 v[8:11], v[80:83], v[242:245], v[8:11]
	v_mfma_f32_16x16x32_bf16 v[52:55], v[174:177], v[214:217], v[52:55]
	v_mfma_f32_16x16x32_bf16 v[52:55], v[182:185], v[218:221], v[52:55]
	v_mfma_f32_16x16x32_bf16 v[36:39], v[174:177], v[222:225], v[36:39]
	v_mfma_f32_16x16x32_bf16 v[36:39], v[182:185], v[226:229], v[36:39]
	v_mfma_f32_16x16x32_bf16 v[20:23], v[174:177], v[230:233], v[20:23]
	v_mfma_f32_16x16x32_bf16 v[20:23], v[182:185], v[234:237], v[20:23]
	v_mfma_f32_16x16x32_bf16 v[4:7], v[174:177], v[238:241], v[4:7]
	v_mfma_f32_16x16x32_bf16 v[4:7], v[182:185], v[242:245], v[4:7]
	v_mfma_f32_16x16x32_bf16 v[48:51], v[186:189], v[214:217], v[48:51]
	v_mfma_f32_16x16x32_bf16 v[48:51], v[210:213], v[218:221], v[48:51]
	v_mfma_f32_16x16x32_bf16 v[32:35], v[186:189], v[222:225], v[32:35]
	v_mfma_f32_16x16x32_bf16 v[32:35], v[210:213], v[226:229], v[32:35]
	v_mfma_f32_16x16x32_bf16 v[16:19], v[186:189], v[230:233], v[16:19]
	v_mfma_f32_16x16x32_bf16 v[16:19], v[210:213], v[234:237], v[16:19]
	v_mfma_f32_16x16x32_bf16 v[0:3], v[186:189], v[238:241], v[0:3]
	v_mfma_f32_16x16x32_bf16 v[0:3], v[210:213], v[242:245], v[0:3]
	s_setprio 0
	s_barrier
	s_add_i32 s56, s56, 2
	s_add_u32 s0, s0, 0x100
	s_addc_u32 s1, s1, 0
	s_add_u32 s54, s54, 0x100
	s_addc_u32 s55, s55, 0
	s_cmp_gt_u32 s56, 13
; #define PG8_STAGE(bufoff, gbase, voff) do { _Pragma("unroll") for (int _i = 0; _i < 2; ++_i) \
;         __builtin_amdgcn_global_load_lds((const unsigned*)((const char*)(gbase) + (voff)[_i]), (PG8_LAS unsigned*)(lds + (bufoff) + ldsw + _i * 8192), 16, 0, 0); } while (0)
; #define PG8_LDA(dst, b, h) do { _Pragma("unroll") for (int m = 0; m < 4; ++m) _Pragma("unroll") for (int k = 0; k < 2; ++k) dst[m][k] = *(const PG8_LAS bf16x8*)(lds + PG8_SA(b, h) + aoff + m * 2048 + k * 1024); } while (0)
; #define PG8_LDB(dst, b, h) do { _Pragma("unroll") for (int n = 0; n < 2; ++n) _Pragma("unroll") for (int k = 0; k < 2; ++k) dst[n][k] = *(const PG8_LAS bf16x8*)(lds + PG8_SB(b, h) + boff + n * 2048 + k * 1024); } while (0)
; #define PG8_MMA(ai, bj, At, Bt) do { __builtin_amdgcn_s_setprio(1); _Pragma("unroll") for (int m = 0; m < 4; ++m) _Pragma("unroll") for (int n = 0; n < 2; ++n) _Pragma("unroll") for (int k = 0; k < 2; ++k) \
;         acc[ai][bj][m][n] = __builtin_amdgcn_mfma_f32_16x16x32_bf16(Bt[n][k], At[m][k], acc[ai][bj][m][n], 0, 0, 0); __builtin_amdgcn_s_setprio(0); } while (0)
; #define PG8_WAIT_V(n) asm volatile("s_waitcnt vmcnt(" #n ")" ::: "memory")
; #define PG8_WAIT_L(n) asm volatile("s_waitcnt lgkmcnt(" #n ")" ::: "memory")
; #define PG8_BAR __builtin_amdgcn_s_barrier()
; #define PG8_SCHED __builtin_amdgcn_sched_barrier(0)
; template <class Epi, class Sched, bool ALIGN_EPI = false, bool SP2 = false>
; __device__ __forceinline__ void gemm_phase(PG8_LAS unsigned char* lds, const Gemm g, const Sched& S, const Epi& E) {
;     ...
;             PG8_LDB(B0, 0, 0); PG8_LDB(B1, 0, 1); PG8_SCHED; PG8_LDA(At, 0, 0); PG8_STAGE(PG8_SA(1, 1), a1 + hstep, voffA);
;             PG8_WAIT_V(8); PG8_WAIT_L(0); PG8_BAR; PG8_MMA(0, 0, At, B0); PG8_MMA(0, 1, At, B1); PG8_BAR; PG8_SCHED;
;             PG8_LDA(At, 0, 1); PG8_STAGE(PG8_SB(0, 0), b2, voffB); PG8_STAGE(PG8_SB(0, 1), b2 + hstep, voffB); PG8_STAGE(PG8_SA(0, 0), a2, voffA);
;             PG8_WAIT_V(8); PG8_WAIT_L(0); PG8_BAR; PG8_MMA(1, 0, At, B0); PG8_MMA(1, 1, At, B1); PG8_BAR; PG8_SCHED;
.LBB0_327:
	ds_read_b128 v[68:71], v254
	ds_read_b128 v[72:75], v254 offset:1024
	ds_read_b128 v[76:79], v254 offset:2048
	ds_read_b128 v[80:83], v254 offset:3072
	ds_read_b128 v[174:177], v254 offset:16384
	ds_read_b128 v[182:185], v254 offset:17408
	ds_read_b128 v[186:189], v254 offset:18432
	ds_read_b128 v[210:213], v254 offset:19456
	s_add_u32 s2, s0, 0xfffc0080
	s_addc_u32 s3, s1, -1
	s_cmp_eq_u32 s56, 12
	s_cselect_b32 s5, s27, s3
	s_cselect_b32 s4, s52, s2
	s_cselect_b32 s3, s25, s55
	s_cselect_b32 s2, s53, s54
	s_add_i32 m0, s29, 0xc000
	ds_read_b128 v[214:217], v179
	ds_read_b128 v[218:221], v179 offset:1024
	ds_read_b128 v[222:225], v179 offset:2048
	ds_read_b128 v[226:229], v179 offset:3072
	ds_read_b128 v[230:233], v179 offset:4096
	ds_read_b128 v[234:237], v179 offset:5120
	ds_read_b128 v[238:241], v179 offset:6144
	ds_read_b128 v[242:245], v179 offset:7168
	global_load_lds_dwordx4 v170, s[0:1]
	s_add_i32 m0, s29, 0xe000
	s_nop 0
	global_load_lds_dwordx4 v172, s[0:1]
	s_waitcnt vmcnt(8)
	s_waitcnt lgkmcnt(0)
	s_barrier
	s_setprio 1
	v_mfma_f32_16x16x32_bf16 v[140:143], v[68:71], v[214:217], v[140:143]
	v_mfma_f32_16x16x32_bf16 v[140:143], v[72:75], v[218:221], v[140:143]
	v_mfma_f32_16x16x32_bf16 v[124:127], v[68:71], v[222:225], v[124:127]
	v_mfma_f32_16x16x32_bf16 v[124:127], v[72:75], v[226:229], v[124:127]
	v_mfma_f32_16x16x32_bf16 v[108:111], v[68:71], v[230:233], v[108:111]
	v_mfma_f32_16x16x32_bf16 v[108:111], v[72:75], v[234:237], v[108:111]
	v_mfma_f32_16x16x32_bf16 v[92:95], v[68:71], v[238:241], v[92:95]
	v_mfma_f32_16x16x32_bf16 v[92:95], v[72:75], v[242:245], v[92:95]
	v_mfma_f32_16x16x32_bf16 v[136:139], v[76:79], v[214:217], v[136:139]
	v_mfma_f32_16x16x32_bf16 v[136:139], v[80:83], v[218:221], v[136:139]
	v_mfma_f32_16x16x32_bf16 v[120:123], v[76:79], v[222:225], v[120:123]
	v_mfma_f32_16x16x32_bf16 v[120:123], v[80:83], v[226:229], v[120:123]
	v_mfma_f32_16x16x32_bf16 v[104:107], v[76:79], v[230:233], v[104:107]
	v_mfma_f32_16x16x32_bf16 v[104:107], v[80:83], v[234:237], v[104:107]
	v_mfma_f32_16x16x32_bf16 v[88:91], v[76:79], v[238:241], v[88:91]
	v_mfma_f32_16x16x32_bf16 v[88:91], v[80:83], v[242:245], v[88:91]
	v_mfma_f32_16x16x32_bf16 v[132:135], v[174:177], v[214:217], v[132:135]
	v_mfma_f32_16x16x32_bf16 v[132:135], v[182:185], v[218:221], v[132:135]
	v_mfma_f32_16x16x32_bf16 v[116:119], v[174:177], v[222:225], v[116:119]
	v_mfma_f32_16x16x32_bf16 v[116:119], v[182:185], v[226:229], v[116:119]
	v_mfma_f32_16x16x32_bf16 v[100:103], v[174:177], v[230:233], v[100:103]
	v_mfma_f32_16x16x32_bf16 v[100:103], v[182:185], v[234:237], v[100:103]
	v_mfma_f32_16x16x32_bf16 v[84:87], v[174:177], v[238:241], v[84:87]
	v_mfma_f32_16x16x32_bf16 v[84:87], v[182:185], v[242:245], v[84:87]
	v_mfma_f32_16x16x32_bf16 v[128:131], v[186:189], v[214:217], v[128:131]
	v_mfma_f32_16x16x32_bf16 v[128:131], v[210:213], v[218:221], v[128:131]
	v_mfma_f32_16x16x32_bf16 v[112:115], v[186:189], v[222:225], v[112:115]
	v_mfma_f32_16x16x32_bf16 v[112:115], v[210:213], v[226:229], v[112:115]
	v_mfma_f32_16x16x32_bf16 v[96:99], v[186:189], v[230:233], v[96:99]
	v_mfma_f32_16x16x32_bf16 v[96:99], v[210:213], v[234:237], v[96:99]
	v_mfma_f32_16x16x32_bf16 v[64:67], v[186:189], v[238:241], v[64:67]
	v_mfma_f32_16x16x32_bf16 v[64:67], v[210:213], v[242:245], v[64:67]
	s_setprio 0
	s_barrier
	s_mov_b32 m0, s30
	s_add_u32 s58, s2, 0x40000
	s_addc_u32 s59, s3, 0
	ds_read_b128 v[214:217], v179 offset:16384
	ds_read_b128 v[218:221], v179 offset:17408
	ds_read_b128 v[222:225], v179 offset:18432
	ds_read_b128 v[226:229], v179 offset:19456
	ds_read_b128 v[230:233], v179 offset:20480
	ds_read_b128 v[234:237], v179 offset:21504
	ds_read_b128 v[238:241], v179 offset:22528
	ds_read_b128 v[242:245], v179 offset:23552
	global_load_lds_dwordx4 v166, s[2:3]
	s_mov_b32 m0, s31
	s_nop 0
	global_load_lds_dwordx4 v162, s[2:3]
	s_mov_b32 m0, s33
	s_nop 0
	global_load_lds_dwordx4 v166, s[58:59]
	s_mov_b32 m0, s34
	s_nop 0
	global_load_lds_dwordx4 v162, s[58:59]
	s_mov_b32 m0, s29
	s_nop 0
	global_load_lds_dwordx4 v168, s[4:5]
	s_mov_b32 m0, s35
	s_nop 0
	global_load_lds_dwordx4 v164, s[4:5]
	s_waitcnt vmcnt(8)
	s_waitcnt lgkmcnt(0)
	s_barrier
	s_setprio 1
	v_mfma_f32_16x16x32_bf16 v[60:63], v[68:71], v[214:217], v[60:63]
	v_mfma_f32_16x16x32_bf16 v[60:63], v[72:75], v[218:221], v[60:63]
	v_mfma_f32_16x16x32_bf16 v[44:47], v[68:71], v[222:225], v[44:47]
	v_mfma_f32_16x16x32_bf16 v[44:47], v[72:75], v[226:229], v[44:47]
	v_mfma_f32_16x16x32_bf16 v[28:31], v[68:71], v[230:233], v[28:31]
	v_mfma_f32_16x16x32_bf16 v[28:31], v[72:75], v[234:237], v[28:31]
	v_mfma_f32_16x16x32_bf16 v[12:15], v[68:71], v[238:241], v[12:15]
	v_mfma_f32_16x16x32_bf16 v[12:15], v[72:75], v[242:245], v[12:15]
	v_mfma_f32_16x16x32_bf16 v[56:59], v[76:79], v[214:217], v[56:59]
	v_mfma_f32_16x16x32_bf16 v[56:59], v[80:83], v[218:221], v[56:59]
	v_mfma_f32_16x16x32_bf16 v[40:43], v[76:79], v[222:225], v[40:43]
	v_mfma_f32_16x16x32_bf16 v[40:43], v[80:83], v[226:229], v[40:43]
	v_mfma_f32_16x16x32_bf16 v[24:27], v[76:79], v[230:233], v[24:27]
	v_mfma_f32_16x16x32_bf16 v[24:27], v[80:83], v[234:237], v[24:27]
	v_mfma_f32_16x16x32_bf16 v[8:11], v[76:79], v[238:241], v[8:11]
	v_mfma_f32_16x16x32_bf16 v[8:11], v[80:83], v[242:245], v[8:11]
	v_mfma_f32_16x16x32_bf16 v[52:55], v[174:177], v[214:217], v[52:55]
	v_mfma_f32_16x16x32_bf16 v[52:55], v[182:185], v[218:221], v[52:55]
	v_mfma_f32_16x16x32_bf16 v[36:39], v[174:177], v[222:225], v[36:39]
	v_mfma_f32_16x16x32_bf16 v[36:39], v[182:185], v[226:229], v[36:39]
	v_mfma_f32_16x16x32_bf16 v[20:23], v[174:177], v[230:233], v[20:23]
	v_mfma_f32_16x16x32_bf16 v[20:23], v[182:185], v[234:237], v[20:23]
	v_mfma_f32_16x16x32_bf16 v[4:7], v[174:177], v[238:241], v[4:7]
	v_mfma_f32_16x16x32_bf16 v[4:7], v[182:185], v[242:245], v[4:7]
	v_mfma_f32_16x16x32_bf16 v[48:51], v[186:189], v[214:217], v[48:51]
	v_mfma_f32_16x16x32_bf16 v[48:51], v[210:213], v[218:221], v[48:51]
	v_mfma_f32_16x16x32_bf16 v[32:35], v[186:189], v[222:225], v[32:35]
	v_mfma_f32_16x16x32_bf16 v[32:35], v[210:213], v[226:229], v[32:35]
	v_mfma_f32_16x16x32_bf16 v[16:19], v[186:189], v[230:233], v[16:19]
	v_mfma_f32_16x16x32_bf16 v[16:19], v[210:213], v[234:237], v[16:19]
	v_mfma_f32_16x16x32_bf16 v[0:3], v[186:189], v[238:241], v[0:3]
	v_mfma_f32_16x16x32_bf16 v[0:3], v[210:213], v[242:245], v[0:3]
	s_setprio 0
	s_barrier
; #define PG8_STAGE(bufoff, gbase, voff) do { _Pragma("unroll") for (int _i = 0; _i < 2; ++_i) \
;         __builtin_amdgcn_global_load_lds((const unsigned*)((const char*)(gbase) + (voff)[_i]), (PG8_LAS unsigned*)(lds + (bufoff) + ldsw + _i * 8192), 16, 0, 0); } while (0)
; #define PG8_LDA(dst, b, h) do { _Pragma("unroll") for (int m = 0; m < 4; ++m) _Pragma("unroll") for (int k = 0; k < 2; ++k) dst[m][k] = *(const PG8_LAS bf16x8*)(lds + PG8_SA(b, h) + aoff + m * 2048 + k * 1024); } while (0)
; #define PG8_LDB(dst, b, h) do { _Pragma("unroll") for (int n = 0; n < 2; ++n) _Pragma("unroll") for (int k = 0; k < 2; ++k) dst[n][k] = *(const PG8_LAS bf16x8*)(lds + PG8_SB(b, h) + boff + n * 2048 + k * 1024); } while (0)
; #define PG8_MMA(ai, bj, At, Bt) do { __builtin_amdgcn_s_setprio(1); _Pragma("unroll") for (int m = 0; m < 4; ++m) _Pragma("unroll") for (int n = 0; n < 2; ++n) _Pragma("unroll") for (int k = 0; k < 2; ++k) \
;         acc[ai][bj][m][n] = __builtin_amdgcn_mfma_f32_16x16x32_bf16(Bt[n][k], At[m][k], acc[ai][bj][m][n], 0, 0, 0); __builtin_amdgcn_s_setprio(0); } while (0)
; #define PG8_WAIT_V(n) asm volatile("s_waitcnt vmcnt(" #n ")" ::: "memory")
; #define PG8_WAIT_L(n) asm volatile("s_waitcnt lgkmcnt(" #n ")" ::: "memory")
; #define PG8_BAR __builtin_amdgcn_s_barrier()
; #define PG8_SCHED __builtin_amdgcn_sched_barrier(0)
; template <class Epi, class Sched, bool ALIGN_EPI = false, bool SP2 = false>
; __device__ __forceinline__ void gemm_phase(PG8_LAS unsigned char* lds, const Gemm g, const Sched& S, const Epi& E) {
;     ...
;             PG8_LDB(B0, 1, 0); PG8_LDB(B1, 1, 1); PG8_SCHED; PG8_LDA(At, 1, 0); PG8_STAGE(PG8_SA(0, 1), a2 + hstep, voffA);
;             PG8_WAIT_V(8); PG8_WAIT_L(0); PG8_BAR; PG8_MMA(0, 0, At, B0); PG8_MMA(0, 1, At, B1); PG8_BAR; PG8_SCHED;
;             PG8_LDA(At, 1, 1); PG8_STAGE(PG8_SB(1, 0), b3, voffB); PG8_STAGE(PG8_SB(1, 1), b3 + hstep, voffB); PG8_STAGE(PG8_SA(1, 0), a3, voffA);
;             PG8_WAIT_V(8); PG8_WAIT_L(0); PG8_BAR; PG8_MMA(1, 0, At, B0); PG8_MMA(1, 1, At, B1); PG8_BAR; PG8_SCHED;
;     ...
;         if constexpr (ALIGN_EPI) { if (wr == 0) PG8_BAR; }
	ds_read_b128 v[68:71], v254 offset:32768
	ds_read_b128 v[72:75], v254 offset:33792
	ds_read_b128 v[76:79], v254 offset:34816
	ds_read_b128 v[80:83], v254 offset:35840
	ds_read_b128 v[174:177], v254 offset:49152
	ds_read_b128 v[182:185], v254 offset:50176
	ds_read_b128 v[186:189], v254 offset:51200
	ds_read_b128 v[210:213], v254 offset:52224
	s_add_u32 s4, s4, 0x40000
	s_addc_u32 s5, s5, 0
	s_mov_b32 m0, s40
	ds_read_b128 v[214:217], v179 offset:32768
	ds_read_b128 v[218:221], v179 offset:33792
	ds_read_b128 v[222:225], v179 offset:34816
	ds_read_b128 v[226:229], v179 offset:35840
	ds_read_b128 v[230:233], v179 offset:36864
	ds_read_b128 v[234:237], v179 offset:37888
	ds_read_b128 v[238:241], v179 offset:38912
	ds_read_b128 v[242:245], v179 offset:39936
	global_load_lds_dwordx4 v168, s[4:5]
	s_mov_b32 m0, s41
	s_nop 0
	global_load_lds_dwordx4 v164, s[4:5]
	s_waitcnt vmcnt(8)
	s_waitcnt lgkmcnt(0)
	s_barrier
	s_setprio 1
	v_mfma_f32_16x16x32_bf16 v[140:143], v[68:71], v[214:217], v[140:143]
	v_mfma_f32_16x16x32_bf16 v[140:143], v[72:75], v[218:221], v[140:143]
	v_mfma_f32_16x16x32_bf16 v[124:127], v[68:71], v[222:225], v[124:127]
	v_mfma_f32_16x16x32_bf16 v[124:127], v[72:75], v[226:229], v[124:127]
	v_mfma_f32_16x16x32_bf16 v[108:111], v[68:71], v[230:233], v[108:111]
	v_mfma_f32_16x16x32_bf16 v[108:111], v[72:75], v[234:237], v[108:111]
	v_mfma_f32_16x16x32_bf16 v[92:95], v[68:71], v[238:241], v[92:95]
	v_mfma_f32_16x16x32_bf16 v[92:95], v[72:75], v[242:245], v[92:95]
	v_mfma_f32_16x16x32_bf16 v[136:139], v[76:79], v[214:217], v[136:139]
	v_mfma_f32_16x16x32_bf16 v[136:139], v[80:83], v[218:221], v[136:139]
	v_mfma_f32_16x16x32_bf16 v[120:123], v[76:79], v[222:225], v[120:123]
	v_mfma_f32_16x16x32_bf16 v[120:123], v[80:83], v[226:229], v[120:123]
	v_mfma_f32_16x16x32_bf16 v[104:107], v[76:79], v[230:233], v[104:107]
	v_mfma_f32_16x16x32_bf16 v[104:107], v[80:83], v[234:237], v[104:107]
	v_mfma_f32_16x16x32_bf16 v[88:91], v[76:79], v[238:241], v[88:91]
	v_mfma_f32_16x16x32_bf16 v[88:91], v[80:83], v[242:245], v[88:91]
	v_mfma_f32_16x16x32_bf16 v[132:135], v[174:177], v[214:217], v[132:135]
	v_mfma_f32_16x16x32_bf16 v[132:135], v[182:185], v[218:221], v[132:135]
	v_mfma_f32_16x16x32_bf16 v[116:119], v[174:177], v[222:225], v[116:119]
	v_mfma_f32_16x16x32_bf16 v[116:119], v[182:185], v[226:229], v[116:119]
	v_mfma_f32_16x16x32_bf16 v[100:103], v[174:177], v[230:233], v[100:103]
	v_mfma_f32_16x16x32_bf16 v[100:103], v[182:185], v[234:237], v[100:103]
	v_mfma_f32_16x16x32_bf16 v[84:87], v[174:177], v[238:241], v[84:87]
	v_mfma_f32_16x16x32_bf16 v[84:87], v[182:185], v[242:245], v[84:87]
	v_mfma_f32_16x16x32_bf16 v[128:131], v[186:189], v[214:217], v[128:131]
	v_mfma_f32_16x16x32_bf16 v[128:131], v[210:213], v[218:221], v[128:131]
	v_mfma_f32_16x16x32_bf16 v[112:115], v[186:189], v[222:225], v[112:115]
	v_mfma_f32_16x16x32_bf16 v[112:115], v[210:213], v[226:229], v[112:115]
	v_mfma_f32_16x16x32_bf16 v[96:99], v[186:189], v[230:233], v[96:99]
	v_mfma_f32_16x16x32_bf16 v[96:99], v[210:213], v[234:237], v[96:99]
	v_mfma_f32_16x16x32_bf16 v[64:67], v[186:189], v[238:241], v[64:67]
	v_mfma_f32_16x16x32_bf16 v[64:67], v[210:213], v[242:245], v[64:67]
	s_setprio 0
	s_barrier
	s_mov_b32 m0, s45
	s_add_u32 s2, s2, 0x40080
	s_addc_u32 s3, s3, 0
	ds_read_b128 v[214:217], v179 offset:49152
	ds_read_b128 v[218:221], v179 offset:50176
	ds_read_b128 v[222:225], v179 offset:51200
	ds_read_b128 v[226:229], v179 offset:52224
	ds_read_b128 v[230:233], v179 offset:53248
	ds_read_b128 v[234:237], v179 offset:54272
	ds_read_b128 v[238:241], v179 offset:55296
	ds_read_b128 v[242:245], v179 offset:56320
	s_add_u32 s98, s2, 0xfffc0000
	s_addc_u32 s99, s3, -1
	global_load_lds_dwordx4 v166, s[98:99]
	s_mov_b32 m0, s46
	s_nop 0
	global_load_lds_dwordx4 v162, s[98:99]
	s_mov_b32 m0, s49
	s_nop 0
	global_load_lds_dwordx4 v166, s[2:3]
	s_mov_b32 m0, s50
	s_nop 0
	global_load_lds_dwordx4 v162, s[2:3]
	s_mov_b32 m0, s47
	s_nop 0
	s_add_u32 s100, s4, 0xfffc0080
	s_addc_u32 s101, s5, -1
	global_load_lds_dwordx4 v168, s[100:101]
	s_mov_b32 m0, s48
	s_nop 0
	global_load_lds_dwordx4 v164, s[100:101]
	s_waitcnt vmcnt(8)
	s_waitcnt lgkmcnt(0)
	s_barrier
	s_setprio 1
	v_mfma_f32_16x16x32_bf16 v[60:63], v[68:71], v[214:217], v[60:63]
	v_mfma_f32_16x16x32_bf16 v[60:63], v[72:75], v[218:221], v[60:63]
	v_mfma_f32_16x16x32_bf16 v[44:47], v[68:71], v[222:225], v[44:47]
	v_mfma_f32_16x16x32_bf16 v[44:47], v[72:75], v[226:229], v[44:47]
	v_mfma_f32_16x16x32_bf16 v[28:31], v[68:71], v[230:233], v[28:31]
	v_mfma_f32_16x16x32_bf16 v[28:31], v[72:75], v[234:237], v[28:31]
	v_mfma_f32_16x16x32_bf16 v[12:15], v[68:71], v[238:241], v[12:15]
	v_mfma_f32_16x16x32_bf16 v[12:15], v[72:75], v[242:245], v[12:15]
	v_mfma_f32_16x16x32_bf16 v[56:59], v[76:79], v[214:217], v[56:59]
	v_mfma_f32_16x16x32_bf16 v[56:59], v[80:83], v[218:221], v[56:59]
	v_mfma_f32_16x16x32_bf16 v[40:43], v[76:79], v[222:225], v[40:43]
	v_mfma_f32_16x16x32_bf16 v[40:43], v[80:83], v[226:229], v[40:43]
	v_mfma_f32_16x16x32_bf16 v[24:27], v[76:79], v[230:233], v[24:27]
	v_mfma_f32_16x16x32_bf16 v[24:27], v[80:83], v[234:237], v[24:27]
	v_mfma_f32_16x16x32_bf16 v[8:11], v[76:79], v[238:241], v[8:11]
	v_mfma_f32_16x16x32_bf16 v[8:11], v[80:83], v[242:245], v[8:11]
	v_mfma_f32_16x16x32_bf16 v[52:55], v[174:177], v[214:217], v[52:55]
	v_mfma_f32_16x16x32_bf16 v[52:55], v[182:185], v[218:221], v[52:55]
	v_mfma_f32_16x16x32_bf16 v[36:39], v[174:177], v[222:225], v[36:39]
	v_mfma_f32_16x16x32_bf16 v[36:39], v[182:185], v[226:229], v[36:39]
	v_mfma_f32_16x16x32_bf16 v[20:23], v[174:177], v[230:233], v[20:23]
	v_mfma_f32_16x16x32_bf16 v[20:23], v[182:185], v[234:237], v[20:23]
	v_mfma_f32_16x16x32_bf16 v[4:7], v[174:177], v[238:241], v[4:7]
	v_mfma_f32_16x16x32_bf16 v[4:7], v[182:185], v[242:245], v[4:7]
	v_mfma_f32_16x16x32_bf16 v[48:51], v[186:189], v[214:217], v[48:51]
	v_mfma_f32_16x16x32_bf16 v[48:51], v[210:213], v[218:221], v[48:51]
	v_mfma_f32_16x16x32_bf16 v[32:35], v[186:189], v[222:225], v[32:35]
	v_mfma_f32_16x16x32_bf16 v[32:35], v[210:213], v[226:229], v[32:35]
	v_mfma_f32_16x16x32_bf16 v[16:19], v[186:189], v[230:233], v[16:19]
	v_mfma_f32_16x16x32_bf16 v[16:19], v[210:213], v[234:237], v[16:19]
	v_mfma_f32_16x16x32_bf16 v[0:3], v[186:189], v[238:241], v[0:3]
	v_mfma_f32_16x16x32_bf16 v[0:3], v[210:213], v[242:245], v[0:3]
	s_setprio 0
	s_barrier
	s_add_i32 s56, s56, 2
	s_add_u32 s0, s0, 0x100
	s_addc_u32 s1, s1, 0
	s_add_u32 s54, s54, 0x100
	s_addc_u32 s55, s55, 0
	s_cmp_gt_u32 s56, 13
	s_cbranch_scc0 .LBB0_327
	s_and_b64 vcc, exec, s[22:23]
	s_cbranch_vccz .LBB0_330
	s_barrier

; #define PG8_STAGE(bufoff, gbase, voff) do { _Pragma("unroll") for (int _i = 0; _i < 2; ++_i) \
;         __builtin_amdgcn_global_load_lds((const unsigned*)((const char*)(gbase) + (voff)[_i]), (PG8_LAS unsigned*)(lds + (bufoff) + ldsw + _i * 8192), 16, 0, 0); } while (0)
; #define PG8_LDA(dst, b, h) do { _Pragma("unroll") for (int m = 0; m < 4; ++m) _Pragma("unroll") for (int k = 0; k < 2; ++k) dst[m][k] = *(const PG8_LAS bf16x8*)(lds + PG8_SA(b, h) + aoff + m * 2048 + k * 1024); } while (0)
; #define PG8_LDB(dst, b, h) do { _Pragma("unroll") for (int n = 0; n < 2; ++n) _Pragma("unroll") for (int k = 0; k < 2; ++k) dst[n][k] = *(const PG8_LAS bf16x8*)(lds + PG8_SB(b, h) + boff + n * 2048 + k * 1024); } while (0)
; #define PG8_MMA(ai, bj, At, Bt) do { __builtin_amdgcn_s_setprio(1); _Pragma("unroll") for (int m = 0; m < 4; ++m) _Pragma("unroll") for (int n = 0; n < 2; ++n) _Pragma("unroll") for (int k = 0; k < 2; ++k) \
;         acc[ai][bj][m][n] = __builtin_amdgcn_mfma_f32_16x16x32_bf16(Bt[n][k], At[m][k], acc[ai][bj][m][n], 0, 0, 0); __builtin_amdgcn_s_setprio(0); } while (0)
; #define PG8_WAIT_V(n) asm volatile("s_waitcnt vmcnt(" #n ")" ::: "memory")
; #define PG8_WAIT_L(n) asm volatile("s_waitcnt lgkmcnt(" #n ")" ::: "memory")
; #define PG8_BAR __builtin_amdgcn_s_barrier()
; #define PG8_SCHED __builtin_amdgcn_sched_barrier(0)
; template <class Epi, class Sched, bool ALIGN_EPI = false, bool SP2 = false>
; __device__ __forceinline__ void gemm_phase(PG8_LAS unsigned char* lds, const Gemm g, const Sched& S, const Epi& E) {
;     ...
;             PG8_LDB(B0, 0, 0); PG8_LDB(B1, 0, 1); PG8_SCHED; PG8_LDA(At, 0, 0); PG8_STAGE(PG8_SA(1, 1), a1 + hstep, voffA);
;             PG8_WAIT_V(8); PG8_WAIT_L(0); PG8_BAR; PG8_MMA(0, 0, At, B0); PG8_MMA(0, 1, At, B1); PG8_BAR; PG8_SCHED;
;             PG8_LDA(At, 0, 1); PG8_STAGE(PG8_SB(0, 0), b2, voffB); PG8_STAGE(PG8_SB(0, 1), b2 + hstep, voffB); PG8_STAGE(PG8_SA(0, 0), a2, voffA);
;             PG8_WAIT_V(8); PG8_WAIT_L(0); PG8_BAR; PG8_MMA(1, 0, At, B0); PG8_MMA(1, 1, At, B1); PG8_BAR; PG8_SCHED;
.Lup_peel:
	ds_read_b128 v[140:143], v254
	ds_read_b128 v[168:171], v254 offset:1024
	ds_read_b128 v[172:175], v254 offset:2048
	ds_read_b128 v[176:179], v254 offset:3072
	ds_read_b128 v[180:183], v254 offset:16384
	ds_read_b128 v[184:187], v254 offset:17408
	ds_read_b128 v[188:191], v254 offset:18432
	ds_read_b128 v[210:213], v254 offset:19456
	s_add_u32 s16, s14, 0xfffc0080
	s_addc_u32 s17, s15, -1
	s_cmp_eq_u32 s53, 12
	s_cselect_b32 s19, s7, s17
	s_cselect_b32 s18, s49, s16
	s_cselect_b32 s17, s5, s52
	s_cselect_b32 s16, s50, s51
	s_mov_b32 m0, s43
	ds_read_b128 v[214:217], v165
	ds_read_b128 v[218:221], v165 offset:1024
	ds_read_b128 v[222:225], v165 offset:2048
	ds_read_b128 v[226:229], v165 offset:3072
	ds_read_b128 v[230:233], v165 offset:4096
	ds_read_b128 v[234:237], v165 offset:5120
	ds_read_b128 v[238:241], v165 offset:6144
	ds_read_b128 v[242:245], v165 offset:7168
	global_load_lds_dwordx4 v136, s[14:15]
	s_mov_b32 m0, s44
	s_nop 0
	global_load_lds_dwordx4 v138, s[14:15]
	s_waitcnt vmcnt(8)
	s_waitcnt lgkmcnt(0)
	s_barrier
	s_setprio 1
	v_mfma_f32_16x16x32_bf16 v[124:127], v[140:143], v[214:217], 0
	v_mfma_f32_16x16x32_bf16 v[124:127], v[168:171], v[218:221], v[124:127]
	v_mfma_f32_16x16x32_bf16 v[108:111], v[140:143], v[222:225], 0
	v_mfma_f32_16x16x32_bf16 v[108:111], v[168:171], v[226:229], v[108:111]
	v_mfma_f32_16x16x32_bf16 v[92:95], v[140:143], v[230:233], 0
	v_mfma_f32_16x16x32_bf16 v[92:95], v[168:171], v[234:237], v[92:95]
	v_mfma_f32_16x16x32_bf16 v[76:79], v[140:143], v[238:241], 0
	v_mfma_f32_16x16x32_bf16 v[76:79], v[168:171], v[242:245], v[76:79]
	v_mfma_f32_16x16x32_bf16 v[116:119], v[172:175], v[214:217], 0
	v_mfma_f32_16x16x32_bf16 v[116:119], v[176:179], v[218:221], v[116:119]
	v_mfma_f32_16x16x32_bf16 v[100:103], v[172:175], v[222:225], 0
	v_mfma_f32_16x16x32_bf16 v[100:103], v[176:179], v[226:229], v[100:103]
	v_mfma_f32_16x16x32_bf16 v[84:87], v[172:175], v[230:233], 0
	v_mfma_f32_16x16x32_bf16 v[84:87], v[176:179], v[234:237], v[84:87]
	v_mfma_f32_16x16x32_bf16 v[68:71], v[172:175], v[238:241], 0
	v_mfma_f32_16x16x32_bf16 v[68:71], v[176:179], v[242:245], v[68:71]
	v_mfma_f32_16x16x32_bf16 v[120:123], v[180:183], v[214:217], 0
	v_mfma_f32_16x16x32_bf16 v[120:123], v[184:187], v[218:221], v[120:123]
	v_mfma_f32_16x16x32_bf16 v[104:107], v[180:183], v[222:225], 0
	v_mfma_f32_16x16x32_bf16 v[104:107], v[184:187], v[226:229], v[104:107]
	v_mfma_f32_16x16x32_bf16 v[88:91], v[180:183], v[230:233], 0
	v_mfma_f32_16x16x32_bf16 v[88:91], v[184:187], v[234:237], v[88:91]
	v_mfma_f32_16x16x32_bf16 v[72:75], v[180:183], v[238:241], 0
	v_mfma_f32_16x16x32_bf16 v[72:75], v[184:187], v[242:245], v[72:75]
	v_mfma_f32_16x16x32_bf16 v[112:115], v[188:191], v[214:217], 0
	v_mfma_f32_16x16x32_bf16 v[112:115], v[210:213], v[218:221], v[112:115]
	v_mfma_f32_16x16x32_bf16 v[96:99], v[188:191], v[222:225], 0
	v_mfma_f32_16x16x32_bf16 v[96:99], v[210:213], v[226:229], v[96:99]
	v_mfma_f32_16x16x32_bf16 v[80:83], v[188:191], v[230:233], 0
	v_mfma_f32_16x16x32_bf16 v[80:83], v[210:213], v[234:237], v[80:83]
	v_mfma_f32_16x16x32_bf16 v[64:67], v[188:191], v[238:241], 0
	v_mfma_f32_16x16x32_bf16 v[64:67], v[210:213], v[242:245], v[64:67]
	s_setprio 0
	s_barrier
	s_mov_b32 m0, s27
	s_add_u32 s54, s16, 0x40000
	s_addc_u32 s55, s17, 0
	ds_read_b128 v[214:217], v165 offset:16384
	ds_read_b128 v[218:221], v165 offset:17408
	ds_read_b128 v[222:225], v165 offset:18432
	ds_read_b128 v[226:229], v165 offset:19456
	ds_read_b128 v[230:233], v165 offset:20480
	ds_read_b128 v[234:237], v165 offset:21504
	ds_read_b128 v[238:241], v165 offset:22528
	ds_read_b128 v[242:245], v165 offset:23552
	global_load_lds_dwordx4 v132, s[16:17]
	s_mov_b32 m0, s28
	s_nop 0
	global_load_lds_dwordx4 v128, s[16:17]
	s_mov_b32 m0, s29
	s_nop 0
	global_load_lds_dwordx4 v132, s[54:55]
	s_mov_b32 m0, s30
	s_nop 0
	global_load_lds_dwordx4 v128, s[54:55]
	s_mov_b32 m0, s22
	s_nop 0
	global_load_lds_dwordx4 v134, s[18:19]
	s_mov_b32 m0, s31
	s_nop 0
	global_load_lds_dwordx4 v130, s[18:19]
	s_waitcnt vmcnt(8)
	s_waitcnt lgkmcnt(0)
	s_barrier
	s_setprio 1
	v_mfma_f32_16x16x32_bf16 v[60:63], v[140:143], v[214:217], 0
	v_mfma_f32_16x16x32_bf16 v[60:63], v[168:171], v[218:221], v[60:63]
	v_mfma_f32_16x16x32_bf16 v[44:47], v[140:143], v[222:225], 0
	v_mfma_f32_16x16x32_bf16 v[44:47], v[168:171], v[226:229], v[44:47]
	v_mfma_f32_16x16x32_bf16 v[28:31], v[140:143], v[230:233], 0
	v_mfma_f32_16x16x32_bf16 v[28:31], v[168:171], v[234:237], v[28:31]
	v_mfma_f32_16x16x32_bf16 v[12:15], v[140:143], v[238:241], 0
	v_mfma_f32_16x16x32_bf16 v[12:15], v[168:171], v[242:245], v[12:15]
	v_mfma_f32_16x16x32_bf16 v[52:55], v[172:175], v[214:217], 0
	v_mfma_f32_16x16x32_bf16 v[52:55], v[176:179], v[218:221], v[52:55]
	v_mfma_f32_16x16x32_bf16 v[36:39], v[172:175], v[222:225], 0
	v_mfma_f32_16x16x32_bf16 v[36:39], v[176:179], v[226:229], v[36:39]
	v_mfma_f32_16x16x32_bf16 v[20:23], v[172:175], v[230:233], 0
	v_mfma_f32_16x16x32_bf16 v[20:23], v[176:179], v[234:237], v[20:23]
	v_mfma_f32_16x16x32_bf16 v[4:7], v[172:175], v[238:241], 0
	v_mfma_f32_16x16x32_bf16 v[4:7], v[176:179], v[242:245], v[4:7]
	v_mfma_f32_16x16x32_bf16 v[56:59], v[180:183], v[214:217], 0
	v_mfma_f32_16x16x32_bf16 v[56:59], v[184:187], v[218:221], v[56:59]
	v_mfma_f32_16x16x32_bf16 v[40:43], v[180:183], v[222:225], 0
	v_mfma_f32_16x16x32_bf16 v[40:43], v[184:187], v[226:229], v[40:43]
	v_mfma_f32_16x16x32_bf16 v[24:27], v[180:183], v[230:233], 0
	v_mfma_f32_16x16x32_bf16 v[24:27], v[184:187], v[234:237], v[24:27]
	v_mfma_f32_16x16x32_bf16 v[8:11], v[180:183], v[238:241], 0
	v_mfma_f32_16x16x32_bf16 v[8:11], v[184:187], v[242:245], v[8:11]
	v_mfma_f32_16x16x32_bf16 v[48:51], v[188:191], v[214:217], 0
	v_mfma_f32_16x16x32_bf16 v[48:51], v[210:213], v[218:221], v[48:51]
	v_mfma_f32_16x16x32_bf16 v[32:35], v[188:191], v[222:225], 0
	v_mfma_f32_16x16x32_bf16 v[32:35], v[210:213], v[226:229], v[32:35]
	v_mfma_f32_16x16x32_bf16 v[16:19], v[188:191], v[230:233], 0
	v_mfma_f32_16x16x32_bf16 v[16:19], v[210:213], v[234:237], v[16:19]
	v_mfma_f32_16x16x32_bf16 v[0:3], v[188:191], v[238:241], 0
	v_mfma_f32_16x16x32_bf16 v[0:3], v[210:213], v[242:245], v[0:3]
	s_setprio 0
	s_barrier
; #define PG8_STAGE(bufoff, gbase, voff) do { _Pragma("unroll") for (int _i = 0; _i < 2; ++_i) \
;         __builtin_amdgcn_global_load_lds((const unsigned*)((const char*)(gbase) + (voff)[_i]), (PG8_LAS unsigned*)(lds + (bufoff) + ldsw + _i * 8192), 16, 0, 0); } while (0)
; #define PG8_LDA(dst, b, h) do { _Pragma("unroll") for (int m = 0; m < 4; ++m) _Pragma("unroll") for (int k = 0; k < 2; ++k) dst[m][k] = *(const PG8_LAS bf16x8*)(lds + PG8_SA(b, h) + aoff + m * 2048 + k * 1024); } while (0)
; #define PG8_LDB(dst, b, h) do { _Pragma("unroll") for (int n = 0; n < 2; ++n) _Pragma("unroll") for (int k = 0; k < 2; ++k) dst[n][k] = *(const PG8_LAS bf16x8*)(lds + PG8_SB(b, h) + boff + n * 2048 + k * 1024); } while (0)
; #define PG8_MMA(ai, bj, At, Bt) do { __builtin_amdgcn_s_setprio(1); _Pragma("unroll") for (int m = 0; m < 4; ++m) _Pragma("unroll") for (int n = 0; n < 2; ++n) _Pragma("unroll") for (int k = 0; k < 2; ++k) \
;         acc[ai][bj][m][n] = __builtin_amdgcn_mfma_f32_16x16x32_bf16(Bt[n][k], At[m][k], acc[ai][bj][m][n], 0, 0, 0); __builtin_amdgcn_s_setprio(0); } while (0)
; #define PG8_WAIT_V(n) asm volatile("s_waitcnt vmcnt(" #n ")" ::: "memory")
; #define PG8_WAIT_L(n) asm volatile("s_waitcnt lgkmcnt(" #n ")" ::: "memory")
; #define PG8_BAR __builtin_amdgcn_s_barrier()
; #define PG8_SCHED __builtin_amdgcn_sched_barrier(0)
; template <class Epi, class Sched, bool ALIGN_EPI = false, bool SP2 = false>
; __device__ __forceinline__ void gemm_phase(PG8_LAS unsigned char* lds, const Gemm g, const Sched& S, const Epi& E) {
;     ...
;             PG8_LDB(B0, 1, 0); PG8_LDB(B1, 1, 1); PG8_SCHED; PG8_LDA(At, 1, 0); PG8_STAGE(PG8_SA(0, 1), a2 + hstep, voffA);
;             PG8_WAIT_V(8); PG8_WAIT_L(0); PG8_BAR; PG8_MMA(0, 0, At, B0); PG8_MMA(0, 1, At, B1); PG8_BAR; PG8_SCHED;
;             PG8_LDA(At, 1, 1); PG8_STAGE(PG8_SB(1, 0), b3, voffB); PG8_STAGE(PG8_SB(1, 1), b3 + hstep, voffB); PG8_STAGE(PG8_SA(1, 0), a3, voffA);
;             PG8_WAIT_V(8); PG8_WAIT_L(0); PG8_BAR; PG8_MMA(1, 0, At, B0); PG8_MMA(1, 1, At, B1); PG8_BAR; PG8_SCHED;
	ds_read_b128 v[140:143], v254 offset:32768
	ds_read_b128 v[168:171], v254 offset:33792
	ds_read_b128 v[172:175], v254 offset:34816
	ds_read_b128 v[176:179], v254 offset:35840
	ds_read_b128 v[180:183], v254 offset:49152
	ds_read_b128 v[184:187], v254 offset:50176
	ds_read_b128 v[188:191], v254 offset:51200
	ds_read_b128 v[210:213], v254 offset:52224
	s_add_u32 s18, s18, 0x40000
	s_addc_u32 s19, s19, 0
	s_mov_b32 m0, s33
	ds_read_b128 v[214:217], v165 offset:32768
	ds_read_b128 v[218:221], v165 offset:33792
	ds_read_b128 v[222:225], v165 offset:34816
	ds_read_b128 v[226:229], v165 offset:35840
	ds_read_b128 v[230:233], v165 offset:36864
	ds_read_b128 v[234:237], v165 offset:37888
	ds_read_b128 v[238:241], v165 offset:38912
	ds_read_b128 v[242:245], v165 offset:39936
	global_load_lds_dwordx4 v134, s[18:19]
	s_mov_b32 m0, s34
	s_nop 0
	global_load_lds_dwordx4 v130, s[18:19]
	s_waitcnt vmcnt(8)
	s_waitcnt lgkmcnt(0)
	s_barrier
	s_setprio 1
	v_mfma_f32_16x16x32_bf16 v[124:127], v[140:143], v[214:217], v[124:127]
	v_mfma_f32_16x16x32_bf16 v[124:127], v[168:171], v[218:221], v[124:127]
	v_mfma_f32_16x16x32_bf16 v[108:111], v[140:143], v[222:225], v[108:111]
	v_mfma_f32_16x16x32_bf16 v[108:111], v[168:171], v[226:229], v[108:111]
	v_mfma_f32_16x16x32_bf16 v[92:95], v[140:143], v[230:233], v[92:95]
	v_mfma_f32_16x16x32_bf16 v[92:95], v[168:171], v[234:237], v[92:95]
	v_mfma_f32_16x16x32_bf16 v[76:79], v[140:143], v[238:241], v[76:79]
	v_mfma_f32_16x16x32_bf16 v[76:79], v[168:171], v[242:245], v[76:79]
	v_mfma_f32_16x16x32_bf16 v[116:119], v[172:175], v[214:217], v[116:119]
	v_mfma_f32_16x16x32_bf16 v[116:119], v[176:179], v[218:221], v[116:119]
	v_mfma_f32_16x16x32_bf16 v[100:103], v[172:175], v[222:225], v[100:103]
	v_mfma_f32_16x16x32_bf16 v[100:103], v[176:179], v[226:229], v[100:103]
	v_mfma_f32_16x16x32_bf16 v[84:87], v[172:175], v[230:233], v[84:87]
	v_mfma_f32_16x16x32_bf16 v[84:87], v[176:179], v[234:237], v[84:87]
	v_mfma_f32_16x16x32_bf16 v[68:71], v[172:175], v[238:241], v[68:71]
	v_mfma_f32_16x16x32_bf16 v[68:71], v[176:179], v[242:245], v[68:71]
	v_mfma_f32_16x16x32_bf16 v[120:123], v[180:183], v[214:217], v[120:123]
	v_mfma_f32_16x16x32_bf16 v[120:123], v[184:187], v[218:221], v[120:123]
	v_mfma_f32_16x16x32_bf16 v[104:107], v[180:183], v[222:225], v[104:107]
	v_mfma_f32_16x16x32_bf16 v[104:107], v[184:187], v[226:229], v[104:107]
	v_mfma_f32_16x16x32_bf16 v[88:91], v[180:183], v[230:233], v[88:91]
	v_mfma_f32_16x16x32_bf16 v[88:91], v[184:187], v[234:237], v[88:91]
	v_mfma_f32_16x16x32_bf16 v[72:75], v[180:183], v[238:241], v[72:75]
	v_mfma_f32_16x16x32_bf16 v[72:75], v[184:187], v[242:245], v[72:75]
	v_mfma_f32_16x16x32_bf16 v[112:115], v[188:191], v[214:217], v[112:115]
	v_mfma_f32_16x16x32_bf16 v[112:115], v[210:213], v[218:221], v[112:115]
	v_mfma_f32_16x16x32_bf16 v[96:99], v[188:191], v[222:225], v[96:99]
	v_mfma_f32_16x16x32_bf16 v[96:99], v[210:213], v[226:229], v[96:99]
	v_mfma_f32_16x16x32_bf16 v[80:83], v[188:191], v[230:233], v[80:83]
	v_mfma_f32_16x16x32_bf16 v[80:83], v[210:213], v[234:237], v[80:83]
	v_mfma_f32_16x16x32_bf16 v[64:67], v[188:191], v[238:241], v[64:67]
	v_mfma_f32_16x16x32_bf16 v[64:67], v[210:213], v[242:245], v[64:67]
	s_setprio 0
	s_barrier
	s_mov_b32 m0, s37
	s_add_u32 s16, s16, 0x40080
	s_addc_u32 s17, s17, 0
	ds_read_b128 v[214:217], v165 offset:49152
	ds_read_b128 v[218:221], v165 offset:50176
	ds_read_b128 v[222:225], v165 offset:51200
	ds_read_b128 v[226:229], v165 offset:52224
	ds_read_b128 v[230:233], v165 offset:53248
	ds_read_b128 v[234:237], v165 offset:54272
	ds_read_b128 v[238:241], v165 offset:55296
	ds_read_b128 v[242:245], v165 offset:56320
	s_add_u32 s98, s16, 0xfffc0000
	s_addc_u32 s99, s17, -1
	global_load_lds_dwordx4 v132, s[98:99]
	s_mov_b32 m0, s38
	s_nop 0
	global_load_lds_dwordx4 v128, s[98:99]
	s_mov_b32 m0, s41
	s_nop 0
	global_load_lds_dwordx4 v132, s[16:17]
	s_mov_b32 m0, s42
	s_nop 0
	global_load_lds_dwordx4 v128, s[16:17]
	s_mov_b32 m0, s39
	s_nop 0
	s_add_u32 s100, s18, 0xfffc0080
	s_addc_u32 s101, s19, -1
	global_load_lds_dwordx4 v134, s[100:101]
	s_mov_b32 m0, s40
	s_nop 0
	global_load_lds_dwordx4 v130, s[100:101]
	s_waitcnt vmcnt(8)
	s_waitcnt lgkmcnt(0)
	s_barrier
	s_setprio 1
	v_mfma_f32_16x16x32_bf16 v[60:63], v[140:143], v[214:217], v[60:63]
	v_mfma_f32_16x16x32_bf16 v[60:63], v[168:171], v[218:221], v[60:63]
	v_mfma_f32_16x16x32_bf16 v[44:47], v[140:143], v[222:225], v[44:47]
	v_mfma_f32_16x16x32_bf16 v[44:47], v[168:171], v[226:229], v[44:47]
	v_mfma_f32_16x16x32_bf16 v[28:31], v[140:143], v[230:233], v[28:31]
	v_mfma_f32_16x16x32_bf16 v[28:31], v[168:171], v[234:237], v[28:31]
	v_mfma_f32_16x16x32_bf16 v[12:15], v[140:143], v[238:241], v[12:15]
	v_mfma_f32_16x16x32_bf16 v[12:15], v[168:171], v[242:245], v[12:15]
	v_mfma_f32_16x16x32_bf16 v[52:55], v[172:175], v[214:217], v[52:55]
	v_mfma_f32_16x16x32_bf16 v[52:55], v[176:179], v[218:221], v[52:55]
	v_mfma_f32_16x16x32_bf16 v[36:39], v[172:175], v[222:225], v[36:39]
	v_mfma_f32_16x16x32_bf16 v[36:39], v[176:179], v[226:229], v[36:39]
	v_mfma_f32_16x16x32_bf16 v[20:23], v[172:175], v[230:233], v[20:23]
	v_mfma_f32_16x16x32_bf16 v[20:23], v[176:179], v[234:237], v[20:23]
	v_mfma_f32_16x16x32_bf16 v[4:7], v[172:175], v[238:241], v[4:7]
	v_mfma_f32_16x16x32_bf16 v[4:7], v[176:179], v[242:245], v[4:7]
	v_mfma_f32_16x16x32_bf16 v[56:59], v[180:183], v[214:217], v[56:59]
	v_mfma_f32_16x16x32_bf16 v[56:59], v[184:187], v[218:221], v[56:59]
	v_mfma_f32_16x16x32_bf16 v[40:43], v[180:183], v[222:225], v[40:43]
	v_mfma_f32_16x16x32_bf16 v[40:43], v[184:187], v[226:229], v[40:43]
	v_mfma_f32_16x16x32_bf16 v[24:27], v[180:183], v[230:233], v[24:27]
	v_mfma_f32_16x16x32_bf16 v[24:27], v[184:187], v[234:237], v[24:27]
	v_mfma_f32_16x16x32_bf16 v[8:11], v[180:183], v[238:241], v[8:11]
	v_mfma_f32_16x16x32_bf16 v[8:11], v[184:187], v[242:245], v[8:11]
	v_mfma_f32_16x16x32_bf16 v[48:51], v[188:191], v[214:217], v[48:51]
	v_mfma_f32_16x16x32_bf16 v[48:51], v[210:213], v[218:221], v[48:51]
	v_mfma_f32_16x16x32_bf16 v[32:35], v[188:191], v[222:225], v[32:35]
	v_mfma_f32_16x16x32_bf16 v[32:35], v[210:213], v[226:229], v[32:35]
	v_mfma_f32_16x16x32_bf16 v[16:19], v[188:191], v[230:233], v[16:19]
	v_mfma_f32_16x16x32_bf16 v[16:19], v[210:213], v[234:237], v[16:19]
	v_mfma_f32_16x16x32_bf16 v[0:3], v[188:191], v[238:241], v[0:3]
	v_mfma_f32_16x16x32_bf16 v[0:3], v[210:213], v[242:245], v[0:3]
	s_setprio 0
	s_barrier
	s_add_i32 s53, s53, 2
	s_add_u32 s14, s14, 0x100
	s_addc_u32 s15, s15, 0
	s_add_u32 s51, s51, 0x100
	s_addc_u32 s52, s52, 0
	s_cmp_gt_u32 s53, 13
; #define PG8_STAGE(bufoff, gbase, voff) do { _Pragma("unroll") for (int _i = 0; _i < 2; ++_i) \
;         __builtin_amdgcn_global_load_lds((const unsigned*)((const char*)(gbase) + (voff)[_i]), (PG8_LAS unsigned*)(lds + (bufoff) + ldsw + _i * 8192), 16, 0, 0); } while (0)
; #define PG8_LDA(dst, b, h) do { _Pragma("unroll") for (int m = 0; m < 4; ++m) _Pragma("unroll") for (int k = 0; k < 2; ++k) dst[m][k] = *(const PG8_LAS bf16x8*)(lds + PG8_SA(b, h) + aoff + m * 2048 + k * 1024); } while (0)
; #define PG8_LDB(dst, b, h) do { _Pragma("unroll") for (int n = 0; n < 2; ++n) _Pragma("unroll") for (int k = 0; k < 2; ++k) dst[n][k] = *(const PG8_LAS bf16x8*)(lds + PG8_SB(b, h) + boff + n * 2048 + k * 1024); } while (0)
; #define PG8_MMA(ai, bj, At, Bt) do { __builtin_amdgcn_s_setprio(1); _Pragma("unroll") for (int m = 0; m < 4; ++m) _Pragma("unroll") for (int n = 0; n < 2; ++n) _Pragma("unroll") for (int k = 0; k < 2; ++k) \
;         acc[ai][bj][m][n] = __builtin_amdgcn_mfma_f32_16x16x32_bf16(Bt[n][k], At[m][k], acc[ai][bj][m][n], 0, 0, 0); __builtin_amdgcn_s_setprio(0); } while (0)
; #define PG8_WAIT_V(n) asm volatile("s_waitcnt vmcnt(" #n ")" ::: "memory")
; #define PG8_WAIT_L(n) asm volatile("s_waitcnt lgkmcnt(" #n ")" ::: "memory")
; #define PG8_BAR __builtin_amdgcn_s_barrier()
; #define PG8_SCHED __builtin_amdgcn_sched_barrier(0)
; template <class Epi, class Sched, bool ALIGN_EPI = false, bool SP2 = false>
; __device__ __forceinline__ void gemm_phase(PG8_LAS unsigned char* lds, const Gemm g, const Sched& S, const Epi& E) {
;     ...
;             PG8_LDB(B0, 0, 0); PG8_LDB(B1, 0, 1); PG8_SCHED; PG8_LDA(At, 0, 0); PG8_STAGE(PG8_SA(1, 1), a1 + hstep, voffA);
;             PG8_WAIT_V(8); PG8_WAIT_L(0); PG8_BAR; PG8_MMA(0, 0, At, B0); PG8_MMA(0, 1, At, B1); PG8_BAR; PG8_SCHED;
;             PG8_LDA(At, 0, 1); PG8_STAGE(PG8_SB(0, 0), b2, voffB); PG8_STAGE(PG8_SB(0, 1), b2 + hstep, voffB); PG8_STAGE(PG8_SA(0, 0), a2, voffA);
;             PG8_WAIT_V(8); PG8_WAIT_L(0); PG8_BAR; PG8_MMA(1, 0, At, B0); PG8_MMA(1, 1, At, B1); PG8_BAR; PG8_SCHED;
.LBB0_446:
	ds_read_b128 v[140:143], v254
	ds_read_b128 v[168:171], v254 offset:1024
	ds_read_b128 v[172:175], v254 offset:2048
	ds_read_b128 v[176:179], v254 offset:3072
	ds_read_b128 v[180:183], v254 offset:16384
	ds_read_b128 v[184:187], v254 offset:17408
	ds_read_b128 v[188:191], v254 offset:18432
	ds_read_b128 v[210:213], v254 offset:19456
	s_add_u32 s16, s14, 0xfffc0080
	s_addc_u32 s17, s15, -1
	s_cmp_eq_u32 s53, 12
	s_cselect_b32 s19, s7, s17
	s_cselect_b32 s18, s49, s16
	s_cselect_b32 s17, s5, s52
	s_cselect_b32 s16, s50, s51
	s_mov_b32 m0, s43
	ds_read_b128 v[214:217], v165
	ds_read_b128 v[218:221], v165 offset:1024
	ds_read_b128 v[222:225], v165 offset:2048
	ds_read_b128 v[226:229], v165 offset:3072
	ds_read_b128 v[230:233], v165 offset:4096
	ds_read_b128 v[234:237], v165 offset:5120
	ds_read_b128 v[238:241], v165 offset:6144
	ds_read_b128 v[242:245], v165 offset:7168
	global_load_lds_dwordx4 v136, s[14:15]
	s_mov_b32 m0, s44
	s_nop 0
	global_load_lds_dwordx4 v138, s[14:15]
	s_waitcnt vmcnt(8)
	s_waitcnt lgkmcnt(0)
	s_barrier
	s_setprio 1
	v_mfma_f32_16x16x32_bf16 v[124:127], v[140:143], v[214:217], v[124:127]
	v_mfma_f32_16x16x32_bf16 v[124:127], v[168:171], v[218:221], v[124:127]
	v_mfma_f32_16x16x32_bf16 v[108:111], v[140:143], v[222:225], v[108:111]
	v_mfma_f32_16x16x32_bf16 v[108:111], v[168:171], v[226:229], v[108:111]
	v_mfma_f32_16x16x32_bf16 v[92:95], v[140:143], v[230:233], v[92:95]
	v_mfma_f32_16x16x32_bf16 v[92:95], v[168:171], v[234:237], v[92:95]
	v_mfma_f32_16x16x32_bf16 v[76:79], v[140:143], v[238:241], v[76:79]
	v_mfma_f32_16x16x32_bf16 v[76:79], v[168:171], v[242:245], v[76:79]
	v_mfma_f32_16x16x32_bf16 v[116:119], v[172:175], v[214:217], v[116:119]
	v_mfma_f32_16x16x32_bf16 v[116:119], v[176:179], v[218:221], v[116:119]
	v_mfma_f32_16x16x32_bf16 v[100:103], v[172:175], v[222:225], v[100:103]
	v_mfma_f32_16x16x32_bf16 v[100:103], v[176:179], v[226:229], v[100:103]
	v_mfma_f32_16x16x32_bf16 v[84:87], v[172:175], v[230:233], v[84:87]
	v_mfma_f32_16x16x32_bf16 v[84:87], v[176:179], v[234:237], v[84:87]
	v_mfma_f32_16x16x32_bf16 v[68:71], v[172:175], v[238:241], v[68:71]
	v_mfma_f32_16x16x32_bf16 v[68:71], v[176:179], v[242:245], v[68:71]
	v_mfma_f32_16x16x32_bf16 v[120:123], v[180:183], v[214:217], v[120:123]
	v_mfma_f32_16x16x32_bf16 v[120:123], v[184:187], v[218:221], v[120:123]
	v_mfma_f32_16x16x32_bf16 v[104:107], v[180:183], v[222:225], v[104:107]
	v_mfma_f32_16x16x32_bf16 v[104:107], v[184:187], v[226:229], v[104:107]
	v_mfma_f32_16x16x32_bf16 v[88:91], v[180:183], v[230:233], v[88:91]
	v_mfma_f32_16x16x32_bf16 v[88:91], v[184:187], v[234:237], v[88:91]
	v_mfma_f32_16x16x32_bf16 v[72:75], v[180:183], v[238:241], v[72:75]
	v_mfma_f32_16x16x32_bf16 v[72:75], v[184:187], v[242:245], v[72:75]
	v_mfma_f32_16x16x32_bf16 v[112:115], v[188:191], v[214:217], v[112:115]
	v_mfma_f32_16x16x32_bf16 v[112:115], v[210:213], v[218:221], v[112:115]
	v_mfma_f32_16x16x32_bf16 v[96:99], v[188:191], v[222:225], v[96:99]
	v_mfma_f32_16x16x32_bf16 v[96:99], v[210:213], v[226:229], v[96:99]
	v_mfma_f32_16x16x32_bf16 v[80:83], v[188:191], v[230:233], v[80:83]
	v_mfma_f32_16x16x32_bf16 v[80:83], v[210:213], v[234:237], v[80:83]
	v_mfma_f32_16x16x32_bf16 v[64:67], v[188:191], v[238:241], v[64:67]
	v_mfma_f32_16x16x32_bf16 v[64:67], v[210:213], v[242:245], v[64:67]
	s_setprio 0
	s_barrier
	s_mov_b32 m0, s27
	s_add_u32 s54, s16, 0x40000
	s_addc_u32 s55, s17, 0
	ds_read_b128 v[214:217], v165 offset:16384
	ds_read_b128 v[218:221], v165 offset:17408
	ds_read_b128 v[222:225], v165 offset:18432
	ds_read_b128 v[226:229], v165 offset:19456
	ds_read_b128 v[230:233], v165 offset:20480
	ds_read_b128 v[234:237], v165 offset:21504
	ds_read_b128 v[238:241], v165 offset:22528
	ds_read_b128 v[242:245], v165 offset:23552
	global_load_lds_dwordx4 v132, s[16:17]
	s_mov_b32 m0, s28
	s_nop 0
	global_load_lds_dwordx4 v128, s[16:17]
	s_mov_b32 m0, s29
	s_nop 0
	global_load_lds_dwordx4 v132, s[54:55]
	s_mov_b32 m0, s30
	s_nop 0
	global_load_lds_dwordx4 v128, s[54:55]
	s_mov_b32 m0, s22
	s_nop 0
	global_load_lds_dwordx4 v134, s[18:19]
	s_mov_b32 m0, s31
	s_nop 0
	global_load_lds_dwordx4 v130, s[18:19]
	s_waitcnt vmcnt(8)
	s_waitcnt lgkmcnt(0)
	s_barrier
	s_setprio 1
	v_mfma_f32_16x16x32_bf16 v[60:63], v[140:143], v[214:217], v[60:63]
	v_mfma_f32_16x16x32_bf16 v[60:63], v[168:171], v[218:221], v[60:63]
	v_mfma_f32_16x16x32_bf16 v[44:47], v[140:143], v[222:225], v[44:47]
	v_mfma_f32_16x16x32_bf16 v[44:47], v[168:171], v[226:229], v[44:47]
	v_mfma_f32_16x16x32_bf16 v[28:31], v[140:143], v[230:233], v[28:31]
	v_mfma_f32_16x16x32_bf16 v[28:31], v[168:171], v[234:237], v[28:31]
	v_mfma_f32_16x16x32_bf16 v[12:15], v[140:143], v[238:241], v[12:15]
	v_mfma_f32_16x16x32_bf16 v[12:15], v[168:171], v[242:245], v[12:15]
	v_mfma_f32_16x16x32_bf16 v[52:55], v[172:175], v[214:217], v[52:55]
	v_mfma_f32_16x16x32_bf16 v[52:55], v[176:179], v[218:221], v[52:55]
	v_mfma_f32_16x16x32_bf16 v[36:39], v[172:175], v[222:225], v[36:39]
	v_mfma_f32_16x16x32_bf16 v[36:39], v[176:179], v[226:229], v[36:39]
	v_mfma_f32_16x16x32_bf16 v[20:23], v[172:175], v[230:233], v[20:23]
	v_mfma_f32_16x16x32_bf16 v[20:23], v[176:179], v[234:237], v[20:23]
	v_mfma_f32_16x16x32_bf16 v[4:7], v[172:175], v[238:241], v[4:7]
	v_mfma_f32_16x16x32_bf16 v[4:7], v[176:179], v[242:245], v[4:7]
	v_mfma_f32_16x16x32_bf16 v[56:59], v[180:183], v[214:217], v[56:59]
	v_mfma_f32_16x16x32_bf16 v[56:59], v[184:187], v[218:221], v[56:59]
	v_mfma_f32_16x16x32_bf16 v[40:43], v[180:183], v[222:225], v[40:43]
	v_mfma_f32_16x16x32_bf16 v[40:43], v[184:187], v[226:229], v[40:43]
	v_mfma_f32_16x16x32_bf16 v[24:27], v[180:183], v[230:233], v[24:27]
	v_mfma_f32_16x16x32_bf16 v[24:27], v[184:187], v[234:237], v[24:27]
	v_mfma_f32_16x16x32_bf16 v[8:11], v[180:183], v[238:241], v[8:11]
	v_mfma_f32_16x16x32_bf16 v[8:11], v[184:187], v[242:245], v[8:11]
	v_mfma_f32_16x16x32_bf16 v[48:51], v[188:191], v[214:217], v[48:51]
	v_mfma_f32_16x16x32_bf16 v[48:51], v[210:213], v[218:221], v[48:51]
	v_mfma_f32_16x16x32_bf16 v[32:35], v[188:191], v[222:225], v[32:35]
	v_mfma_f32_16x16x32_bf16 v[32:35], v[210:213], v[226:229], v[32:35]
	v_mfma_f32_16x16x32_bf16 v[16:19], v[188:191], v[230:233], v[16:19]
	v_mfma_f32_16x16x32_bf16 v[16:19], v[210:213], v[234:237], v[16:19]
	v_mfma_f32_16x16x32_bf16 v[0:3], v[188:191], v[238:241], v[0:3]
	v_mfma_f32_16x16x32_bf16 v[0:3], v[210:213], v[242:245], v[0:3]
	s_setprio 0
	s_barrier
; #define PG8_STAGE(bufoff, gbase, voff) do { _Pragma("unroll") for (int _i = 0; _i < 2; ++_i) \
;         __builtin_amdgcn_global_load_lds((const unsigned*)((const char*)(gbase) + (voff)[_i]), (PG8_LAS unsigned*)(lds + (bufoff) + ldsw + _i * 8192), 16, 0, 0); } while (0)
; #define PG8_LDA(dst, b, h) do { _Pragma("unroll") for (int m = 0; m < 4; ++m) _Pragma("unroll") for (int k = 0; k < 2; ++k) dst[m][k] = *(const PG8_LAS bf16x8*)(lds + PG8_SA(b, h) + aoff + m * 2048 + k * 1024); } while (0)
; #define PG8_LDB(dst, b, h) do { _Pragma("unroll") for (int n = 0; n < 2; ++n) _Pragma("unroll") for (int k = 0; k < 2; ++k) dst[n][k] = *(const PG8_LAS bf16x8*)(lds + PG8_SB(b, h) + boff + n * 2048 + k * 1024); } while (0)
; #define PG8_MMA(ai, bj, At, Bt) do { __builtin_amdgcn_s_setprio(1); _Pragma("unroll") for (int m = 0; m < 4; ++m) _Pragma("unroll") for (int n = 0; n < 2; ++n) _Pragma("unroll") for (int k = 0; k < 2; ++k) \
;         acc[ai][bj][m][n] = __builtin_amdgcn_mfma_f32_16x16x32_bf16(Bt[n][k], At[m][k], acc[ai][bj][m][n], 0, 0, 0); __builtin_amdgcn_s_setprio(0); } while (0)
; #define PG8_WAIT_V(n) asm volatile("s_waitcnt vmcnt(" #n ")" ::: "memory")
; #define PG8_WAIT_L(n) asm volatile("s_waitcnt lgkmcnt(" #n ")" ::: "memory")
; #define PG8_BAR __builtin_amdgcn_s_barrier()
; #define PG8_SCHED __builtin_amdgcn_sched_barrier(0)
; template <class Epi, class Sched, bool ALIGN_EPI = false, bool SP2 = false>
; __device__ __forceinline__ void gemm_phase(PG8_LAS unsigned char* lds, const Gemm g, const Sched& S, const Epi& E) {
;     ...
;             PG8_LDB(B0, 1, 0); PG8_LDB(B1, 1, 1); PG8_SCHED; PG8_LDA(At, 1, 0); PG8_STAGE(PG8_SA(0, 1), a2 + hstep, voffA);
;             PG8_WAIT_V(8); PG8_WAIT_L(0); PG8_BAR; PG8_MMA(0, 0, At, B0); PG8_MMA(0, 1, At, B1); PG8_BAR; PG8_SCHED;
;             PG8_LDA(At, 1, 1); PG8_STAGE(PG8_SB(1, 0), b3, voffB); PG8_STAGE(PG8_SB(1, 1), b3 + hstep, voffB); PG8_STAGE(PG8_SA(1, 0), a3, voffA);
;             PG8_WAIT_V(8); PG8_WAIT_L(0); PG8_BAR; PG8_MMA(1, 0, At, B0); PG8_MMA(1, 1, At, B1); PG8_BAR; PG8_SCHED;
;     ...
;         if constexpr (ALIGN_EPI) { if (wr == 0) PG8_BAR; }
	ds_read_b128 v[140:143], v254 offset:32768
	ds_read_b128 v[168:171], v254 offset:33792
	ds_read_b128 v[172:175], v254 offset:34816
	ds_read_b128 v[176:179], v254 offset:35840
	ds_read_b128 v[180:183], v254 offset:49152
	ds_read_b128 v[184:187], v254 offset:50176
	ds_read_b128 v[188:191], v254 offset:51200
	ds_read_b128 v[210:213], v254 offset:52224
	s_add_u32 s18, s18, 0x40000
	s_addc_u32 s19, s19, 0
	s_mov_b32 m0, s33
	ds_read_b128 v[214:217], v165 offset:32768
	ds_read_b128 v[218:221], v165 offset:33792
	ds_read_b128 v[222:225], v165 offset:34816
	ds_read_b128 v[226:229], v165 offset:35840
	ds_read_b128 v[230:233], v165 offset:36864
	ds_read_b128 v[234:237], v165 offset:37888
	ds_read_b128 v[238:241], v165 offset:38912
	ds_read_b128 v[242:245], v165 offset:39936
	global_load_lds_dwordx4 v134, s[18:19]
	s_mov_b32 m0, s34
	s_nop 0
	global_load_lds_dwordx4 v130, s[18:19]
	s_waitcnt vmcnt(8)
	s_waitcnt lgkmcnt(0)
	s_barrier
	s_setprio 1
	v_mfma_f32_16x16x32_bf16 v[124:127], v[140:143], v[214:217], v[124:127]
	v_mfma_f32_16x16x32_bf16 v[124:127], v[168:171], v[218:221], v[124:127]
	v_mfma_f32_16x16x32_bf16 v[108:111], v[140:143], v[222:225], v[108:111]
	v_mfma_f32_16x16x32_bf16 v[108:111], v[168:171], v[226:229], v[108:111]
	v_mfma_f32_16x16x32_bf16 v[92:95], v[140:143], v[230:233], v[92:95]
	v_mfma_f32_16x16x32_bf16 v[92:95], v[168:171], v[234:237], v[92:95]
	v_mfma_f32_16x16x32_bf16 v[76:79], v[140:143], v[238:241], v[76:79]
	v_mfma_f32_16x16x32_bf16 v[76:79], v[168:171], v[242:245], v[76:79]
	v_mfma_f32_16x16x32_bf16 v[116:119], v[172:175], v[214:217], v[116:119]
	v_mfma_f32_16x16x32_bf16 v[116:119], v[176:179], v[218:221], v[116:119]
	v_mfma_f32_16x16x32_bf16 v[100:103], v[172:175], v[222:225], v[100:103]
	v_mfma_f32_16x16x32_bf16 v[100:103], v[176:179], v[226:229], v[100:103]
	v_mfma_f32_16x16x32_bf16 v[84:87], v[172:175], v[230:233], v[84:87]
	v_mfma_f32_16x16x32_bf16 v[84:87], v[176:179], v[234:237], v[84:87]
	v_mfma_f32_16x16x32_bf16 v[68:71], v[172:175], v[238:241], v[68:71]
	v_mfma_f32_16x16x32_bf16 v[68:71], v[176:179], v[242:245], v[68:71]
	v_mfma_f32_16x16x32_bf16 v[120:123], v[180:183], v[214:217], v[120:123]
	v_mfma_f32_16x16x32_bf16 v[120:123], v[184:187], v[218:221], v[120:123]
	v_mfma_f32_16x16x32_bf16 v[104:107], v[180:183], v[222:225], v[104:107]
	v_mfma_f32_16x16x32_bf16 v[104:107], v[184:187], v[226:229], v[104:107]
	v_mfma_f32_16x16x32_bf16 v[88:91], v[180:183], v[230:233], v[88:91]
	v_mfma_f32_16x16x32_bf16 v[88:91], v[184:187], v[234:237], v[88:91]
	v_mfma_f32_16x16x32_bf16 v[72:75], v[180:183], v[238:241], v[72:75]
	v_mfma_f32_16x16x32_bf16 v[72:75], v[184:187], v[242:245], v[72:75]
	v_mfma_f32_16x16x32_bf16 v[112:115], v[188:191], v[214:217], v[112:115]
	v_mfma_f32_16x16x32_bf16 v[112:115], v[210:213], v[218:221], v[112:115]
	v_mfma_f32_16x16x32_bf16 v[96:99], v[188:191], v[222:225], v[96:99]
	v_mfma_f32_16x16x32_bf16 v[96:99], v[210:213], v[226:229], v[96:99]
	v_mfma_f32_16x16x32_bf16 v[80:83], v[188:191], v[230:233], v[80:83]
	v_mfma_f32_16x16x32_bf16 v[80:83], v[210:213], v[234:237], v[80:83]
	v_mfma_f32_16x16x32_bf16 v[64:67], v[188:191], v[238:241], v[64:67]
	v_mfma_f32_16x16x32_bf16 v[64:67], v[210:213], v[242:245], v[64:67]
	s_setprio 0
	s_barrier
	s_mov_b32 m0, s37
	s_add_u32 s16, s16, 0x40080
	s_addc_u32 s17, s17, 0
	ds_read_b128 v[214:217], v165 offset:49152
	ds_read_b128 v[218:221], v165 offset:50176
	ds_read_b128 v[222:225], v165 offset:51200
	ds_read_b128 v[226:229], v165 offset:52224
	ds_read_b128 v[230:233], v165 offset:53248
	ds_read_b128 v[234:237], v165 offset:54272
	ds_read_b128 v[238:241], v165 offset:55296
	ds_read_b128 v[242:245], v165 offset:56320
	s_add_u32 s98, s16, 0xfffc0000
	s_addc_u32 s99, s17, -1
	global_load_lds_dwordx4 v132, s[98:99]
	s_mov_b32 m0, s38
	s_nop 0
	global_load_lds_dwordx4 v128, s[98:99]
	s_mov_b32 m0, s41
	s_nop 0
	global_load_lds_dwordx4 v132, s[16:17]
	s_mov_b32 m0, s42
	s_nop 0
	global_load_lds_dwordx4 v128, s[16:17]
	s_mov_b32 m0, s39
	s_nop 0
	s_add_u32 s100, s18, 0xfffc0080
	s_addc_u32 s101, s19, -1
	global_load_lds_dwordx4 v134, s[100:101]
	s_mov_b32 m0, s40
	s_nop 0
	global_load_lds_dwordx4 v130, s[100:101]
	s_waitcnt vmcnt(8)
	s_waitcnt lgkmcnt(0)
	s_barrier
	s_setprio 1
	v_mfma_f32_16x16x32_bf16 v[60:63], v[140:143], v[214:217], v[60:63]
	v_mfma_f32_16x16x32_bf16 v[60:63], v[168:171], v[218:221], v[60:63]
	v_mfma_f32_16x16x32_bf16 v[44:47], v[140:143], v[222:225], v[44:47]
	v_mfma_f32_16x16x32_bf16 v[44:47], v[168:171], v[226:229], v[44:47]
	v_mfma_f32_16x16x32_bf16 v[28:31], v[140:143], v[230:233], v[28:31]
	v_mfma_f32_16x16x32_bf16 v[28:31], v[168:171], v[234:237], v[28:31]
	v_mfma_f32_16x16x32_bf16 v[12:15], v[140:143], v[238:241], v[12:15]
	v_mfma_f32_16x16x32_bf16 v[12:15], v[168:171], v[242:245], v[12:15]
	v_mfma_f32_16x16x32_bf16 v[52:55], v[172:175], v[214:217], v[52:55]
	v_mfma_f32_16x16x32_bf16 v[52:55], v[176:179], v[218:221], v[52:55]
	v_mfma_f32_16x16x32_bf16 v[36:39], v[172:175], v[222:225], v[36:39]
	v_mfma_f32_16x16x32_bf16 v[36:39], v[176:179], v[226:229], v[36:39]
	v_mfma_f32_16x16x32_bf16 v[20:23], v[172:175], v[230:233], v[20:23]
	v_mfma_f32_16x16x32_bf16 v[20:23], v[176:179], v[234:237], v[20:23]
	v_mfma_f32_16x16x32_bf16 v[4:7], v[172:175], v[238:241], v[4:7]
	v_mfma_f32_16x16x32_bf16 v[4:7], v[176:179], v[242:245], v[4:7]
	v_mfma_f32_16x16x32_bf16 v[56:59], v[180:183], v[214:217], v[56:59]
	v_mfma_f32_16x16x32_bf16 v[56:59], v[184:187], v[218:221], v[56:59]
	v_mfma_f32_16x16x32_bf16 v[40:43], v[180:183], v[222:225], v[40:43]
	v_mfma_f32_16x16x32_bf16 v[40:43], v[184:187], v[226:229], v[40:43]
	v_mfma_f32_16x16x32_bf16 v[24:27], v[180:183], v[230:233], v[24:27]
	v_mfma_f32_16x16x32_bf16 v[24:27], v[184:187], v[234:237], v[24:27]
	v_mfma_f32_16x16x32_bf16 v[8:11], v[180:183], v[238:241], v[8:11]
	v_mfma_f32_16x16x32_bf16 v[8:11], v[184:187], v[242:245], v[8:11]
	v_mfma_f32_16x16x32_bf16 v[48:51], v[188:191], v[214:217], v[48:51]
	v_mfma_f32_16x16x32_bf16 v[48:51], v[210:213], v[218:221], v[48:51]
	v_mfma_f32_16x16x32_bf16 v[32:35], v[188:191], v[222:225], v[32:35]
	v_mfma_f32_16x16x32_bf16 v[32:35], v[210:213], v[226:229], v[32:35]
	v_mfma_f32_16x16x32_bf16 v[16:19], v[188:191], v[230:233], v[16:19]
	v_mfma_f32_16x16x32_bf16 v[16:19], v[210:213], v[234:237], v[16:19]
	v_mfma_f32_16x16x32_bf16 v[0:3], v[188:191], v[238:241], v[0:3]
	v_mfma_f32_16x16x32_bf16 v[0:3], v[210:213], v[242:245], v[0:3]
	s_setprio 0
	s_barrier
	s_add_i32 s53, s53, 2
	s_add_u32 s14, s14, 0x100
	s_addc_u32 s15, s15, 0
	s_add_u32 s51, s51, 0x100
	s_addc_u32 s52, s52, 0
	s_cmp_gt_u32 s53, 13
	s_cbranch_scc0 .LBB0_446
	s_and_b64 vcc, exec, s[2:3]
	s_cbranch_vccz .LBB0_449
	s_barrier

; #define PG8_STAGE(bufoff, gbase, voff) do { _Pragma("unroll") for (int _i = 0; _i < 2; ++_i) \
;         __builtin_amdgcn_global_load_lds((const unsigned*)((const char*)(gbase) + (voff)[_i]), (PG8_LAS unsigned*)(lds + (bufoff) + ldsw + _i * 8192), 16, 0, 0); } while (0)
; #define PG8_LDA(dst, b, h) do { _Pragma("unroll") for (int m = 0; m < 4; ++m) _Pragma("unroll") for (int k = 0; k < 2; ++k) dst[m][k] = *(const PG8_LAS bf16x8*)(lds + PG8_SA(b, h) + aoff + m * 2048 + k * 1024); } while (0)
; #define PG8_LDB(dst, b, h) do { _Pragma("unroll") for (int n = 0; n < 2; ++n) _Pragma("unroll") for (int k = 0; k < 2; ++k) dst[n][k] = *(const PG8_LAS bf16x8*)(lds + PG8_SB(b, h) + boff + n * 2048 + k * 1024); } while (0)
; #define PG8_MMA(ai, bj, At, Bt) do { __builtin_amdgcn_s_setprio(1); _Pragma("unroll") for (int m = 0; m < 4; ++m) _Pragma("unroll") for (int n = 0; n < 2; ++n) _Pragma("unroll") for (int k = 0; k < 2; ++k) \
;         acc[ai][bj][m][n] = __builtin_amdgcn_mfma_f32_16x16x32_bf16(Bt[n][k], At[m][k], acc[ai][bj][m][n], 0, 0, 0); __builtin_amdgcn_s_setprio(0); } while (0)
; #define PG8_WAIT_V(n) asm volatile("s_waitcnt vmcnt(" #n ")" ::: "memory")
; #define PG8_WAIT_L(n) asm volatile("s_waitcnt lgkmcnt(" #n ")" ::: "memory")
; template <class Epi, class Sched, bool ALIGN_EPI = false, bool SP2 = false>
; __device__ __forceinline__ void gemm_phase(PG8_LAS unsigned char* lds, const Gemm g, const Sched& S, const Epi& E) {
;     ...
;             const bool last = (t == nt - 2);
;             const char* a1 = cA + (size_t)(t + 1) * kstep;
;             const char* a2 = last ? nA : cA + (size_t)(t + 2) * kstep; const char* b2 = last ? nB : cB + (size_t)(t + 2) * kstep;
;             const char* a3 = a2 + kstep; const char* b3 = b2 + kstep;
;             if (last && has_next) S.a_ready(nxt);
;             if constexpr (SP2) {
;             PG8_LDB(B0, 0, 0); PG8_LDB(B1, 0, 1); PG8_SCHED; PG8_LDA(At, 0, 0); PG8_STAGE(PG8_SA(1, 1), a1 + hstep, voffA);
;             PG8_WAIT_V(8); PG8_WAIT_L(0); PG8_BAR; PG8_MMA(0, 0, At, B0); PG8_MMA(0, 1, At, B1); PG8_BAR; PG8_SCHED;
;             PG8_LDA(At, 0, 1); PG8_STAGE(PG8_SB(0, 0), b2, voffB); PG8_STAGE(PG8_SB(0, 1), b2 + hstep, voffB); PG8_STAGE(PG8_SA(0, 0), a2, voffA);
;             PG8_WAIT_V(8); PG8_WAIT_L(0); PG8_BAR; PG8_MMA(1, 0, At, B0); PG8_MMA(1, 1, At, B1); PG8_BAR; PG8_SCHED;
.Ldn_peel:
	ds_read_b128 v[128:131], v254
	ds_read_b128 v[132:135], v254 offset:1024
	ds_read_b128 v[136:139], v254 offset:2048
	ds_read_b128 v[140:143], v254 offset:3072
	ds_read_b128 v[174:177], v254 offset:16384
	ds_read_b128 v[184:187], v254 offset:17408
	ds_read_b128 v[188:191], v254 offset:18432
	ds_read_b128 v[210:213], v254 offset:19456
	s_add_u32 s2, s0, 0x100
	s_addc_u32 s3, s1, 0
	s_cmp_eq_u32 s13, 40
	s_cselect_b32 s7, s27, s3
	s_cselect_b32 s6, s26, s2
	s_cselect_b32 s5, s37, s11
	s_cselect_b32 s4, s36, s10
	s_add_i32 m0, s29, 0xc000
	ds_read_b128 v[214:217], v181
	ds_read_b128 v[218:221], v181 offset:1024
	ds_read_b128 v[222:225], v181 offset:2048
	ds_read_b128 v[226:229], v181 offset:3072
	ds_read_b128 v[230:233], v181 offset:4096
	ds_read_b128 v[234:237], v181 offset:5120
	ds_read_b128 v[238:241], v181 offset:6144
	ds_read_b128 v[242:245], v181 offset:7168
	global_load_lds_dwordx4 v170, s[0:1]
	s_add_i32 m0, s29, 0xe000
	s_nop 0
	global_load_lds_dwordx4 v172, s[0:1]
	s_waitcnt vmcnt(8)
	s_waitcnt lgkmcnt(0)
	s_barrier
	s_setprio 1
	v_mfma_f32_16x16x32_bf16 v[124:127], v[128:131], v[214:217], 0
	v_mfma_f32_16x16x32_bf16 v[124:127], v[132:135], v[218:221], v[124:127]
	v_mfma_f32_16x16x32_bf16 v[108:111], v[128:131], v[222:225], 0
	v_mfma_f32_16x16x32_bf16 v[108:111], v[132:135], v[226:229], v[108:111]
	v_mfma_f32_16x16x32_bf16 v[92:95], v[128:131], v[230:233], 0
	v_mfma_f32_16x16x32_bf16 v[92:95], v[132:135], v[234:237], v[92:95]
	v_mfma_f32_16x16x32_bf16 v[76:79], v[128:131], v[238:241], 0
	v_mfma_f32_16x16x32_bf16 v[76:79], v[132:135], v[242:245], v[76:79]
	v_mfma_f32_16x16x32_bf16 v[120:123], v[136:139], v[214:217], 0
	v_mfma_f32_16x16x32_bf16 v[120:123], v[140:143], v[218:221], v[120:123]
	v_mfma_f32_16x16x32_bf16 v[104:107], v[136:139], v[222:225], 0
	v_mfma_f32_16x16x32_bf16 v[104:107], v[140:143], v[226:229], v[104:107]
	v_mfma_f32_16x16x32_bf16 v[88:91], v[136:139], v[230:233], 0
	v_mfma_f32_16x16x32_bf16 v[88:91], v[140:143], v[234:237], v[88:91]
	v_mfma_f32_16x16x32_bf16 v[72:75], v[136:139], v[238:241], 0
	v_mfma_f32_16x16x32_bf16 v[72:75], v[140:143], v[242:245], v[72:75]
	v_mfma_f32_16x16x32_bf16 v[116:119], v[174:177], v[214:217], 0
	v_mfma_f32_16x16x32_bf16 v[116:119], v[184:187], v[218:221], v[116:119]
	v_mfma_f32_16x16x32_bf16 v[100:103], v[174:177], v[222:225], 0
	v_mfma_f32_16x16x32_bf16 v[100:103], v[184:187], v[226:229], v[100:103]
	v_mfma_f32_16x16x32_bf16 v[84:87], v[174:177], v[230:233], 0
	v_mfma_f32_16x16x32_bf16 v[84:87], v[184:187], v[234:237], v[84:87]
	v_mfma_f32_16x16x32_bf16 v[68:71], v[174:177], v[238:241], 0
	v_mfma_f32_16x16x32_bf16 v[68:71], v[184:187], v[242:245], v[68:71]
	v_mfma_f32_16x16x32_bf16 v[112:115], v[188:191], v[214:217], 0
	v_mfma_f32_16x16x32_bf16 v[112:115], v[210:213], v[218:221], v[112:115]
	v_mfma_f32_16x16x32_bf16 v[96:99], v[188:191], v[222:225], 0
	v_mfma_f32_16x16x32_bf16 v[96:99], v[210:213], v[226:229], v[96:99]
	v_mfma_f32_16x16x32_bf16 v[80:83], v[188:191], v[230:233], 0
	v_mfma_f32_16x16x32_bf16 v[80:83], v[210:213], v[234:237], v[80:83]
	v_mfma_f32_16x16x32_bf16 v[64:67], v[188:191], v[238:241], 0
	v_mfma_f32_16x16x32_bf16 v[64:67], v[210:213], v[242:245], v[64:67]
	s_setprio 0
	s_barrier
	s_mov_b32 m0, s35
	s_add_u32 s0, s4, 0xb0000
	s_addc_u32 s1, s5, 0
	ds_read_b128 v[214:217], v181 offset:16384
	ds_read_b128 v[218:221], v181 offset:17408
	ds_read_b128 v[222:225], v181 offset:18432
	ds_read_b128 v[226:229], v181 offset:19456
	ds_read_b128 v[230:233], v181 offset:20480
	ds_read_b128 v[234:237], v181 offset:21504
	ds_read_b128 v[238:241], v181 offset:22528
	ds_read_b128 v[242:245], v181 offset:23552
	global_load_lds_dwordx4 v166, s[4:5]
	s_mov_b32 m0, s38
	s_nop 0
	global_load_lds_dwordx4 v162, s[4:5]
	s_mov_b32 m0, s39
	s_nop 0
	global_load_lds_dwordx4 v166, s[0:1]
	s_mov_b32 m0, s40
	s_nop 0
	global_load_lds_dwordx4 v162, s[0:1]
	s_mov_b32 m0, s29
	s_nop 0
	global_load_lds_dwordx4 v168, s[6:7]
	s_mov_b32 m0, s41
	s_nop 0
	global_load_lds_dwordx4 v164, s[6:7]
	s_waitcnt vmcnt(8)
	s_waitcnt lgkmcnt(0)
	s_barrier
	s_setprio 1
	v_mfma_f32_16x16x32_bf16 v[60:63], v[128:131], v[214:217], 0
	v_mfma_f32_16x16x32_bf16 v[60:63], v[132:135], v[218:221], v[60:63]
	v_mfma_f32_16x16x32_bf16 v[44:47], v[128:131], v[222:225], 0
	v_mfma_f32_16x16x32_bf16 v[44:47], v[132:135], v[226:229], v[44:47]
	v_mfma_f32_16x16x32_bf16 v[28:31], v[128:131], v[230:233], 0
	v_mfma_f32_16x16x32_bf16 v[28:31], v[132:135], v[234:237], v[28:31]
	v_mfma_f32_16x16x32_bf16 v[12:15], v[128:131], v[238:241], 0
	v_mfma_f32_16x16x32_bf16 v[12:15], v[132:135], v[242:245], v[12:15]
	v_mfma_f32_16x16x32_bf16 v[56:59], v[136:139], v[214:217], 0
	v_mfma_f32_16x16x32_bf16 v[56:59], v[140:143], v[218:221], v[56:59]
	v_mfma_f32_16x16x32_bf16 v[40:43], v[136:139], v[222:225], 0
	v_mfma_f32_16x16x32_bf16 v[40:43], v[140:143], v[226:229], v[40:43]
	v_mfma_f32_16x16x32_bf16 v[24:27], v[136:139], v[230:233], 0
	v_mfma_f32_16x16x32_bf16 v[24:27], v[140:143], v[234:237], v[24:27]
	v_mfma_f32_16x16x32_bf16 v[8:11], v[136:139], v[238:241], 0
	v_mfma_f32_16x16x32_bf16 v[8:11], v[140:143], v[242:245], v[8:11]
	v_mfma_f32_16x16x32_bf16 v[52:55], v[174:177], v[214:217], 0
	v_mfma_f32_16x16x32_bf16 v[52:55], v[184:187], v[218:221], v[52:55]
	v_mfma_f32_16x16x32_bf16 v[36:39], v[174:177], v[222:225], 0
	v_mfma_f32_16x16x32_bf16 v[36:39], v[184:187], v[226:229], v[36:39]
	v_mfma_f32_16x16x32_bf16 v[20:23], v[174:177], v[230:233], 0
	v_mfma_f32_16x16x32_bf16 v[20:23], v[184:187], v[234:237], v[20:23]
	v_mfma_f32_16x16x32_bf16 v[4:7], v[174:177], v[238:241], 0
	v_mfma_f32_16x16x32_bf16 v[4:7], v[184:187], v[242:245], v[4:7]
	v_mfma_f32_16x16x32_bf16 v[48:51], v[188:191], v[214:217], 0
	v_mfma_f32_16x16x32_bf16 v[48:51], v[210:213], v[218:221], v[48:51]
	v_mfma_f32_16x16x32_bf16 v[32:35], v[188:191], v[222:225], 0
	v_mfma_f32_16x16x32_bf16 v[32:35], v[210:213], v[226:229], v[32:35]
	v_mfma_f32_16x16x32_bf16 v[16:19], v[188:191], v[230:233], 0
	v_mfma_f32_16x16x32_bf16 v[16:19], v[210:213], v[234:237], v[16:19]
	v_mfma_f32_16x16x32_bf16 v[0:3], v[188:191], v[238:241], 0
	v_mfma_f32_16x16x32_bf16 v[0:3], v[210:213], v[242:245], v[0:3]
	s_setprio 0
	s_barrier
; #define PG8_STAGE(bufoff, gbase, voff) do { _Pragma("unroll") for (int _i = 0; _i < 2; ++_i) \
;         __builtin_amdgcn_global_load_lds((const unsigned*)((const char*)(gbase) + (voff)[_i]), (PG8_LAS unsigned*)(lds + (bufoff) + ldsw + _i * 8192), 16, 0, 0); } while (0)
; #define PG8_LDA(dst, b, h) do { _Pragma("unroll") for (int m = 0; m < 4; ++m) _Pragma("unroll") for (int k = 0; k < 2; ++k) dst[m][k] = *(const PG8_LAS bf16x8*)(lds + PG8_SA(b, h) + aoff + m * 2048 + k * 1024); } while (0)
; #define PG8_LDB(dst, b, h) do { _Pragma("unroll") for (int n = 0; n < 2; ++n) _Pragma("unroll") for (int k = 0; k < 2; ++k) dst[n][k] = *(const PG8_LAS bf16x8*)(lds + PG8_SB(b, h) + boff + n * 2048 + k * 1024); } while (0)
; #define PG8_MMA(ai, bj, At, Bt) do { __builtin_amdgcn_s_setprio(1); _Pragma("unroll") for (int m = 0; m < 4; ++m) _Pragma("unroll") for (int n = 0; n < 2; ++n) _Pragma("unroll") for (int k = 0; k < 2; ++k) \
;         acc[ai][bj][m][n] = __builtin_amdgcn_mfma_f32_16x16x32_bf16(Bt[n][k], At[m][k], acc[ai][bj][m][n], 0, 0, 0); __builtin_amdgcn_s_setprio(0); } while (0)
; #define PG8_WAIT_V(n) asm volatile("s_waitcnt vmcnt(" #n ")" ::: "memory")
; #define PG8_WAIT_L(n) asm volatile("s_waitcnt lgkmcnt(" #n ")" ::: "memory")
; #define PG8_BAR __builtin_amdgcn_s_barrier()
; #define PG8_SCHED __builtin_amdgcn_sched_barrier(0)
; template <class Epi, class Sched, bool ALIGN_EPI = false, bool SP2 = false>
; __device__ __forceinline__ void gemm_phase(PG8_LAS unsigned char* lds, const Gemm g, const Sched& S, const Epi& E) {
;     ...
;             PG8_LDB(B0, 1, 0); PG8_LDB(B1, 1, 1); PG8_SCHED; PG8_LDA(At, 1, 0); PG8_STAGE(PG8_SA(0, 1), a2 + hstep, voffA);
;             PG8_WAIT_V(8); PG8_WAIT_L(0); PG8_BAR; PG8_MMA(0, 0, At, B0); PG8_MMA(0, 1, At, B1); PG8_BAR; PG8_SCHED;
;             PG8_LDA(At, 1, 1); PG8_STAGE(PG8_SB(1, 0), b3, voffB); PG8_STAGE(PG8_SB(1, 1), b3 + hstep, voffB); PG8_STAGE(PG8_SA(1, 0), a3, voffA);
;             PG8_WAIT_V(8); PG8_WAIT_L(0); PG8_BAR; PG8_MMA(1, 0, At, B0); PG8_MMA(1, 1, At, B1); PG8_BAR; PG8_SCHED;
	ds_read_b128 v[128:131], v254 offset:32768
	ds_read_b128 v[132:135], v254 offset:33792
	ds_read_b128 v[136:139], v254 offset:34816
	ds_read_b128 v[140:143], v254 offset:35840
	ds_read_b128 v[174:177], v254 offset:49152
	ds_read_b128 v[184:187], v254 offset:50176
	ds_read_b128 v[188:191], v254 offset:51200
	ds_read_b128 v[210:213], v254 offset:52224
	s_add_u32 s0, s6, 0xb0000
	s_addc_u32 s1, s7, 0
	s_mov_b32 m0, s42
	ds_read_b128 v[214:217], v181 offset:32768
	ds_read_b128 v[218:221], v181 offset:33792
	ds_read_b128 v[222:225], v181 offset:34816
	ds_read_b128 v[226:229], v181 offset:35840
	ds_read_b128 v[230:233], v181 offset:36864
	ds_read_b128 v[234:237], v181 offset:37888
	ds_read_b128 v[238:241], v181 offset:38912
	ds_read_b128 v[242:245], v181 offset:39936
	global_load_lds_dwordx4 v168, s[0:1]
	s_mov_b32 m0, s43
	s_nop 0
	global_load_lds_dwordx4 v164, s[0:1]
	s_waitcnt vmcnt(8)
	s_waitcnt lgkmcnt(0)
	s_barrier
	s_setprio 1
	v_mfma_f32_16x16x32_bf16 v[124:127], v[128:131], v[214:217], v[124:127]
	v_mfma_f32_16x16x32_bf16 v[124:127], v[132:135], v[218:221], v[124:127]
	v_mfma_f32_16x16x32_bf16 v[108:111], v[128:131], v[222:225], v[108:111]
	v_mfma_f32_16x16x32_bf16 v[108:111], v[132:135], v[226:229], v[108:111]
	v_mfma_f32_16x16x32_bf16 v[92:95], v[128:131], v[230:233], v[92:95]
	v_mfma_f32_16x16x32_bf16 v[92:95], v[132:135], v[234:237], v[92:95]
	v_mfma_f32_16x16x32_bf16 v[76:79], v[128:131], v[238:241], v[76:79]
	v_mfma_f32_16x16x32_bf16 v[76:79], v[132:135], v[242:245], v[76:79]
	v_mfma_f32_16x16x32_bf16 v[120:123], v[136:139], v[214:217], v[120:123]
	v_mfma_f32_16x16x32_bf16 v[120:123], v[140:143], v[218:221], v[120:123]
	v_mfma_f32_16x16x32_bf16 v[104:107], v[136:139], v[222:225], v[104:107]
	v_mfma_f32_16x16x32_bf16 v[104:107], v[140:143], v[226:229], v[104:107]
	v_mfma_f32_16x16x32_bf16 v[88:91], v[136:139], v[230:233], v[88:91]
	v_mfma_f32_16x16x32_bf16 v[88:91], v[140:143], v[234:237], v[88:91]
	v_mfma_f32_16x16x32_bf16 v[72:75], v[136:139], v[238:241], v[72:75]
	v_mfma_f32_16x16x32_bf16 v[72:75], v[140:143], v[242:245], v[72:75]
	v_mfma_f32_16x16x32_bf16 v[116:119], v[174:177], v[214:217], v[116:119]
	v_mfma_f32_16x16x32_bf16 v[116:119], v[184:187], v[218:221], v[116:119]
	v_mfma_f32_16x16x32_bf16 v[100:103], v[174:177], v[222:225], v[100:103]
	v_mfma_f32_16x16x32_bf16 v[100:103], v[184:187], v[226:229], v[100:103]
	v_mfma_f32_16x16x32_bf16 v[84:87], v[174:177], v[230:233], v[84:87]
	v_mfma_f32_16x16x32_bf16 v[84:87], v[184:187], v[234:237], v[84:87]
	v_mfma_f32_16x16x32_bf16 v[68:71], v[174:177], v[238:241], v[68:71]
	v_mfma_f32_16x16x32_bf16 v[68:71], v[184:187], v[242:245], v[68:71]
	v_mfma_f32_16x16x32_bf16 v[112:115], v[188:191], v[214:217], v[112:115]
	v_mfma_f32_16x16x32_bf16 v[112:115], v[210:213], v[218:221], v[112:115]
	v_mfma_f32_16x16x32_bf16 v[96:99], v[188:191], v[222:225], v[96:99]
	v_mfma_f32_16x16x32_bf16 v[96:99], v[210:213], v[226:229], v[96:99]
	v_mfma_f32_16x16x32_bf16 v[80:83], v[188:191], v[230:233], v[80:83]
	v_mfma_f32_16x16x32_bf16 v[80:83], v[210:213], v[234:237], v[80:83]
	v_mfma_f32_16x16x32_bf16 v[64:67], v[188:191], v[238:241], v[64:67]
	v_mfma_f32_16x16x32_bf16 v[64:67], v[210:213], v[242:245], v[64:67]
	s_setprio 0
	s_barrier
	s_mov_b32 m0, s47
	s_add_u32 s0, s4, 0xb0080
	s_addc_u32 s1, s5, 0
	ds_read_b128 v[214:217], v181 offset:49152
	ds_read_b128 v[218:221], v181 offset:50176
	ds_read_b128 v[222:225], v181 offset:51200
	ds_read_b128 v[226:229], v181 offset:52224
	ds_read_b128 v[230:233], v181 offset:53248
	ds_read_b128 v[234:237], v181 offset:54272
	ds_read_b128 v[238:241], v181 offset:55296
	ds_read_b128 v[242:245], v181 offset:56320
	s_add_u32 s98, s4, 0x80
	s_addc_u32 s99, s5, 0
	global_load_lds_dwordx4 v166, s[98:99]
	s_mov_b32 m0, s48
	s_nop 0
	global_load_lds_dwordx4 v162, s[98:99]
	s_mov_b32 m0, s51
	s_nop 0
	global_load_lds_dwordx4 v166, s[0:1]
	s_mov_b32 m0, s52
	s_nop 0
	global_load_lds_dwordx4 v162, s[0:1]
	s_mov_b32 m0, s49
	s_nop 0
	s_add_u32 s100, s6, 0x80
	s_addc_u32 s101, s7, 0
	global_load_lds_dwordx4 v168, s[100:101]
	s_mov_b32 m0, s50
	s_nop 0
	global_load_lds_dwordx4 v164, s[100:101]
	s_waitcnt vmcnt(8)
	s_waitcnt lgkmcnt(0)
	s_barrier
	s_setprio 1
	v_mfma_f32_16x16x32_bf16 v[60:63], v[128:131], v[214:217], v[60:63]
	v_mfma_f32_16x16x32_bf16 v[60:63], v[132:135], v[218:221], v[60:63]
	v_mfma_f32_16x16x32_bf16 v[44:47], v[128:131], v[222:225], v[44:47]
	v_mfma_f32_16x16x32_bf16 v[44:47], v[132:135], v[226:229], v[44:47]
	v_mfma_f32_16x16x32_bf16 v[28:31], v[128:131], v[230:233], v[28:31]
	v_mfma_f32_16x16x32_bf16 v[28:31], v[132:135], v[234:237], v[28:31]
	v_mfma_f32_16x16x32_bf16 v[12:15], v[128:131], v[238:241], v[12:15]
	v_mfma_f32_16x16x32_bf16 v[12:15], v[132:135], v[242:245], v[12:15]
	v_mfma_f32_16x16x32_bf16 v[56:59], v[136:139], v[214:217], v[56:59]
	v_mfma_f32_16x16x32_bf16 v[56:59], v[140:143], v[218:221], v[56:59]
	v_mfma_f32_16x16x32_bf16 v[40:43], v[136:139], v[222:225], v[40:43]
	v_mfma_f32_16x16x32_bf16 v[40:43], v[140:143], v[226:229], v[40:43]
	v_mfma_f32_16x16x32_bf16 v[24:27], v[136:139], v[230:233], v[24:27]
	v_mfma_f32_16x16x32_bf16 v[24:27], v[140:143], v[234:237], v[24:27]
	v_mfma_f32_16x16x32_bf16 v[8:11], v[136:139], v[238:241], v[8:11]
	v_mfma_f32_16x16x32_bf16 v[8:11], v[140:143], v[242:245], v[8:11]
	v_mfma_f32_16x16x32_bf16 v[52:55], v[174:177], v[214:217], v[52:55]
	v_mfma_f32_16x16x32_bf16 v[52:55], v[184:187], v[218:221], v[52:55]
	v_mfma_f32_16x16x32_bf16 v[36:39], v[174:177], v[222:225], v[36:39]
	v_mfma_f32_16x16x32_bf16 v[36:39], v[184:187], v[226:229], v[36:39]
	v_mfma_f32_16x16x32_bf16 v[20:23], v[174:177], v[230:233], v[20:23]
	v_mfma_f32_16x16x32_bf16 v[20:23], v[184:187], v[234:237], v[20:23]
	v_mfma_f32_16x16x32_bf16 v[4:7], v[174:177], v[238:241], v[4:7]
	v_mfma_f32_16x16x32_bf16 v[4:7], v[184:187], v[242:245], v[4:7]
	v_mfma_f32_16x16x32_bf16 v[48:51], v[188:191], v[214:217], v[48:51]
	v_mfma_f32_16x16x32_bf16 v[48:51], v[210:213], v[218:221], v[48:51]
	v_mfma_f32_16x16x32_bf16 v[32:35], v[188:191], v[222:225], v[32:35]
	v_mfma_f32_16x16x32_bf16 v[32:35], v[210:213], v[226:229], v[32:35]
	v_mfma_f32_16x16x32_bf16 v[16:19], v[188:191], v[230:233], v[16:19]
	v_mfma_f32_16x16x32_bf16 v[16:19], v[210:213], v[234:237], v[16:19]
	v_mfma_f32_16x16x32_bf16 v[0:3], v[188:191], v[238:241], v[0:3]
	v_mfma_f32_16x16x32_bf16 v[0:3], v[210:213], v[242:245], v[0:3]
	s_setprio 0
	s_barrier
	s_add_i32 s13, s13, 2
	s_add_u32 s10, s10, 0x100
	s_addc_u32 s11, s11, 0
	s_cmp_gt_u32 s13, 41
	s_mov_b64 s[0:1], s[2:3]
; #define PG8_STAGE(bufoff, gbase, voff) do { _Pragma("unroll") for (int _i = 0; _i < 2; ++_i) \
;         __builtin_amdgcn_global_load_lds((const unsigned*)((const char*)(gbase) + (voff)[_i]), (PG8_LAS unsigned*)(lds + (bufoff) + ldsw + _i * 8192), 16, 0, 0); } while (0)
; #define PG8_LDA(dst, b, h) do { _Pragma("unroll") for (int m = 0; m < 4; ++m) _Pragma("unroll") for (int k = 0; k < 2; ++k) dst[m][k] = *(const PG8_LAS bf16x8*)(lds + PG8_SA(b, h) + aoff + m * 2048 + k * 1024); } while (0)
; #define PG8_LDB(dst, b, h) do { _Pragma("unroll") for (int n = 0; n < 2; ++n) _Pragma("unroll") for (int k = 0; k < 2; ++k) dst[n][k] = *(const PG8_LAS bf16x8*)(lds + PG8_SB(b, h) + boff + n * 2048 + k * 1024); } while (0)
; #define PG8_MMA(ai, bj, At, Bt) do { __builtin_amdgcn_s_setprio(1); _Pragma("unroll") for (int m = 0; m < 4; ++m) _Pragma("unroll") for (int n = 0; n < 2; ++n) _Pragma("unroll") for (int k = 0; k < 2; ++k) \
;         acc[ai][bj][m][n] = __builtin_amdgcn_mfma_f32_16x16x32_bf16(Bt[n][k], At[m][k], acc[ai][bj][m][n], 0, 0, 0); __builtin_amdgcn_s_setprio(0); } while (0)
; #define PG8_WAIT_V(n) asm volatile("s_waitcnt vmcnt(" #n ")" ::: "memory")
; #define PG8_BAR __builtin_amdgcn_s_barrier()
; template <class Epi, class Sched, bool ALIGN_EPI = false, bool SP2 = false>
; __device__ __forceinline__ void gemm_phase(PG8_LAS unsigned char* lds, const Gemm g, const Sched& S, const Epi& E) {
;     ...
;         for (int t = 0; t < nt; t += 2) {
;             const bool last = (t == nt - 2);
;             const char* a1 = cA + (size_t)(t + 1) * kstep;
;             const char* a2 = last ? nA : cA + (size_t)(t + 2) * kstep; const char* b2 = last ? nB : cB + (size_t)(t + 2) * kstep;
;             const char* a3 = a2 + kstep; const char* b3 = b2 + kstep;
;             if (last && has_next) S.a_ready(nxt);
;             if constexpr (SP2) {
;             PG8_LDB(B0, 0, 0); PG8_LDB(B1, 0, 1); PG8_SCHED; PG8_LDA(At, 0, 0); PG8_STAGE(PG8_SA(1, 1), a1 + hstep, voffA);
;             PG8_WAIT_V(8); PG8_WAIT_L(0); PG8_BAR; PG8_MMA(0, 0, At, B0); PG8_MMA(0, 1, At, B1); PG8_BAR; PG8_SCHED;
;             PG8_LDA(At, 0, 1); PG8_STAGE(PG8_SB(0, 0), b2, voffB); PG8_STAGE(PG8_SB(0, 1), b2 + hstep, voffB); PG8_STAGE(PG8_SA(0, 0), a2, voffA);
;             PG8_WAIT_V(8); PG8_WAIT_L(0); PG8_BAR; PG8_MMA(1, 0, At, B0); PG8_MMA(1, 1, At, B1); PG8_BAR; PG8_SCHED;
.LBB0_545:
	ds_read_b128 v[128:131], v254
	ds_read_b128 v[132:135], v254 offset:1024
	ds_read_b128 v[136:139], v254 offset:2048
	ds_read_b128 v[140:143], v254 offset:3072
	ds_read_b128 v[174:177], v254 offset:16384
	ds_read_b128 v[184:187], v254 offset:17408
	ds_read_b128 v[188:191], v254 offset:18432
	ds_read_b128 v[210:213], v254 offset:19456
	s_add_u32 s2, s0, 0x100
	s_addc_u32 s3, s1, 0
	s_cmp_eq_u32 s13, 40
	s_cselect_b32 s7, s27, s3
	s_cselect_b32 s6, s26, s2
	s_cselect_b32 s5, s37, s11
	s_cselect_b32 s4, s36, s10
	s_add_i32 m0, s29, 0xc000
	ds_read_b128 v[214:217], v181
	ds_read_b128 v[218:221], v181 offset:1024
	ds_read_b128 v[222:225], v181 offset:2048
	ds_read_b128 v[226:229], v181 offset:3072
	ds_read_b128 v[230:233], v181 offset:4096
	ds_read_b128 v[234:237], v181 offset:5120
	ds_read_b128 v[238:241], v181 offset:6144
	ds_read_b128 v[242:245], v181 offset:7168
	global_load_lds_dwordx4 v170, s[0:1]
	s_add_i32 m0, s29, 0xe000
	s_nop 0
	global_load_lds_dwordx4 v172, s[0:1]
	s_waitcnt vmcnt(8)
	s_waitcnt lgkmcnt(0)
	s_barrier
	s_setprio 1
	v_mfma_f32_16x16x32_bf16 v[124:127], v[128:131], v[214:217], v[124:127]
	v_mfma_f32_16x16x32_bf16 v[124:127], v[132:135], v[218:221], v[124:127]
	v_mfma_f32_16x16x32_bf16 v[108:111], v[128:131], v[222:225], v[108:111]
	v_mfma_f32_16x16x32_bf16 v[108:111], v[132:135], v[226:229], v[108:111]
	v_mfma_f32_16x16x32_bf16 v[92:95], v[128:131], v[230:233], v[92:95]
	v_mfma_f32_16x16x32_bf16 v[92:95], v[132:135], v[234:237], v[92:95]
	v_mfma_f32_16x16x32_bf16 v[76:79], v[128:131], v[238:241], v[76:79]
	v_mfma_f32_16x16x32_bf16 v[76:79], v[132:135], v[242:245], v[76:79]
	v_mfma_f32_16x16x32_bf16 v[120:123], v[136:139], v[214:217], v[120:123]
	v_mfma_f32_16x16x32_bf16 v[120:123], v[140:143], v[218:221], v[120:123]
	v_mfma_f32_16x16x32_bf16 v[104:107], v[136:139], v[222:225], v[104:107]
	v_mfma_f32_16x16x32_bf16 v[104:107], v[140:143], v[226:229], v[104:107]
	v_mfma_f32_16x16x32_bf16 v[88:91], v[136:139], v[230:233], v[88:91]
	v_mfma_f32_16x16x32_bf16 v[88:91], v[140:143], v[234:237], v[88:91]
	v_mfma_f32_16x16x32_bf16 v[72:75], v[136:139], v[238:241], v[72:75]
	v_mfma_f32_16x16x32_bf16 v[72:75], v[140:143], v[242:245], v[72:75]
	v_mfma_f32_16x16x32_bf16 v[116:119], v[174:177], v[214:217], v[116:119]
	v_mfma_f32_16x16x32_bf16 v[116:119], v[184:187], v[218:221], v[116:119]
	v_mfma_f32_16x16x32_bf16 v[100:103], v[174:177], v[222:225], v[100:103]
	v_mfma_f32_16x16x32_bf16 v[100:103], v[184:187], v[226:229], v[100:103]
	v_mfma_f32_16x16x32_bf16 v[84:87], v[174:177], v[230:233], v[84:87]
	v_mfma_f32_16x16x32_bf16 v[84:87], v[184:187], v[234:237], v[84:87]
	v_mfma_f32_16x16x32_bf16 v[68:71], v[174:177], v[238:241], v[68:71]
	v_mfma_f32_16x16x32_bf16 v[68:71], v[184:187], v[242:245], v[68:71]
	v_mfma_f32_16x16x32_bf16 v[112:115], v[188:191], v[214:217], v[112:115]
	v_mfma_f32_16x16x32_bf16 v[112:115], v[210:213], v[218:221], v[112:115]
	v_mfma_f32_16x16x32_bf16 v[96:99], v[188:191], v[222:225], v[96:99]
	v_mfma_f32_16x16x32_bf16 v[96:99], v[210:213], v[226:229], v[96:99]
	v_mfma_f32_16x16x32_bf16 v[80:83], v[188:191], v[230:233], v[80:83]
	v_mfma_f32_16x16x32_bf16 v[80:83], v[210:213], v[234:237], v[80:83]
	v_mfma_f32_16x16x32_bf16 v[64:67], v[188:191], v[238:241], v[64:67]
	v_mfma_f32_16x16x32_bf16 v[64:67], v[210:213], v[242:245], v[64:67]
	s_setprio 0
	s_barrier
	s_mov_b32 m0, s35
	s_add_u32 s0, s4, 0xb0000
	s_addc_u32 s1, s5, 0
	ds_read_b128 v[214:217], v181 offset:16384
	ds_read_b128 v[218:221], v181 offset:17408
	ds_read_b128 v[222:225], v181 offset:18432
	ds_read_b128 v[226:229], v181 offset:19456
	ds_read_b128 v[230:233], v181 offset:20480
	ds_read_b128 v[234:237], v181 offset:21504
	ds_read_b128 v[238:241], v181 offset:22528
	ds_read_b128 v[242:245], v181 offset:23552
	global_load_lds_dwordx4 v166, s[4:5]
	s_mov_b32 m0, s38
	s_nop 0
	global_load_lds_dwordx4 v162, s[4:5]
	s_mov_b32 m0, s39
	s_nop 0
	global_load_lds_dwordx4 v166, s[0:1]
	s_mov_b32 m0, s40
	s_nop 0
	global_load_lds_dwordx4 v162, s[0:1]
	s_mov_b32 m0, s29
	s_nop 0
	global_load_lds_dwordx4 v168, s[6:7]
	s_mov_b32 m0, s41
	s_nop 0
	global_load_lds_dwordx4 v164, s[6:7]
	s_waitcnt vmcnt(8)
	s_waitcnt lgkmcnt(0)
	s_barrier
	s_setprio 1
	v_mfma_f32_16x16x32_bf16 v[60:63], v[128:131], v[214:217], v[60:63]
	v_mfma_f32_16x16x32_bf16 v[60:63], v[132:135], v[218:221], v[60:63]
	v_mfma_f32_16x16x32_bf16 v[44:47], v[128:131], v[222:225], v[44:47]
	v_mfma_f32_16x16x32_bf16 v[44:47], v[132:135], v[226:229], v[44:47]
	v_mfma_f32_16x16x32_bf16 v[28:31], v[128:131], v[230:233], v[28:31]
	v_mfma_f32_16x16x32_bf16 v[28:31], v[132:135], v[234:237], v[28:31]
	v_mfma_f32_16x16x32_bf16 v[12:15], v[128:131], v[238:241], v[12:15]
	v_mfma_f32_16x16x32_bf16 v[12:15], v[132:135], v[242:245], v[12:15]
	v_mfma_f32_16x16x32_bf16 v[56:59], v[136:139], v[214:217], v[56:59]
	v_mfma_f32_16x16x32_bf16 v[56:59], v[140:143], v[218:221], v[56:59]
	v_mfma_f32_16x16x32_bf16 v[40:43], v[136:139], v[222:225], v[40:43]
	v_mfma_f32_16x16x32_bf16 v[40:43], v[140:143], v[226:229], v[40:43]
	v_mfma_f32_16x16x32_bf16 v[24:27], v[136:139], v[230:233], v[24:27]
	v_mfma_f32_16x16x32_bf16 v[24:27], v[140:143], v[234:237], v[24:27]
	v_mfma_f32_16x16x32_bf16 v[8:11], v[136:139], v[238:241], v[8:11]
	v_mfma_f32_16x16x32_bf16 v[8:11], v[140:143], v[242:245], v[8:11]
	v_mfma_f32_16x16x32_bf16 v[52:55], v[174:177], v[214:217], v[52:55]
	v_mfma_f32_16x16x32_bf16 v[52:55], v[184:187], v[218:221], v[52:55]
	v_mfma_f32_16x16x32_bf16 v[36:39], v[174:177], v[222:225], v[36:39]
	v_mfma_f32_16x16x32_bf16 v[36:39], v[184:187], v[226:229], v[36:39]
	v_mfma_f32_16x16x32_bf16 v[20:23], v[174:177], v[230:233], v[20:23]
	v_mfma_f32_16x16x32_bf16 v[20:23], v[184:187], v[234:237], v[20:23]
	v_mfma_f32_16x16x32_bf16 v[4:7], v[174:177], v[238:241], v[4:7]
	v_mfma_f32_16x16x32_bf16 v[4:7], v[184:187], v[242:245], v[4:7]
	v_mfma_f32_16x16x32_bf16 v[48:51], v[188:191], v[214:217], v[48:51]
	v_mfma_f32_16x16x32_bf16 v[48:51], v[210:213], v[218:221], v[48:51]
	v_mfma_f32_16x16x32_bf16 v[32:35], v[188:191], v[222:225], v[32:35]
	v_mfma_f32_16x16x32_bf16 v[32:35], v[210:213], v[226:229], v[32:35]
	v_mfma_f32_16x16x32_bf16 v[16:19], v[188:191], v[230:233], v[16:19]
	v_mfma_f32_16x16x32_bf16 v[16:19], v[210:213], v[234:237], v[16:19]
	v_mfma_f32_16x16x32_bf16 v[0:3], v[188:191], v[238:241], v[0:3]
	v_mfma_f32_16x16x32_bf16 v[0:3], v[210:213], v[242:245], v[0:3]
	s_setprio 0
	s_barrier
; #define PG8_STAGE(bufoff, gbase, voff) do { _Pragma("unroll") for (int _i = 0; _i < 2; ++_i) \
;         __builtin_amdgcn_global_load_lds((const unsigned*)((const char*)(gbase) + (voff)[_i]), (PG8_LAS unsigned*)(lds + (bufoff) + ldsw + _i * 8192), 16, 0, 0); } while (0)
; #define PG8_LDA(dst, b, h) do { _Pragma("unroll") for (int m = 0; m < 4; ++m) _Pragma("unroll") for (int k = 0; k < 2; ++k) dst[m][k] = *(const PG8_LAS bf16x8*)(lds + PG8_SA(b, h) + aoff + m * 2048 + k * 1024); } while (0)
; #define PG8_LDB(dst, b, h) do { _Pragma("unroll") for (int n = 0; n < 2; ++n) _Pragma("unroll") for (int k = 0; k < 2; ++k) dst[n][k] = *(const PG8_LAS bf16x8*)(lds + PG8_SB(b, h) + boff + n * 2048 + k * 1024); } while (0)
; #define PG8_MMA(ai, bj, At, Bt) do { __builtin_amdgcn_s_setprio(1); _Pragma("unroll") for (int m = 0; m < 4; ++m) _Pragma("unroll") for (int n = 0; n < 2; ++n) _Pragma("unroll") for (int k = 0; k < 2; ++k) \
;         acc[ai][bj][m][n] = __builtin_amdgcn_mfma_f32_16x16x32_bf16(Bt[n][k], At[m][k], acc[ai][bj][m][n], 0, 0, 0); __builtin_amdgcn_s_setprio(0); } while (0)
; #define PG8_WAIT_V(n) asm volatile("s_waitcnt vmcnt(" #n ")" ::: "memory")
; #define PG8_WAIT_L(n) asm volatile("s_waitcnt lgkmcnt(" #n ")" ::: "memory")
; #define PG8_BAR __builtin_amdgcn_s_barrier()
; #define PG8_SCHED __builtin_amdgcn_sched_barrier(0)
; template <class Epi, class Sched, bool ALIGN_EPI = false, bool SP2 = false>
; __device__ __forceinline__ void gemm_phase(PG8_LAS unsigned char* lds, const Gemm g, const Sched& S, const Epi& E) {
;     ...
;         for (int t = 0; t < nt; t += 2) {
;             const bool last = (t == nt - 2);
;             const char* a1 = cA + (size_t)(t + 1) * kstep;
;             const char* a2 = last ? nA : cA + (size_t)(t + 2) * kstep; const char* b2 = last ? nB : cB + (size_t)(t + 2) * kstep;
;     ...
;             PG8_LDB(B0, 1, 0); PG8_LDB(B1, 1, 1); PG8_SCHED; PG8_LDA(At, 1, 0); PG8_STAGE(PG8_SA(0, 1), a2 + hstep, voffA);
;             PG8_WAIT_V(8); PG8_WAIT_L(0); PG8_BAR; PG8_MMA(0, 0, At, B0); PG8_MMA(0, 1, At, B1); PG8_BAR; PG8_SCHED;
;             PG8_LDA(At, 1, 1); PG8_STAGE(PG8_SB(1, 0), b3, voffB); PG8_STAGE(PG8_SB(1, 1), b3 + hstep, voffB); PG8_STAGE(PG8_SA(1, 0), a3, voffA);
;             PG8_WAIT_V(8); PG8_WAIT_L(0); PG8_BAR; PG8_MMA(1, 0, At, B0); PG8_MMA(1, 1, At, B1); PG8_BAR; PG8_SCHED;
	ds_read_b128 v[128:131], v254 offset:32768
	ds_read_b128 v[132:135], v254 offset:33792
	ds_read_b128 v[136:139], v254 offset:34816
	ds_read_b128 v[140:143], v254 offset:35840
	ds_read_b128 v[174:177], v254 offset:49152
	ds_read_b128 v[184:187], v254 offset:50176
	ds_read_b128 v[188:191], v254 offset:51200
	ds_read_b128 v[210:213], v254 offset:52224
	s_add_u32 s0, s6, 0xb0000
	s_addc_u32 s1, s7, 0
	s_mov_b32 m0, s42
	ds_read_b128 v[214:217], v181 offset:32768
	ds_read_b128 v[218:221], v181 offset:33792
	ds_read_b128 v[222:225], v181 offset:34816
	ds_read_b128 v[226:229], v181 offset:35840
	ds_read_b128 v[230:233], v181 offset:36864
	ds_read_b128 v[234:237], v181 offset:37888
	ds_read_b128 v[238:241], v181 offset:38912
	ds_read_b128 v[242:245], v181 offset:39936
	global_load_lds_dwordx4 v168, s[0:1]
	s_mov_b32 m0, s43
	s_nop 0
	global_load_lds_dwordx4 v164, s[0:1]
	s_waitcnt vmcnt(8)
	s_waitcnt lgkmcnt(0)
	s_barrier
	s_setprio 1
	v_mfma_f32_16x16x32_bf16 v[124:127], v[128:131], v[214:217], v[124:127]
	v_mfma_f32_16x16x32_bf16 v[124:127], v[132:135], v[218:221], v[124:127]
	v_mfma_f32_16x16x32_bf16 v[108:111], v[128:131], v[222:225], v[108:111]
	v_mfma_f32_16x16x32_bf16 v[108:111], v[132:135], v[226:229], v[108:111]
	v_mfma_f32_16x16x32_bf16 v[92:95], v[128:131], v[230:233], v[92:95]
	v_mfma_f32_16x16x32_bf16 v[92:95], v[132:135], v[234:237], v[92:95]
	v_mfma_f32_16x16x32_bf16 v[76:79], v[128:131], v[238:241], v[76:79]
	v_mfma_f32_16x16x32_bf16 v[76:79], v[132:135], v[242:245], v[76:79]
	v_mfma_f32_16x16x32_bf16 v[120:123], v[136:139], v[214:217], v[120:123]
	v_mfma_f32_16x16x32_bf16 v[120:123], v[140:143], v[218:221], v[120:123]
	v_mfma_f32_16x16x32_bf16 v[104:107], v[136:139], v[222:225], v[104:107]
	v_mfma_f32_16x16x32_bf16 v[104:107], v[140:143], v[226:229], v[104:107]
	v_mfma_f32_16x16x32_bf16 v[88:91], v[136:139], v[230:233], v[88:91]
	v_mfma_f32_16x16x32_bf16 v[88:91], v[140:143], v[234:237], v[88:91]
	v_mfma_f32_16x16x32_bf16 v[72:75], v[136:139], v[238:241], v[72:75]
	v_mfma_f32_16x16x32_bf16 v[72:75], v[140:143], v[242:245], v[72:75]
	v_mfma_f32_16x16x32_bf16 v[116:119], v[174:177], v[214:217], v[116:119]
	v_mfma_f32_16x16x32_bf16 v[116:119], v[184:187], v[218:221], v[116:119]
	v_mfma_f32_16x16x32_bf16 v[100:103], v[174:177], v[222:225], v[100:103]
	v_mfma_f32_16x16x32_bf16 v[100:103], v[184:187], v[226:229], v[100:103]
	v_mfma_f32_16x16x32_bf16 v[84:87], v[174:177], v[230:233], v[84:87]
	v_mfma_f32_16x16x32_bf16 v[84:87], v[184:187], v[234:237], v[84:87]
	v_mfma_f32_16x16x32_bf16 v[68:71], v[174:177], v[238:241], v[68:71]
	v_mfma_f32_16x16x32_bf16 v[68:71], v[184:187], v[242:245], v[68:71]
	v_mfma_f32_16x16x32_bf16 v[112:115], v[188:191], v[214:217], v[112:115]
	v_mfma_f32_16x16x32_bf16 v[112:115], v[210:213], v[218:221], v[112:115]
	v_mfma_f32_16x16x32_bf16 v[96:99], v[188:191], v[222:225], v[96:99]
	v_mfma_f32_16x16x32_bf16 v[96:99], v[210:213], v[226:229], v[96:99]
	v_mfma_f32_16x16x32_bf16 v[80:83], v[188:191], v[230:233], v[80:83]
	v_mfma_f32_16x16x32_bf16 v[80:83], v[210:213], v[234:237], v[80:83]
	v_mfma_f32_16x16x32_bf16 v[64:67], v[188:191], v[238:241], v[64:67]
	v_mfma_f32_16x16x32_bf16 v[64:67], v[210:213], v[242:245], v[64:67]
	s_setprio 0
	s_barrier
	s_mov_b32 m0, s47
	s_add_u32 s0, s4, 0xb0080
	s_addc_u32 s1, s5, 0
	ds_read_b128 v[214:217], v181 offset:49152
	ds_read_b128 v[218:221], v181 offset:50176
	ds_read_b128 v[222:225], v181 offset:51200
	ds_read_b128 v[226:229], v181 offset:52224
	ds_read_b128 v[230:233], v181 offset:53248
	ds_read_b128 v[234:237], v181 offset:54272
	ds_read_b128 v[238:241], v181 offset:55296
	ds_read_b128 v[242:245], v181 offset:56320
	s_add_u32 s98, s4, 0x80
	s_addc_u32 s99, s5, 0
	global_load_lds_dwordx4 v166, s[98:99]
	s_mov_b32 m0, s48
	s_nop 0
	global_load_lds_dwordx4 v162, s[98:99]
	s_mov_b32 m0, s51
	s_nop 0
	global_load_lds_dwordx4 v166, s[0:1]
	s_mov_b32 m0, s52
	s_nop 0
	global_load_lds_dwordx4 v162, s[0:1]
	s_mov_b32 m0, s49
	s_nop 0
	s_add_u32 s100, s6, 0x80
	s_addc_u32 s101, s7, 0
	global_load_lds_dwordx4 v168, s[100:101]
	s_mov_b32 m0, s50
	s_nop 0
	global_load_lds_dwordx4 v164, s[100:101]
	s_waitcnt vmcnt(8)
	s_waitcnt lgkmcnt(0)
	s_barrier
	s_setprio 1
	v_mfma_f32_16x16x32_bf16 v[60:63], v[128:131], v[214:217], v[60:63]
	v_mfma_f32_16x16x32_bf16 v[60:63], v[132:135], v[218:221], v[60:63]
	v_mfma_f32_16x16x32_bf16 v[44:47], v[128:131], v[222:225], v[44:47]
	v_mfma_f32_16x16x32_bf16 v[44:47], v[132:135], v[226:229], v[44:47]
	v_mfma_f32_16x16x32_bf16 v[28:31], v[128:131], v[230:233], v[28:31]
	v_mfma_f32_16x16x32_bf16 v[28:31], v[132:135], v[234:237], v[28:31]
	v_mfma_f32_16x16x32_bf16 v[12:15], v[128:131], v[238:241], v[12:15]
	v_mfma_f32_16x16x32_bf16 v[12:15], v[132:135], v[242:245], v[12:15]
	v_mfma_f32_16x16x32_bf16 v[56:59], v[136:139], v[214:217], v[56:59]
	v_mfma_f32_16x16x32_bf16 v[56:59], v[140:143], v[218:221], v[56:59]
	v_mfma_f32_16x16x32_bf16 v[40:43], v[136:139], v[222:225], v[40:43]
	v_mfma_f32_16x16x32_bf16 v[40:43], v[140:143], v[226:229], v[40:43]
	v_mfma_f32_16x16x32_bf16 v[24:27], v[136:139], v[230:233], v[24:27]
	v_mfma_f32_16x16x32_bf16 v[24:27], v[140:143], v[234:237], v[24:27]
	v_mfma_f32_16x16x32_bf16 v[8:11], v[136:139], v[238:241], v[8:11]
	v_mfma_f32_16x16x32_bf16 v[8:11], v[140:143], v[242:245], v[8:11]
	v_mfma_f32_16x16x32_bf16 v[52:55], v[174:177], v[214:217], v[52:55]
	v_mfma_f32_16x16x32_bf16 v[52:55], v[184:187], v[218:221], v[52:55]
	v_mfma_f32_16x16x32_bf16 v[36:39], v[174:177], v[222:225], v[36:39]
	v_mfma_f32_16x16x32_bf16 v[36:39], v[184:187], v[226:229], v[36:39]
	v_mfma_f32_16x16x32_bf16 v[20:23], v[174:177], v[230:233], v[20:23]
	v_mfma_f32_16x16x32_bf16 v[20:23], v[184:187], v[234:237], v[20:23]
	v_mfma_f32_16x16x32_bf16 v[4:7], v[174:177], v[238:241], v[4:7]
	v_mfma_f32_16x16x32_bf16 v[4:7], v[184:187], v[242:245], v[4:7]
	v_mfma_f32_16x16x32_bf16 v[48:51], v[188:191], v[214:217], v[48:51]
	v_mfma_f32_16x16x32_bf16 v[48:51], v[210:213], v[218:221], v[48:51]
	v_mfma_f32_16x16x32_bf16 v[32:35], v[188:191], v[222:225], v[32:35]
	v_mfma_f32_16x16x32_bf16 v[32:35], v[210:213], v[226:229], v[32:35]
	v_mfma_f32_16x16x32_bf16 v[16:19], v[188:191], v[230:233], v[16:19]
	v_mfma_f32_16x16x32_bf16 v[16:19], v[210:213], v[234:237], v[16:19]
	v_mfma_f32_16x16x32_bf16 v[0:3], v[188:191], v[238:241], v[0:3]
	v_mfma_f32_16x16x32_bf16 v[0:3], v[210:213], v[242:245], v[0:3]
	s_setprio 0
	s_barrier
	s_add_i32 s13, s13, 2
	s_add_u32 s10, s10, 0x100
	s_addc_u32 s11, s11, 0
	s_cmp_gt_u32 s13, 41
	s_mov_b64 s[0:1], s[2:3]
	s_cbranch_scc0 .LBB0_545
	s_and_b64 vcc, exec, s[22:23]
	s_cbranch_vccz .LBB0_548
	s_barrier

; #define PG8_STAGE(bufoff, gbase, voff) do { _Pragma("unroll") for (int _i = 0; _i < 2; ++_i) \
;         __builtin_amdgcn_global_load_lds((const unsigned*)((const char*)(gbase) + (voff)[_i]), (PG8_LAS unsigned*)(lds + (bufoff) + ldsw + _i * 8192), 16, 0, 0); } while (0)
; #define PG8_LDA(dst, b, h) do { _Pragma("unroll") for (int m = 0; m < 4; ++m) _Pragma("unroll") for (int k = 0; k < 2; ++k) dst[m][k] = *(const PG8_LAS bf16x8*)(lds + PG8_SA(b, h) + aoff + m * 2048 + k * 1024); } while (0)
; #define PG8_LDB(dst, b, h) do { _Pragma("unroll") for (int n = 0; n < 2; ++n) _Pragma("unroll") for (int k = 0; k < 2; ++k) dst[n][k] = *(const PG8_LAS bf16x8*)(lds + PG8_SB(b, h) + boff + n * 2048 + k * 1024); } while (0)
; #define PG8_MMA(ai, bj, At, Bt) do { __builtin_amdgcn_s_setprio(1); _Pragma("unroll") for (int m = 0; m < 4; ++m) _Pragma("unroll") for (int n = 0; n < 2; ++n) _Pragma("unroll") for (int k = 0; k < 2; ++k) \
;         acc[ai][bj][m][n] = __builtin_amdgcn_mfma_f32_16x16x32_bf16(Bt[n][k], At[m][k], acc[ai][bj][m][n], 0, 0, 0); __builtin_amdgcn_s_setprio(0); } while (0)
; #define PG8_WAIT_V(n) asm volatile("s_waitcnt vmcnt(" #n ")" ::: "memory")
; #define PG8_WAIT_L(n) asm volatile("s_waitcnt lgkmcnt(" #n ")" ::: "memory")
; template <class Epi, class Sched, bool ALIGN_EPI = false, bool SP2 = false>
; __device__ __forceinline__ void gemm_phase(PG8_LAS unsigned char* lds, const Gemm g, const Sched& S, const Epi& E) {
;     ...
;             const bool last = (t == nt - 2);
;             const char* a1 = cA + (size_t)(t + 1) * kstep;
;             const char* a2 = last ? nA : cA + (size_t)(t + 2) * kstep; const char* b2 = last ? nB : cB + (size_t)(t + 2) * kstep;
;             const char* a3 = a2 + kstep; const char* b3 = b2 + kstep;
;             if (last && has_next) S.a_ready(nxt);
;             if constexpr (SP2) {
;             PG8_LDB(B0, 0, 0); PG8_LDB(B1, 0, 1); PG8_SCHED; PG8_LDA(At, 0, 0); PG8_STAGE(PG8_SA(1, 1), a1 + hstep, voffA);
;             PG8_WAIT_V(8); PG8_WAIT_L(0); PG8_BAR; PG8_MMA(0, 0, At, B0); PG8_MMA(0, 1, At, B1); PG8_BAR; PG8_SCHED;
;             PG8_LDA(At, 0, 1); PG8_STAGE(PG8_SB(0, 0), b2, voffB); PG8_STAGE(PG8_SB(0, 1), b2 + hstep, voffB); PG8_STAGE(PG8_SA(0, 0), a2, voffA);
;             PG8_WAIT_V(8); PG8_WAIT_L(0); PG8_BAR; PG8_MMA(1, 0, At, B0); PG8_MMA(1, 1, At, B1); PG8_BAR; PG8_SCHED;
.Lsgi_peel:
	ds_read_b128 v[140:143], v254
	ds_read_b128 v[162:165], v254 offset:1024
	ds_read_b128 v[166:169], v254 offset:2048
	ds_read_b128 v[170:173], v254 offset:3072
	ds_read_b128 v[180:183], v254 offset:16384
	ds_read_b128 v[184:187], v254 offset:17408
	ds_read_b128 v[188:191], v254 offset:18432
	ds_read_b128 v[210:213], v254 offset:19456
	s_add_u32 s2, s0, 0xfffc0080
	s_addc_u32 s3, s1, -1
	s_cmp_eq_u32 s55, 12
	s_cselect_b32 s5, s13, s3
	s_cselect_b32 s4, s25, s2
	s_cselect_b32 s3, s23, s39
	s_cselect_b32 s2, s33, s38
	s_add_i32 m0, s6, 0xc000
	ds_read_b128 v[214:217], v178
	ds_read_b128 v[218:221], v178 offset:1024
	ds_read_b128 v[222:225], v178 offset:2048
	ds_read_b128 v[226:229], v178 offset:3072
	ds_read_b128 v[230:233], v178 offset:4096
	ds_read_b128 v[234:237], v178 offset:5120
	ds_read_b128 v[238:241], v178 offset:6144
	ds_read_b128 v[242:245], v178 offset:7168
	global_load_lds_dwordx4 v136, s[0:1]
	s_add_i32 m0, s6, 0xe000
	s_nop 0
	global_load_lds_dwordx4 v138, s[0:1]
	s_waitcnt vmcnt(8)
	s_waitcnt lgkmcnt(0)
	s_barrier
	s_setprio 1
	v_mfma_f32_16x16x32_bf16 v[124:127], v[140:143], v[214:217], 0
	v_mfma_f32_16x16x32_bf16 v[124:127], v[162:165], v[218:221], v[124:127]
	v_mfma_f32_16x16x32_bf16 v[108:111], v[140:143], v[222:225], 0
	v_mfma_f32_16x16x32_bf16 v[108:111], v[162:165], v[226:229], v[108:111]
	v_mfma_f32_16x16x32_bf16 v[92:95], v[140:143], v[230:233], 0
	v_mfma_f32_16x16x32_bf16 v[92:95], v[162:165], v[234:237], v[92:95]
	v_mfma_f32_16x16x32_bf16 v[76:79], v[140:143], v[238:241], 0
	v_mfma_f32_16x16x32_bf16 v[76:79], v[162:165], v[242:245], v[76:79]
	v_mfma_f32_16x16x32_bf16 v[120:123], v[166:169], v[214:217], 0
	v_mfma_f32_16x16x32_bf16 v[120:123], v[170:173], v[218:221], v[120:123]
	v_mfma_f32_16x16x32_bf16 v[104:107], v[166:169], v[222:225], 0
	v_mfma_f32_16x16x32_bf16 v[104:107], v[170:173], v[226:229], v[104:107]
	v_mfma_f32_16x16x32_bf16 v[88:91], v[166:169], v[230:233], 0
	v_mfma_f32_16x16x32_bf16 v[88:91], v[170:173], v[234:237], v[88:91]
	v_mfma_f32_16x16x32_bf16 v[72:75], v[166:169], v[238:241], 0
	v_mfma_f32_16x16x32_bf16 v[72:75], v[170:173], v[242:245], v[72:75]
	v_mfma_f32_16x16x32_bf16 v[116:119], v[180:183], v[214:217], 0
	v_mfma_f32_16x16x32_bf16 v[116:119], v[184:187], v[218:221], v[116:119]
	v_mfma_f32_16x16x32_bf16 v[100:103], v[180:183], v[222:225], 0
	v_mfma_f32_16x16x32_bf16 v[100:103], v[184:187], v[226:229], v[100:103]
	v_mfma_f32_16x16x32_bf16 v[84:87], v[180:183], v[230:233], 0
	v_mfma_f32_16x16x32_bf16 v[84:87], v[184:187], v[234:237], v[84:87]
	v_mfma_f32_16x16x32_bf16 v[68:71], v[180:183], v[238:241], 0
	v_mfma_f32_16x16x32_bf16 v[68:71], v[184:187], v[242:245], v[68:71]
	v_mfma_f32_16x16x32_bf16 v[112:115], v[188:191], v[214:217], 0
	v_mfma_f32_16x16x32_bf16 v[112:115], v[210:213], v[218:221], v[112:115]
	v_mfma_f32_16x16x32_bf16 v[96:99], v[188:191], v[222:225], 0
	v_mfma_f32_16x16x32_bf16 v[96:99], v[210:213], v[226:229], v[96:99]
	v_mfma_f32_16x16x32_bf16 v[80:83], v[188:191], v[230:233], 0
	v_mfma_f32_16x16x32_bf16 v[80:83], v[210:213], v[234:237], v[80:83]
	v_mfma_f32_16x16x32_bf16 v[64:67], v[188:191], v[238:241], 0
	v_mfma_f32_16x16x32_bf16 v[64:67], v[210:213], v[242:245], v[64:67]
	s_setprio 0
	s_barrier
	s_mov_b32 m0, s31
	s_add_u32 s56, s2, 0x40000
	s_addc_u32 s57, s3, 0
	ds_read_b128 v[214:217], v178 offset:16384
	ds_read_b128 v[218:221], v178 offset:17408
	ds_read_b128 v[222:225], v178 offset:18432
	ds_read_b128 v[226:229], v178 offset:19456
	ds_read_b128 v[230:233], v178 offset:20480
	ds_read_b128 v[234:237], v178 offset:21504
	ds_read_b128 v[238:241], v178 offset:22528
	ds_read_b128 v[242:245], v178 offset:23552
	global_load_lds_dwordx4 v132, s[2:3]
	s_mov_b32 m0, s34
	s_nop 0
	global_load_lds_dwordx4 v128, s[2:3]
	s_mov_b32 m0, s35
	s_nop 0
	global_load_lds_dwordx4 v132, s[56:57]
	s_mov_b32 m0, s40
	s_nop 0
	global_load_lds_dwordx4 v128, s[56:57]
	s_mov_b32 m0, s6
	s_nop 0
	global_load_lds_dwordx4 v134, s[4:5]
	s_mov_b32 m0, s41
	s_nop 0
	global_load_lds_dwordx4 v130, s[4:5]
	s_waitcnt vmcnt(8)
	s_waitcnt lgkmcnt(0)
	s_barrier
	s_setprio 1
	v_mfma_f32_16x16x32_bf16 v[60:63], v[140:143], v[214:217], 0
	v_mfma_f32_16x16x32_bf16 v[60:63], v[162:165], v[218:221], v[60:63]
	v_mfma_f32_16x16x32_bf16 v[44:47], v[140:143], v[222:225], 0
	v_mfma_f32_16x16x32_bf16 v[44:47], v[162:165], v[226:229], v[44:47]
	v_mfma_f32_16x16x32_bf16 v[28:31], v[140:143], v[230:233], 0
	v_mfma_f32_16x16x32_bf16 v[28:31], v[162:165], v[234:237], v[28:31]
	v_mfma_f32_16x16x32_bf16 v[12:15], v[140:143], v[238:241], 0
	v_mfma_f32_16x16x32_bf16 v[12:15], v[162:165], v[242:245], v[12:15]
	v_mfma_f32_16x16x32_bf16 v[56:59], v[166:169], v[214:217], 0
	v_mfma_f32_16x16x32_bf16 v[56:59], v[170:173], v[218:221], v[56:59]
	v_mfma_f32_16x16x32_bf16 v[40:43], v[166:169], v[222:225], 0
	v_mfma_f32_16x16x32_bf16 v[40:43], v[170:173], v[226:229], v[40:43]
	v_mfma_f32_16x16x32_bf16 v[24:27], v[166:169], v[230:233], 0
	v_mfma_f32_16x16x32_bf16 v[24:27], v[170:173], v[234:237], v[24:27]
	v_mfma_f32_16x16x32_bf16 v[8:11], v[166:169], v[238:241], 0
	v_mfma_f32_16x16x32_bf16 v[8:11], v[170:173], v[242:245], v[8:11]
	v_mfma_f32_16x16x32_bf16 v[52:55], v[180:183], v[214:217], 0
	v_mfma_f32_16x16x32_bf16 v[52:55], v[184:187], v[218:221], v[52:55]
	v_mfma_f32_16x16x32_bf16 v[36:39], v[180:183], v[222:225], 0
	v_mfma_f32_16x16x32_bf16 v[36:39], v[184:187], v[226:229], v[36:39]
	v_mfma_f32_16x16x32_bf16 v[20:23], v[180:183], v[230:233], 0
	v_mfma_f32_16x16x32_bf16 v[20:23], v[184:187], v[234:237], v[20:23]
	v_mfma_f32_16x16x32_bf16 v[4:7], v[180:183], v[238:241], 0
	v_mfma_f32_16x16x32_bf16 v[4:7], v[184:187], v[242:245], v[4:7]
	v_mfma_f32_16x16x32_bf16 v[48:51], v[188:191], v[214:217], 0
	v_mfma_f32_16x16x32_bf16 v[48:51], v[210:213], v[218:221], v[48:51]
	v_mfma_f32_16x16x32_bf16 v[32:35], v[188:191], v[222:225], 0
	v_mfma_f32_16x16x32_bf16 v[32:35], v[210:213], v[226:229], v[32:35]
	v_mfma_f32_16x16x32_bf16 v[16:19], v[188:191], v[230:233], 0
	v_mfma_f32_16x16x32_bf16 v[16:19], v[210:213], v[234:237], v[16:19]
	v_mfma_f32_16x16x32_bf16 v[0:3], v[188:191], v[238:241], 0
	v_mfma_f32_16x16x32_bf16 v[0:3], v[210:213], v[242:245], v[0:3]
	s_setprio 0
	s_barrier
; #define PG8_STAGE(bufoff, gbase, voff) do { _Pragma("unroll") for (int _i = 0; _i < 2; ++_i) \
;         __builtin_amdgcn_global_load_lds((const unsigned*)((const char*)(gbase) + (voff)[_i]), (PG8_LAS unsigned*)(lds + (bufoff) + ldsw + _i * 8192), 16, 0, 0); } while (0)
; #define PG8_LDA(dst, b, h) do { _Pragma("unroll") for (int m = 0; m < 4; ++m) _Pragma("unroll") for (int k = 0; k < 2; ++k) dst[m][k] = *(const PG8_LAS bf16x8*)(lds + PG8_SA(b, h) + aoff + m * 2048 + k * 1024); } while (0)
; #define PG8_LDB(dst, b, h) do { _Pragma("unroll") for (int n = 0; n < 2; ++n) _Pragma("unroll") for (int k = 0; k < 2; ++k) dst[n][k] = *(const PG8_LAS bf16x8*)(lds + PG8_SB(b, h) + boff + n * 2048 + k * 1024); } while (0)
; #define PG8_MMA(ai, bj, At, Bt) do { __builtin_amdgcn_s_setprio(1); _Pragma("unroll") for (int m = 0; m < 4; ++m) _Pragma("unroll") for (int n = 0; n < 2; ++n) _Pragma("unroll") for (int k = 0; k < 2; ++k) \
;         acc[ai][bj][m][n] = __builtin_amdgcn_mfma_f32_16x16x32_bf16(Bt[n][k], At[m][k], acc[ai][bj][m][n], 0, 0, 0); __builtin_amdgcn_s_setprio(0); } while (0)
; #define PG8_WAIT_V(n) asm volatile("s_waitcnt vmcnt(" #n ")" ::: "memory")
; #define PG8_WAIT_L(n) asm volatile("s_waitcnt lgkmcnt(" #n ")" ::: "memory")
; #define PG8_BAR __builtin_amdgcn_s_barrier()
; #define PG8_SCHED __builtin_amdgcn_sched_barrier(0)
; template <class Epi, class Sched, bool ALIGN_EPI = false, bool SP2 = false>
; __device__ __forceinline__ void gemm_phase(PG8_LAS unsigned char* lds, const Gemm g, const Sched& S, const Epi& E) {
;     ...
;             PG8_LDB(B0, 1, 0); PG8_LDB(B1, 1, 1); PG8_SCHED; PG8_LDA(At, 1, 0); PG8_STAGE(PG8_SA(0, 1), a2 + hstep, voffA);
;             PG8_WAIT_V(8); PG8_WAIT_L(0); PG8_BAR; PG8_MMA(0, 0, At, B0); PG8_MMA(0, 1, At, B1); PG8_BAR; PG8_SCHED;
;             PG8_LDA(At, 1, 1); PG8_STAGE(PG8_SB(1, 0), b3, voffB); PG8_STAGE(PG8_SB(1, 1), b3 + hstep, voffB); PG8_STAGE(PG8_SA(1, 0), a3, voffA);
;             PG8_WAIT_V(8); PG8_WAIT_L(0); PG8_BAR; PG8_MMA(1, 0, At, B0); PG8_MMA(1, 1, At, B1); PG8_BAR; PG8_SCHED;
	ds_read_b128 v[140:143], v254 offset:32768
	ds_read_b128 v[162:165], v254 offset:33792
	ds_read_b128 v[166:169], v254 offset:34816
	ds_read_b128 v[170:173], v254 offset:35840
	ds_read_b128 v[180:183], v254 offset:49152
	ds_read_b128 v[184:187], v254 offset:50176
	ds_read_b128 v[188:191], v254 offset:51200
	ds_read_b128 v[210:213], v254 offset:52224
	s_add_u32 s4, s4, 0x40000
	s_addc_u32 s5, s5, 0
	s_mov_b32 m0, s42
	ds_read_b128 v[214:217], v178 offset:32768
	ds_read_b128 v[218:221], v178 offset:33792
	ds_read_b128 v[222:225], v178 offset:34816
	ds_read_b128 v[226:229], v178 offset:35840
	ds_read_b128 v[230:233], v178 offset:36864
	ds_read_b128 v[234:237], v178 offset:37888
	ds_read_b128 v[238:241], v178 offset:38912
	ds_read_b128 v[242:245], v178 offset:39936
	global_load_lds_dwordx4 v134, s[4:5]
	s_mov_b32 m0, s43
	s_nop 0
	global_load_lds_dwordx4 v130, s[4:5]
	s_waitcnt vmcnt(8)
	s_waitcnt lgkmcnt(0)
	s_barrier
	s_setprio 1
	v_mfma_f32_16x16x32_bf16 v[124:127], v[140:143], v[214:217], v[124:127]
	v_mfma_f32_16x16x32_bf16 v[124:127], v[162:165], v[218:221], v[124:127]
	v_mfma_f32_16x16x32_bf16 v[108:111], v[140:143], v[222:225], v[108:111]
	v_mfma_f32_16x16x32_bf16 v[108:111], v[162:165], v[226:229], v[108:111]
	v_mfma_f32_16x16x32_bf16 v[92:95], v[140:143], v[230:233], v[92:95]
	v_mfma_f32_16x16x32_bf16 v[92:95], v[162:165], v[234:237], v[92:95]
	v_mfma_f32_16x16x32_bf16 v[76:79], v[140:143], v[238:241], v[76:79]
	v_mfma_f32_16x16x32_bf16 v[76:79], v[162:165], v[242:245], v[76:79]
	v_mfma_f32_16x16x32_bf16 v[120:123], v[166:169], v[214:217], v[120:123]
	v_mfma_f32_16x16x32_bf16 v[120:123], v[170:173], v[218:221], v[120:123]
	v_mfma_f32_16x16x32_bf16 v[104:107], v[166:169], v[222:225], v[104:107]
	v_mfma_f32_16x16x32_bf16 v[104:107], v[170:173], v[226:229], v[104:107]
	v_mfma_f32_16x16x32_bf16 v[88:91], v[166:169], v[230:233], v[88:91]
	v_mfma_f32_16x16x32_bf16 v[88:91], v[170:173], v[234:237], v[88:91]
	v_mfma_f32_16x16x32_bf16 v[72:75], v[166:169], v[238:241], v[72:75]
	v_mfma_f32_16x16x32_bf16 v[72:75], v[170:173], v[242:245], v[72:75]
	v_mfma_f32_16x16x32_bf16 v[116:119], v[180:183], v[214:217], v[116:119]
	v_mfma_f32_16x16x32_bf16 v[116:119], v[184:187], v[218:221], v[116:119]
	v_mfma_f32_16x16x32_bf16 v[100:103], v[180:183], v[222:225], v[100:103]
	v_mfma_f32_16x16x32_bf16 v[100:103], v[184:187], v[226:229], v[100:103]
	v_mfma_f32_16x16x32_bf16 v[84:87], v[180:183], v[230:233], v[84:87]
	v_mfma_f32_16x16x32_bf16 v[84:87], v[184:187], v[234:237], v[84:87]
	v_mfma_f32_16x16x32_bf16 v[68:71], v[180:183], v[238:241], v[68:71]
	v_mfma_f32_16x16x32_bf16 v[68:71], v[184:187], v[242:245], v[68:71]
	v_mfma_f32_16x16x32_bf16 v[112:115], v[188:191], v[214:217], v[112:115]
	v_mfma_f32_16x16x32_bf16 v[112:115], v[210:213], v[218:221], v[112:115]
	v_mfma_f32_16x16x32_bf16 v[96:99], v[188:191], v[222:225], v[96:99]
	v_mfma_f32_16x16x32_bf16 v[96:99], v[210:213], v[226:229], v[96:99]
	v_mfma_f32_16x16x32_bf16 v[80:83], v[188:191], v[230:233], v[80:83]
	v_mfma_f32_16x16x32_bf16 v[80:83], v[210:213], v[234:237], v[80:83]
	v_mfma_f32_16x16x32_bf16 v[64:67], v[188:191], v[238:241], v[64:67]
	v_mfma_f32_16x16x32_bf16 v[64:67], v[210:213], v[242:245], v[64:67]
	s_setprio 0
	s_barrier
	s_mov_b32 m0, s48
	s_add_u32 s2, s2, 0x40080
	s_addc_u32 s3, s3, 0
	ds_read_b128 v[214:217], v178 offset:49152
	ds_read_b128 v[218:221], v178 offset:50176
	ds_read_b128 v[222:225], v178 offset:51200
	ds_read_b128 v[226:229], v178 offset:52224
	ds_read_b128 v[230:233], v178 offset:53248
	ds_read_b128 v[234:237], v178 offset:54272
	ds_read_b128 v[238:241], v178 offset:55296
	ds_read_b128 v[242:245], v178 offset:56320
	s_add_u32 s98, s2, 0xfffc0000
	s_addc_u32 s99, s3, -1
	global_load_lds_dwordx4 v132, s[98:99]
	s_mov_b32 m0, s49
	s_nop 0
	global_load_lds_dwordx4 v128, s[98:99]
	s_mov_b32 m0, s52
	s_nop 0
	global_load_lds_dwordx4 v132, s[2:3]
	s_mov_b32 m0, s53
	s_nop 0
	global_load_lds_dwordx4 v128, s[2:3]
	s_mov_b32 m0, s50
	s_nop 0
	s_add_u32 s100, s4, 0xfffc0080
	s_addc_u32 s101, s5, -1
	global_load_lds_dwordx4 v134, s[100:101]
	s_mov_b32 m0, s51
	s_nop 0
	global_load_lds_dwordx4 v130, s[100:101]
	s_waitcnt vmcnt(8)
	s_waitcnt lgkmcnt(0)
	s_barrier
	s_setprio 1
	v_mfma_f32_16x16x32_bf16 v[60:63], v[140:143], v[214:217], v[60:63]
	v_mfma_f32_16x16x32_bf16 v[60:63], v[162:165], v[218:221], v[60:63]
	v_mfma_f32_16x16x32_bf16 v[44:47], v[140:143], v[222:225], v[44:47]
	v_mfma_f32_16x16x32_bf16 v[44:47], v[162:165], v[226:229], v[44:47]
	v_mfma_f32_16x16x32_bf16 v[28:31], v[140:143], v[230:233], v[28:31]
	v_mfma_f32_16x16x32_bf16 v[28:31], v[162:165], v[234:237], v[28:31]
	v_mfma_f32_16x16x32_bf16 v[12:15], v[140:143], v[238:241], v[12:15]
	v_mfma_f32_16x16x32_bf16 v[12:15], v[162:165], v[242:245], v[12:15]
	v_mfma_f32_16x16x32_bf16 v[56:59], v[166:169], v[214:217], v[56:59]
	v_mfma_f32_16x16x32_bf16 v[56:59], v[170:173], v[218:221], v[56:59]
	v_mfma_f32_16x16x32_bf16 v[40:43], v[166:169], v[222:225], v[40:43]
	v_mfma_f32_16x16x32_bf16 v[40:43], v[170:173], v[226:229], v[40:43]
	v_mfma_f32_16x16x32_bf16 v[24:27], v[166:169], v[230:233], v[24:27]
	v_mfma_f32_16x16x32_bf16 v[24:27], v[170:173], v[234:237], v[24:27]
	v_mfma_f32_16x16x32_bf16 v[8:11], v[166:169], v[238:241], v[8:11]
	v_mfma_f32_16x16x32_bf16 v[8:11], v[170:173], v[242:245], v[8:11]
	v_mfma_f32_16x16x32_bf16 v[52:55], v[180:183], v[214:217], v[52:55]
	v_mfma_f32_16x16x32_bf16 v[52:55], v[184:187], v[218:221], v[52:55]
	v_mfma_f32_16x16x32_bf16 v[36:39], v[180:183], v[222:225], v[36:39]
	v_mfma_f32_16x16x32_bf16 v[36:39], v[184:187], v[226:229], v[36:39]
	v_mfma_f32_16x16x32_bf16 v[20:23], v[180:183], v[230:233], v[20:23]
	v_mfma_f32_16x16x32_bf16 v[20:23], v[184:187], v[234:237], v[20:23]
	v_mfma_f32_16x16x32_bf16 v[4:7], v[180:183], v[238:241], v[4:7]
	v_mfma_f32_16x16x32_bf16 v[4:7], v[184:187], v[242:245], v[4:7]
	v_mfma_f32_16x16x32_bf16 v[48:51], v[188:191], v[214:217], v[48:51]
	v_mfma_f32_16x16x32_bf16 v[48:51], v[210:213], v[218:221], v[48:51]
	v_mfma_f32_16x16x32_bf16 v[32:35], v[188:191], v[222:225], v[32:35]
	v_mfma_f32_16x16x32_bf16 v[32:35], v[210:213], v[226:229], v[32:35]
	v_mfma_f32_16x16x32_bf16 v[16:19], v[188:191], v[230:233], v[16:19]
	v_mfma_f32_16x16x32_bf16 v[16:19], v[210:213], v[234:237], v[16:19]
	v_mfma_f32_16x16x32_bf16 v[0:3], v[188:191], v[238:241], v[0:3]
	v_mfma_f32_16x16x32_bf16 v[0:3], v[210:213], v[242:245], v[0:3]
	s_setprio 0
	s_barrier
	s_add_i32 s55, s55, 2
	s_add_u32 s0, s0, 0x100
	s_addc_u32 s1, s1, 0
	s_add_u32 s38, s38, 0x100
	s_addc_u32 s39, s39, 0
	s_cmp_gt_u32 s55, 13
; #define PG8_STAGE(bufoff, gbase, voff) do { _Pragma("unroll") for (int _i = 0; _i < 2; ++_i) \
;         __builtin_amdgcn_global_load_lds((const unsigned*)((const char*)(gbase) + (voff)[_i]), (PG8_LAS unsigned*)(lds + (bufoff) + ldsw + _i * 8192), 16, 0, 0); } while (0)
; #define PG8_LDA(dst, b, h) do { _Pragma("unroll") for (int m = 0; m < 4; ++m) _Pragma("unroll") for (int k = 0; k < 2; ++k) dst[m][k] = *(const PG8_LAS bf16x8*)(lds + PG8_SA(b, h) + aoff + m * 2048 + k * 1024); } while (0)
; #define PG8_LDB(dst, b, h) do { _Pragma("unroll") for (int n = 0; n < 2; ++n) _Pragma("unroll") for (int k = 0; k < 2; ++k) dst[n][k] = *(const PG8_LAS bf16x8*)(lds + PG8_SB(b, h) + boff + n * 2048 + k * 1024); } while (0)
; #define PG8_MMA(ai, bj, At, Bt) do { __builtin_amdgcn_s_setprio(1); _Pragma("unroll") for (int m = 0; m < 4; ++m) _Pragma("unroll") for (int n = 0; n < 2; ++n) _Pragma("unroll") for (int k = 0; k < 2; ++k) \
;         acc[ai][bj][m][n] = __builtin_amdgcn_mfma_f32_16x16x32_bf16(Bt[n][k], At[m][k], acc[ai][bj][m][n], 0, 0, 0); __builtin_amdgcn_s_setprio(0); } while (0)
; #define PG8_WAIT_V(n) asm volatile("s_waitcnt vmcnt(" #n ")" ::: "memory")
; #define PG8_BAR __builtin_amdgcn_s_barrier()
; template <class Epi, class Sched, bool ALIGN_EPI = false, bool SP2 = false>
; __device__ __forceinline__ void gemm_phase(PG8_LAS unsigned char* lds, const Gemm g, const Sched& S, const Epi& E) {
;     ...
;         for (int t = 0; t < nt; t += 2) {
;             const bool last = (t == nt - 2);
;             const char* a1 = cA + (size_t)(t + 1) * kstep;
;             const char* a2 = last ? nA : cA + (size_t)(t + 2) * kstep; const char* b2 = last ? nB : cB + (size_t)(t + 2) * kstep;
;             const char* a3 = a2 + kstep; const char* b3 = b2 + kstep;
;             if (last && has_next) S.a_ready(nxt);
;             if constexpr (SP2) {
;             PG8_LDB(B0, 0, 0); PG8_LDB(B1, 0, 1); PG8_SCHED; PG8_LDA(At, 0, 0); PG8_STAGE(PG8_SA(1, 1), a1 + hstep, voffA);
;             PG8_WAIT_V(8); PG8_WAIT_L(0); PG8_BAR; PG8_MMA(0, 0, At, B0); PG8_MMA(0, 1, At, B1); PG8_BAR; PG8_SCHED;
;             PG8_LDA(At, 0, 1); PG8_STAGE(PG8_SB(0, 0), b2, voffB); PG8_STAGE(PG8_SB(0, 1), b2 + hstep, voffB); PG8_STAGE(PG8_SA(0, 0), a2, voffA);
;             PG8_WAIT_V(8); PG8_WAIT_L(0); PG8_BAR; PG8_MMA(1, 0, At, B0); PG8_MMA(1, 1, At, B1); PG8_BAR; PG8_SCHED;
.LBB0_749:
	ds_read_b128 v[140:143], v254
	ds_read_b128 v[162:165], v254 offset:1024
	ds_read_b128 v[166:169], v254 offset:2048
	ds_read_b128 v[170:173], v254 offset:3072
	ds_read_b128 v[180:183], v254 offset:16384
	ds_read_b128 v[184:187], v254 offset:17408
	ds_read_b128 v[188:191], v254 offset:18432
	ds_read_b128 v[210:213], v254 offset:19456
	s_add_u32 s2, s0, 0xfffc0080
	s_addc_u32 s3, s1, -1
	s_cmp_eq_u32 s55, 12
	s_cselect_b32 s5, s13, s3
	s_cselect_b32 s4, s25, s2
	s_cselect_b32 s3, s23, s39
	s_cselect_b32 s2, s33, s38
	s_add_i32 m0, s6, 0xc000
	ds_read_b128 v[214:217], v178
	ds_read_b128 v[218:221], v178 offset:1024
	ds_read_b128 v[222:225], v178 offset:2048
	ds_read_b128 v[226:229], v178 offset:3072
	ds_read_b128 v[230:233], v178 offset:4096
	ds_read_b128 v[234:237], v178 offset:5120
	ds_read_b128 v[238:241], v178 offset:6144
	ds_read_b128 v[242:245], v178 offset:7168
	global_load_lds_dwordx4 v136, s[0:1]
	s_add_i32 m0, s6, 0xe000
	s_nop 0
	global_load_lds_dwordx4 v138, s[0:1]
	s_waitcnt vmcnt(8)
	s_waitcnt lgkmcnt(0)
	s_barrier
	s_setprio 1
	v_mfma_f32_16x16x32_bf16 v[124:127], v[140:143], v[214:217], v[124:127]
	v_mfma_f32_16x16x32_bf16 v[124:127], v[162:165], v[218:221], v[124:127]
	v_mfma_f32_16x16x32_bf16 v[108:111], v[140:143], v[222:225], v[108:111]
	v_mfma_f32_16x16x32_bf16 v[108:111], v[162:165], v[226:229], v[108:111]
	v_mfma_f32_16x16x32_bf16 v[92:95], v[140:143], v[230:233], v[92:95]
	v_mfma_f32_16x16x32_bf16 v[92:95], v[162:165], v[234:237], v[92:95]
	v_mfma_f32_16x16x32_bf16 v[76:79], v[140:143], v[238:241], v[76:79]
	v_mfma_f32_16x16x32_bf16 v[76:79], v[162:165], v[242:245], v[76:79]
	v_mfma_f32_16x16x32_bf16 v[120:123], v[166:169], v[214:217], v[120:123]
	v_mfma_f32_16x16x32_bf16 v[120:123], v[170:173], v[218:221], v[120:123]
	v_mfma_f32_16x16x32_bf16 v[104:107], v[166:169], v[222:225], v[104:107]
	v_mfma_f32_16x16x32_bf16 v[104:107], v[170:173], v[226:229], v[104:107]
	v_mfma_f32_16x16x32_bf16 v[88:91], v[166:169], v[230:233], v[88:91]
	v_mfma_f32_16x16x32_bf16 v[88:91], v[170:173], v[234:237], v[88:91]
	v_mfma_f32_16x16x32_bf16 v[72:75], v[166:169], v[238:241], v[72:75]
	v_mfma_f32_16x16x32_bf16 v[72:75], v[170:173], v[242:245], v[72:75]
	v_mfma_f32_16x16x32_bf16 v[116:119], v[180:183], v[214:217], v[116:119]
	v_mfma_f32_16x16x32_bf16 v[116:119], v[184:187], v[218:221], v[116:119]
	v_mfma_f32_16x16x32_bf16 v[100:103], v[180:183], v[222:225], v[100:103]
	v_mfma_f32_16x16x32_bf16 v[100:103], v[184:187], v[226:229], v[100:103]
	v_mfma_f32_16x16x32_bf16 v[84:87], v[180:183], v[230:233], v[84:87]
	v_mfma_f32_16x16x32_bf16 v[84:87], v[184:187], v[234:237], v[84:87]
	v_mfma_f32_16x16x32_bf16 v[68:71], v[180:183], v[238:241], v[68:71]
	v_mfma_f32_16x16x32_bf16 v[68:71], v[184:187], v[242:245], v[68:71]
	v_mfma_f32_16x16x32_bf16 v[112:115], v[188:191], v[214:217], v[112:115]
	v_mfma_f32_16x16x32_bf16 v[112:115], v[210:213], v[218:221], v[112:115]
	v_mfma_f32_16x16x32_bf16 v[96:99], v[188:191], v[222:225], v[96:99]
	v_mfma_f32_16x16x32_bf16 v[96:99], v[210:213], v[226:229], v[96:99]
	v_mfma_f32_16x16x32_bf16 v[80:83], v[188:191], v[230:233], v[80:83]
	v_mfma_f32_16x16x32_bf16 v[80:83], v[210:213], v[234:237], v[80:83]
	v_mfma_f32_16x16x32_bf16 v[64:67], v[188:191], v[238:241], v[64:67]
	v_mfma_f32_16x16x32_bf16 v[64:67], v[210:213], v[242:245], v[64:67]
	s_setprio 0
	s_barrier
	s_mov_b32 m0, s31
	s_add_u32 s56, s2, 0x40000
	s_addc_u32 s57, s3, 0
	ds_read_b128 v[214:217], v178 offset:16384
	ds_read_b128 v[218:221], v178 offset:17408
	ds_read_b128 v[222:225], v178 offset:18432
	ds_read_b128 v[226:229], v178 offset:19456
	ds_read_b128 v[230:233], v178 offset:20480
	ds_read_b128 v[234:237], v178 offset:21504
	ds_read_b128 v[238:241], v178 offset:22528
	ds_read_b128 v[242:245], v178 offset:23552
	global_load_lds_dwordx4 v132, s[2:3]
	s_mov_b32 m0, s34
	s_nop 0
	global_load_lds_dwordx4 v128, s[2:3]
	s_mov_b32 m0, s35
	s_nop 0
	global_load_lds_dwordx4 v132, s[56:57]
	s_mov_b32 m0, s40
	s_nop 0
	global_load_lds_dwordx4 v128, s[56:57]
	s_mov_b32 m0, s6
	s_nop 0
	global_load_lds_dwordx4 v134, s[4:5]
	s_mov_b32 m0, s41
	s_nop 0
	global_load_lds_dwordx4 v130, s[4:5]
	s_waitcnt vmcnt(8)
	s_waitcnt lgkmcnt(0)
	s_barrier
	s_setprio 1
	v_mfma_f32_16x16x32_bf16 v[60:63], v[140:143], v[214:217], v[60:63]
	v_mfma_f32_16x16x32_bf16 v[60:63], v[162:165], v[218:221], v[60:63]
	v_mfma_f32_16x16x32_bf16 v[44:47], v[140:143], v[222:225], v[44:47]
	v_mfma_f32_16x16x32_bf16 v[44:47], v[162:165], v[226:229], v[44:47]
	v_mfma_f32_16x16x32_bf16 v[28:31], v[140:143], v[230:233], v[28:31]
	v_mfma_f32_16x16x32_bf16 v[28:31], v[162:165], v[234:237], v[28:31]
	v_mfma_f32_16x16x32_bf16 v[12:15], v[140:143], v[238:241], v[12:15]
	v_mfma_f32_16x16x32_bf16 v[12:15], v[162:165], v[242:245], v[12:15]
	v_mfma_f32_16x16x32_bf16 v[56:59], v[166:169], v[214:217], v[56:59]
	v_mfma_f32_16x16x32_bf16 v[56:59], v[170:173], v[218:221], v[56:59]
	v_mfma_f32_16x16x32_bf16 v[40:43], v[166:169], v[222:225], v[40:43]
	v_mfma_f32_16x16x32_bf16 v[40:43], v[170:173], v[226:229], v[40:43]
	v_mfma_f32_16x16x32_bf16 v[24:27], v[166:169], v[230:233], v[24:27]
	v_mfma_f32_16x16x32_bf16 v[24:27], v[170:173], v[234:237], v[24:27]
	v_mfma_f32_16x16x32_bf16 v[8:11], v[166:169], v[238:241], v[8:11]
	v_mfma_f32_16x16x32_bf16 v[8:11], v[170:173], v[242:245], v[8:11]
	v_mfma_f32_16x16x32_bf16 v[52:55], v[180:183], v[214:217], v[52:55]
	v_mfma_f32_16x16x32_bf16 v[52:55], v[184:187], v[218:221], v[52:55]
	v_mfma_f32_16x16x32_bf16 v[36:39], v[180:183], v[222:225], v[36:39]
	v_mfma_f32_16x16x32_bf16 v[36:39], v[184:187], v[226:229], v[36:39]
	v_mfma_f32_16x16x32_bf16 v[20:23], v[180:183], v[230:233], v[20:23]
	v_mfma_f32_16x16x32_bf16 v[20:23], v[184:187], v[234:237], v[20:23]
	v_mfma_f32_16x16x32_bf16 v[4:7], v[180:183], v[238:241], v[4:7]
	v_mfma_f32_16x16x32_bf16 v[4:7], v[184:187], v[242:245], v[4:7]
	v_mfma_f32_16x16x32_bf16 v[48:51], v[188:191], v[214:217], v[48:51]
	v_mfma_f32_16x16x32_bf16 v[48:51], v[210:213], v[218:221], v[48:51]
	v_mfma_f32_16x16x32_bf16 v[32:35], v[188:191], v[222:225], v[32:35]
	v_mfma_f32_16x16x32_bf16 v[32:35], v[210:213], v[226:229], v[32:35]
	v_mfma_f32_16x16x32_bf16 v[16:19], v[188:191], v[230:233], v[16:19]
	v_mfma_f32_16x16x32_bf16 v[16:19], v[210:213], v[234:237], v[16:19]
	v_mfma_f32_16x16x32_bf16 v[0:3], v[188:191], v[238:241], v[0:3]
	v_mfma_f32_16x16x32_bf16 v[0:3], v[210:213], v[242:245], v[0:3]
	s_setprio 0
	s_barrier
; #define PG8_STAGE(bufoff, gbase, voff) do { _Pragma("unroll") for (int _i = 0; _i < 2; ++_i) \
;         __builtin_amdgcn_global_load_lds((const unsigned*)((const char*)(gbase) + (voff)[_i]), (PG8_LAS unsigned*)(lds + (bufoff) + ldsw + _i * 8192), 16, 0, 0); } while (0)
; #define PG8_LDA(dst, b, h) do { _Pragma("unroll") for (int m = 0; m < 4; ++m) _Pragma("unroll") for (int k = 0; k < 2; ++k) dst[m][k] = *(const PG8_LAS bf16x8*)(lds + PG8_SA(b, h) + aoff + m * 2048 + k * 1024); } while (0)
; #define PG8_LDB(dst, b, h) do { _Pragma("unroll") for (int n = 0; n < 2; ++n) _Pragma("unroll") for (int k = 0; k < 2; ++k) dst[n][k] = *(const PG8_LAS bf16x8*)(lds + PG8_SB(b, h) + boff + n * 2048 + k * 1024); } while (0)
; #define PG8_MMA(ai, bj, At, Bt) do { __builtin_amdgcn_s_setprio(1); _Pragma("unroll") for (int m = 0; m < 4; ++m) _Pragma("unroll") for (int n = 0; n < 2; ++n) _Pragma("unroll") for (int k = 0; k < 2; ++k) \
;         acc[ai][bj][m][n] = __builtin_amdgcn_mfma_f32_16x16x32_bf16(Bt[n][k], At[m][k], acc[ai][bj][m][n], 0, 0, 0); __builtin_amdgcn_s_setprio(0); } while (0)
; #define PG8_WAIT_V(n) asm volatile("s_waitcnt vmcnt(" #n ")" ::: "memory")
; #define PG8_WAIT_L(n) asm volatile("s_waitcnt lgkmcnt(" #n ")" ::: "memory")
; #define PG8_BAR __builtin_amdgcn_s_barrier()
; #define PG8_SCHED __builtin_amdgcn_sched_barrier(0)
; template <class Epi, class Sched, bool ALIGN_EPI = false, bool SP2 = false>
; __device__ __forceinline__ void gemm_phase(PG8_LAS unsigned char* lds, const Gemm g, const Sched& S, const Epi& E) {
;     ...
;         for (int t = 0; t < nt; t += 2) {
;             const bool last = (t == nt - 2);
;             const char* a1 = cA + (size_t)(t + 1) * kstep;
;             const char* a2 = last ? nA : cA + (size_t)(t + 2) * kstep; const char* b2 = last ? nB : cB + (size_t)(t + 2) * kstep;
;     ...
;             PG8_LDB(B0, 1, 0); PG8_LDB(B1, 1, 1); PG8_SCHED; PG8_LDA(At, 1, 0); PG8_STAGE(PG8_SA(0, 1), a2 + hstep, voffA);
;             PG8_WAIT_V(8); PG8_WAIT_L(0); PG8_BAR; PG8_MMA(0, 0, At, B0); PG8_MMA(0, 1, At, B1); PG8_BAR; PG8_SCHED;
;             PG8_LDA(At, 1, 1); PG8_STAGE(PG8_SB(1, 0), b3, voffB); PG8_STAGE(PG8_SB(1, 1), b3 + hstep, voffB); PG8_STAGE(PG8_SA(1, 0), a3, voffA);
;             PG8_WAIT_V(8); PG8_WAIT_L(0); PG8_BAR; PG8_MMA(1, 0, At, B0); PG8_MMA(1, 1, At, B1); PG8_BAR; PG8_SCHED;
	ds_read_b128 v[140:143], v254 offset:32768
	ds_read_b128 v[162:165], v254 offset:33792
	ds_read_b128 v[166:169], v254 offset:34816
	ds_read_b128 v[170:173], v254 offset:35840
	ds_read_b128 v[180:183], v254 offset:49152
	ds_read_b128 v[184:187], v254 offset:50176
	ds_read_b128 v[188:191], v254 offset:51200
	ds_read_b128 v[210:213], v254 offset:52224
	s_add_u32 s4, s4, 0x40000
	s_addc_u32 s5, s5, 0
	s_mov_b32 m0, s42
	ds_read_b128 v[214:217], v178 offset:32768
	ds_read_b128 v[218:221], v178 offset:33792
	ds_read_b128 v[222:225], v178 offset:34816
	ds_read_b128 v[226:229], v178 offset:35840
	ds_read_b128 v[230:233], v178 offset:36864
	ds_read_b128 v[234:237], v178 offset:37888
	ds_read_b128 v[238:241], v178 offset:38912
	ds_read_b128 v[242:245], v178 offset:39936
	global_load_lds_dwordx4 v134, s[4:5]
	s_mov_b32 m0, s43
	s_nop 0
	global_load_lds_dwordx4 v130, s[4:5]
	s_waitcnt vmcnt(8)
	s_waitcnt lgkmcnt(0)
	s_barrier
	s_setprio 1
	v_mfma_f32_16x16x32_bf16 v[124:127], v[140:143], v[214:217], v[124:127]
	v_mfma_f32_16x16x32_bf16 v[124:127], v[162:165], v[218:221], v[124:127]
	v_mfma_f32_16x16x32_bf16 v[108:111], v[140:143], v[222:225], v[108:111]
	v_mfma_f32_16x16x32_bf16 v[108:111], v[162:165], v[226:229], v[108:111]
	v_mfma_f32_16x16x32_bf16 v[92:95], v[140:143], v[230:233], v[92:95]
	v_mfma_f32_16x16x32_bf16 v[92:95], v[162:165], v[234:237], v[92:95]
	v_mfma_f32_16x16x32_bf16 v[76:79], v[140:143], v[238:241], v[76:79]
	v_mfma_f32_16x16x32_bf16 v[76:79], v[162:165], v[242:245], v[76:79]
	v_mfma_f32_16x16x32_bf16 v[120:123], v[166:169], v[214:217], v[120:123]
	v_mfma_f32_16x16x32_bf16 v[120:123], v[170:173], v[218:221], v[120:123]
	v_mfma_f32_16x16x32_bf16 v[104:107], v[166:169], v[222:225], v[104:107]
	v_mfma_f32_16x16x32_bf16 v[104:107], v[170:173], v[226:229], v[104:107]
	v_mfma_f32_16x16x32_bf16 v[88:91], v[166:169], v[230:233], v[88:91]
	v_mfma_f32_16x16x32_bf16 v[88:91], v[170:173], v[234:237], v[88:91]
	v_mfma_f32_16x16x32_bf16 v[72:75], v[166:169], v[238:241], v[72:75]
	v_mfma_f32_16x16x32_bf16 v[72:75], v[170:173], v[242:245], v[72:75]
	v_mfma_f32_16x16x32_bf16 v[116:119], v[180:183], v[214:217], v[116:119]
	v_mfma_f32_16x16x32_bf16 v[116:119], v[184:187], v[218:221], v[116:119]
	v_mfma_f32_16x16x32_bf16 v[100:103], v[180:183], v[222:225], v[100:103]
	v_mfma_f32_16x16x32_bf16 v[100:103], v[184:187], v[226:229], v[100:103]
	v_mfma_f32_16x16x32_bf16 v[84:87], v[180:183], v[230:233], v[84:87]
	v_mfma_f32_16x16x32_bf16 v[84:87], v[184:187], v[234:237], v[84:87]
	v_mfma_f32_16x16x32_bf16 v[68:71], v[180:183], v[238:241], v[68:71]
	v_mfma_f32_16x16x32_bf16 v[68:71], v[184:187], v[242:245], v[68:71]
	v_mfma_f32_16x16x32_bf16 v[112:115], v[188:191], v[214:217], v[112:115]
	v_mfma_f32_16x16x32_bf16 v[112:115], v[210:213], v[218:221], v[112:115]
	v_mfma_f32_16x16x32_bf16 v[96:99], v[188:191], v[222:225], v[96:99]
	v_mfma_f32_16x16x32_bf16 v[96:99], v[210:213], v[226:229], v[96:99]
	v_mfma_f32_16x16x32_bf16 v[80:83], v[188:191], v[230:233], v[80:83]
	v_mfma_f32_16x16x32_bf16 v[80:83], v[210:213], v[234:237], v[80:83]
	v_mfma_f32_16x16x32_bf16 v[64:67], v[188:191], v[238:241], v[64:67]
	v_mfma_f32_16x16x32_bf16 v[64:67], v[210:213], v[242:245], v[64:67]
	s_setprio 0
	s_barrier
	s_mov_b32 m0, s48
	s_add_u32 s2, s2, 0x40080
	s_addc_u32 s3, s3, 0
	ds_read_b128 v[214:217], v178 offset:49152
	ds_read_b128 v[218:221], v178 offset:50176
	ds_read_b128 v[222:225], v178 offset:51200
	ds_read_b128 v[226:229], v178 offset:52224
	ds_read_b128 v[230:233], v178 offset:53248
	ds_read_b128 v[234:237], v178 offset:54272
	ds_read_b128 v[238:241], v178 offset:55296
	ds_read_b128 v[242:245], v178 offset:56320
	s_add_u32 s98, s2, 0xfffc0000
	s_addc_u32 s99, s3, -1
	global_load_lds_dwordx4 v132, s[98:99]
	s_mov_b32 m0, s49
	s_nop 0
	global_load_lds_dwordx4 v128, s[98:99]
	s_mov_b32 m0, s52
	s_nop 0
	global_load_lds_dwordx4 v132, s[2:3]
	s_mov_b32 m0, s53
	s_nop 0
	global_load_lds_dwordx4 v128, s[2:3]
	s_mov_b32 m0, s50
	s_nop 0
	s_add_u32 s100, s4, 0xfffc0080
	s_addc_u32 s101, s5, -1
	global_load_lds_dwordx4 v134, s[100:101]
	s_mov_b32 m0, s51
	s_nop 0
	global_load_lds_dwordx4 v130, s[100:101]
	s_waitcnt vmcnt(8)
	s_waitcnt lgkmcnt(0)
	s_barrier
	s_setprio 1
	v_mfma_f32_16x16x32_bf16 v[60:63], v[140:143], v[214:217], v[60:63]
	v_mfma_f32_16x16x32_bf16 v[60:63], v[162:165], v[218:221], v[60:63]
	v_mfma_f32_16x16x32_bf16 v[44:47], v[140:143], v[222:225], v[44:47]
	v_mfma_f32_16x16x32_bf16 v[44:47], v[162:165], v[226:229], v[44:47]
	v_mfma_f32_16x16x32_bf16 v[28:31], v[140:143], v[230:233], v[28:31]
	v_mfma_f32_16x16x32_bf16 v[28:31], v[162:165], v[234:237], v[28:31]
	v_mfma_f32_16x16x32_bf16 v[12:15], v[140:143], v[238:241], v[12:15]
	v_mfma_f32_16x16x32_bf16 v[12:15], v[162:165], v[242:245], v[12:15]
	v_mfma_f32_16x16x32_bf16 v[56:59], v[166:169], v[214:217], v[56:59]
	v_mfma_f32_16x16x32_bf16 v[56:59], v[170:173], v[218:221], v[56:59]
	v_mfma_f32_16x16x32_bf16 v[40:43], v[166:169], v[222:225], v[40:43]
	v_mfma_f32_16x16x32_bf16 v[40:43], v[170:173], v[226:229], v[40:43]
	v_mfma_f32_16x16x32_bf16 v[24:27], v[166:169], v[230:233], v[24:27]
	v_mfma_f32_16x16x32_bf16 v[24:27], v[170:173], v[234:237], v[24:27]
	v_mfma_f32_16x16x32_bf16 v[8:11], v[166:169], v[238:241], v[8:11]
	v_mfma_f32_16x16x32_bf16 v[8:11], v[170:173], v[242:245], v[8:11]
	v_mfma_f32_16x16x32_bf16 v[52:55], v[180:183], v[214:217], v[52:55]
	v_mfma_f32_16x16x32_bf16 v[52:55], v[184:187], v[218:221], v[52:55]
	v_mfma_f32_16x16x32_bf16 v[36:39], v[180:183], v[222:225], v[36:39]
	v_mfma_f32_16x16x32_bf16 v[36:39], v[184:187], v[226:229], v[36:39]
	v_mfma_f32_16x16x32_bf16 v[20:23], v[180:183], v[230:233], v[20:23]
	v_mfma_f32_16x16x32_bf16 v[20:23], v[184:187], v[234:237], v[20:23]
	v_mfma_f32_16x16x32_bf16 v[4:7], v[180:183], v[238:241], v[4:7]
	v_mfma_f32_16x16x32_bf16 v[4:7], v[184:187], v[242:245], v[4:7]
	v_mfma_f32_16x16x32_bf16 v[48:51], v[188:191], v[214:217], v[48:51]
	v_mfma_f32_16x16x32_bf16 v[48:51], v[210:213], v[218:221], v[48:51]
	v_mfma_f32_16x16x32_bf16 v[32:35], v[188:191], v[222:225], v[32:35]
	v_mfma_f32_16x16x32_bf16 v[32:35], v[210:213], v[226:229], v[32:35]
	v_mfma_f32_16x16x32_bf16 v[16:19], v[188:191], v[230:233], v[16:19]
	v_mfma_f32_16x16x32_bf16 v[16:19], v[210:213], v[234:237], v[16:19]
	v_mfma_f32_16x16x32_bf16 v[0:3], v[188:191], v[238:241], v[0:3]
	v_mfma_f32_16x16x32_bf16 v[0:3], v[210:213], v[242:245], v[0:3]
	s_setprio 0
	s_barrier
	s_add_i32 s55, s55, 2
	s_add_u32 s0, s0, 0x100
	s_addc_u32 s1, s1, 0
	s_add_u32 s38, s38, 0x100
	s_addc_u32 s39, s39, 0
	s_cmp_gt_u32 s55, 13
	s_cbranch_scc0 .LBB0_749
	s_and_b64 vcc, exec, s[18:19]
	s_cbranch_vccz .LBB0_752
	s_barrier

; #define PG8_STAGE(bufoff, gbase, voff) do { _Pragma("unroll") for (int _i = 0; _i < 2; ++_i) \
;         __builtin_amdgcn_global_load_lds((const unsigned*)((const char*)(gbase) + (voff)[_i]), (PG8_LAS unsigned*)(lds + (bufoff) + ldsw + _i * 8192), 16, 0, 0); } while (0)
; #define PG8_LDA(dst, b, h) do { _Pragma("unroll") for (int m = 0; m < 4; ++m) _Pragma("unroll") for (int k = 0; k < 2; ++k) dst[m][k] = *(const PG8_LAS bf16x8*)(lds + PG8_SA(b, h) + aoff + m * 2048 + k * 1024); } while (0)
; #define PG8_LDB(dst, b, h) do { _Pragma("unroll") for (int n = 0; n < 2; ++n) _Pragma("unroll") for (int k = 0; k < 2; ++k) dst[n][k] = *(const PG8_LAS bf16x8*)(lds + PG8_SB(b, h) + boff + n * 2048 + k * 1024); } while (0)
; #define PG8_MMA(ai, bj, At, Bt) do { __builtin_amdgcn_s_setprio(1); _Pragma("unroll") for (int m = 0; m < 4; ++m) _Pragma("unroll") for (int n = 0; n < 2; ++n) _Pragma("unroll") for (int k = 0; k < 2; ++k) \
;         acc[ai][bj][m][n] = __builtin_amdgcn_mfma_f32_16x16x32_bf16(Bt[n][k], At[m][k], acc[ai][bj][m][n], 0, 0, 0); __builtin_amdgcn_s_setprio(0); } while (0)
; #define PG8_WAIT_V(n) asm volatile("s_waitcnt vmcnt(" #n ")" ::: "memory")
; #define PG8_WAIT_L(n) asm volatile("s_waitcnt lgkmcnt(" #n ")" ::: "memory")
; template <class Epi, class Sched, bool ALIGN_EPI = false, bool SP2 = false>
; __device__ __forceinline__ void gemm_phase(PG8_LAS unsigned char* lds, const Gemm g, const Sched& S, const Epi& E) {
;     ...
;             const bool last = (t == nt - 2);
;             const char* a1 = cA + (size_t)(t + 1) * kstep;
;             const char* a2 = last ? nA : cA + (size_t)(t + 2) * kstep; const char* b2 = last ? nB : cB + (size_t)(t + 2) * kstep;
;             const char* a3 = a2 + kstep; const char* b3 = b2 + kstep;
;             if (last && has_next) S.a_ready(nxt);
;             if constexpr (SP2) {
;             PG8_LDB(B0, 0, 0); PG8_LDB(B1, 0, 1); PG8_SCHED; PG8_LDA(At, 0, 0); PG8_STAGE(PG8_SA(1, 1), a1 + hstep, voffA);
;             PG8_WAIT_V(8); PG8_WAIT_L(0); PG8_BAR; PG8_MMA(0, 0, At, B0); PG8_MMA(0, 1, At, B1); PG8_BAR; PG8_SCHED;
;             PG8_LDA(At, 0, 1); PG8_STAGE(PG8_SB(0, 0), b2, voffB); PG8_STAGE(PG8_SB(0, 1), b2 + hstep, voffB); PG8_STAGE(PG8_SA(0, 0), a2, voffA);
;             PG8_WAIT_V(8); PG8_WAIT_L(0); PG8_BAR; PG8_MMA(1, 0, At, B0); PG8_MMA(1, 1, At, B1); PG8_BAR; PG8_SCHED;
.Labi_peel:
	s_waitcnt lgkmcnt(0)
	ds_read_b128 v[140:143], v254
	ds_read_b128 v[162:165], v254 offset:1024
	ds_read_b128 v[166:169], v254 offset:2048
	ds_read_b128 v[176:179], v254 offset:3072
	ds_read_b128 v[180:183], v254 offset:16384
	ds_read_b128 v[184:187], v254 offset:17408
	ds_read_b128 v[188:191], v254 offset:18432
	ds_read_b128 v[210:213], v254 offset:19456
	s_add_u32 s2, s0, 0xfffc0080
	s_addc_u32 s3, s1, -1
	s_cmp_eq_u32 s52, 12
	s_cselect_b32 s5, s17, s3
	s_cselect_b32 s4, s48, s2
	s_cselect_b32 s3, s15, s51
	s_cselect_b32 s2, s49, s50
	s_add_i32 m0, s6, 0xc000
	ds_read_b128 v[214:217], v173
	ds_read_b128 v[218:221], v173 offset:1024
	ds_read_b128 v[222:225], v173 offset:2048
	ds_read_b128 v[226:229], v173 offset:3072
	ds_read_b128 v[230:233], v173 offset:4096
	ds_read_b128 v[234:237], v173 offset:5120
	ds_read_b128 v[238:241], v173 offset:6144
	ds_read_b128 v[242:245], v173 offset:7168
	global_load_lds_dwordx4 v136, s[0:1]
	s_add_i32 m0, s6, 0xe000
	s_nop 0
	global_load_lds_dwordx4 v138, s[0:1]
	s_waitcnt vmcnt(8)
	s_waitcnt lgkmcnt(0)
	s_barrier
	s_setprio 1
	v_mfma_f32_16x16x32_bf16 v[124:127], v[140:143], v[214:217], 0
	v_mfma_f32_16x16x32_bf16 v[124:127], v[162:165], v[218:221], v[124:127]
	v_mfma_f32_16x16x32_bf16 v[112:115], v[140:143], v[222:225], 0
	v_mfma_f32_16x16x32_bf16 v[112:115], v[162:165], v[226:229], v[112:115]
	v_mfma_f32_16x16x32_bf16 v[96:99], v[140:143], v[230:233], 0
	v_mfma_f32_16x16x32_bf16 v[96:99], v[162:165], v[234:237], v[96:99]
	v_mfma_f32_16x16x32_bf16 v[80:83], v[140:143], v[238:241], 0
	v_mfma_f32_16x16x32_bf16 v[80:83], v[162:165], v[242:245], v[80:83]
	v_mfma_f32_16x16x32_bf16 v[120:123], v[166:169], v[214:217], 0
	v_mfma_f32_16x16x32_bf16 v[120:123], v[176:179], v[218:221], v[120:123]
	v_mfma_f32_16x16x32_bf16 v[104:107], v[166:169], v[222:225], 0
	v_mfma_f32_16x16x32_bf16 v[104:107], v[176:179], v[226:229], v[104:107]
	v_mfma_f32_16x16x32_bf16 v[88:91], v[166:169], v[230:233], 0
	v_mfma_f32_16x16x32_bf16 v[88:91], v[176:179], v[234:237], v[88:91]
	v_mfma_f32_16x16x32_bf16 v[72:75], v[166:169], v[238:241], 0
	v_mfma_f32_16x16x32_bf16 v[72:75], v[176:179], v[242:245], v[72:75]
	v_mfma_f32_16x16x32_bf16 v[116:119], v[180:183], v[214:217], 0
	v_mfma_f32_16x16x32_bf16 v[116:119], v[184:187], v[218:221], v[116:119]
	v_mfma_f32_16x16x32_bf16 v[100:103], v[180:183], v[222:225], 0
	v_mfma_f32_16x16x32_bf16 v[100:103], v[184:187], v[226:229], v[100:103]
	v_mfma_f32_16x16x32_bf16 v[84:87], v[180:183], v[230:233], 0
	v_mfma_f32_16x16x32_bf16 v[84:87], v[184:187], v[234:237], v[84:87]
	v_mfma_f32_16x16x32_bf16 v[68:71], v[180:183], v[238:241], 0
	v_mfma_f32_16x16x32_bf16 v[68:71], v[184:187], v[242:245], v[68:71]
	v_mfma_f32_16x16x32_bf16 v[108:111], v[188:191], v[214:217], 0
	v_mfma_f32_16x16x32_bf16 v[108:111], v[210:213], v[218:221], v[108:111]
	v_mfma_f32_16x16x32_bf16 v[92:95], v[188:191], v[222:225], 0
	v_mfma_f32_16x16x32_bf16 v[92:95], v[210:213], v[226:229], v[92:95]
	v_mfma_f32_16x16x32_bf16 v[76:79], v[188:191], v[230:233], 0
	v_mfma_f32_16x16x32_bf16 v[76:79], v[210:213], v[234:237], v[76:79]
	v_mfma_f32_16x16x32_bf16 v[64:67], v[188:191], v[238:241], 0
	v_mfma_f32_16x16x32_bf16 v[64:67], v[210:213], v[242:245], v[64:67]
	s_setprio 0
	s_barrier
	s_mov_b32 m0, s27
	s_add_u32 s54, s2, 0x40000
	s_addc_u32 s55, s3, 0
	ds_read_b128 v[214:217], v173 offset:16384
	ds_read_b128 v[218:221], v173 offset:17408
	ds_read_b128 v[222:225], v173 offset:18432
	ds_read_b128 v[226:229], v173 offset:19456
	ds_read_b128 v[230:233], v173 offset:20480
	ds_read_b128 v[234:237], v173 offset:21504
	ds_read_b128 v[238:241], v173 offset:22528
	ds_read_b128 v[242:245], v173 offset:23552
	global_load_lds_dwordx4 v132, s[2:3]
	s_mov_b32 m0, s28
	s_nop 0
	global_load_lds_dwordx4 v128, s[2:3]
	s_mov_b32 m0, s29
	s_nop 0
	global_load_lds_dwordx4 v132, s[54:55]
	s_mov_b32 m0, s30
	s_nop 0
	global_load_lds_dwordx4 v128, s[54:55]
	s_mov_b32 m0, s6
	s_nop 0
	global_load_lds_dwordx4 v134, s[4:5]
	s_mov_b32 m0, s31
	s_nop 0
	global_load_lds_dwordx4 v130, s[4:5]
	s_waitcnt vmcnt(8)
	s_waitcnt lgkmcnt(0)
	s_barrier
	s_setprio 1
	v_mfma_f32_16x16x32_bf16 v[60:63], v[140:143], v[214:217], 0
	v_mfma_f32_16x16x32_bf16 v[60:63], v[162:165], v[218:221], v[60:63]
	v_mfma_f32_16x16x32_bf16 v[48:51], v[140:143], v[222:225], 0
	v_mfma_f32_16x16x32_bf16 v[48:51], v[162:165], v[226:229], v[48:51]
	v_mfma_f32_16x16x32_bf16 v[32:35], v[140:143], v[230:233], 0
	v_mfma_f32_16x16x32_bf16 v[32:35], v[162:165], v[234:237], v[32:35]
	v_mfma_f32_16x16x32_bf16 v[16:19], v[140:143], v[238:241], 0
	v_mfma_f32_16x16x32_bf16 v[16:19], v[162:165], v[242:245], v[16:19]
	v_mfma_f32_16x16x32_bf16 v[56:59], v[166:169], v[214:217], 0
	v_mfma_f32_16x16x32_bf16 v[56:59], v[176:179], v[218:221], v[56:59]
	v_mfma_f32_16x16x32_bf16 v[40:43], v[166:169], v[222:225], 0
	v_mfma_f32_16x16x32_bf16 v[40:43], v[176:179], v[226:229], v[40:43]
	v_mfma_f32_16x16x32_bf16 v[24:27], v[166:169], v[230:233], 0
	v_mfma_f32_16x16x32_bf16 v[24:27], v[176:179], v[234:237], v[24:27]
	v_mfma_f32_16x16x32_bf16 v[8:11], v[166:169], v[238:241], 0
	v_mfma_f32_16x16x32_bf16 v[8:11], v[176:179], v[242:245], v[8:11]
	v_mfma_f32_16x16x32_bf16 v[52:55], v[180:183], v[214:217], 0
	v_mfma_f32_16x16x32_bf16 v[52:55], v[184:187], v[218:221], v[52:55]
	v_mfma_f32_16x16x32_bf16 v[36:39], v[180:183], v[222:225], 0
	v_mfma_f32_16x16x32_bf16 v[36:39], v[184:187], v[226:229], v[36:39]
	v_mfma_f32_16x16x32_bf16 v[20:23], v[180:183], v[230:233], 0
	v_mfma_f32_16x16x32_bf16 v[20:23], v[184:187], v[234:237], v[20:23]
	v_mfma_f32_16x16x32_bf16 v[4:7], v[180:183], v[238:241], 0
	v_mfma_f32_16x16x32_bf16 v[4:7], v[184:187], v[242:245], v[4:7]
	v_mfma_f32_16x16x32_bf16 v[44:47], v[188:191], v[214:217], 0
	v_mfma_f32_16x16x32_bf16 v[44:47], v[210:213], v[218:221], v[44:47]
	v_mfma_f32_16x16x32_bf16 v[28:31], v[188:191], v[222:225], 0
	v_mfma_f32_16x16x32_bf16 v[28:31], v[210:213], v[226:229], v[28:31]
	v_mfma_f32_16x16x32_bf16 v[12:15], v[188:191], v[230:233], 0
	v_mfma_f32_16x16x32_bf16 v[12:15], v[210:213], v[234:237], v[12:15]
	v_mfma_f32_16x16x32_bf16 v[0:3], v[188:191], v[238:241], 0
	v_mfma_f32_16x16x32_bf16 v[0:3], v[210:213], v[242:245], v[0:3]
	s_setprio 0
	s_barrier
; #define PG8_STAGE(bufoff, gbase, voff) do { _Pragma("unroll") for (int _i = 0; _i < 2; ++_i) \
;         __builtin_amdgcn_global_load_lds((const unsigned*)((const char*)(gbase) + (voff)[_i]), (PG8_LAS unsigned*)(lds + (bufoff) + ldsw + _i * 8192), 16, 0, 0); } while (0)
; #define PG8_LDA(dst, b, h) do { _Pragma("unroll") for (int m = 0; m < 4; ++m) _Pragma("unroll") for (int k = 0; k < 2; ++k) dst[m][k] = *(const PG8_LAS bf16x8*)(lds + PG8_SA(b, h) + aoff + m * 2048 + k * 1024); } while (0)
; #define PG8_LDB(dst, b, h) do { _Pragma("unroll") for (int n = 0; n < 2; ++n) _Pragma("unroll") for (int k = 0; k < 2; ++k) dst[n][k] = *(const PG8_LAS bf16x8*)(lds + PG8_SB(b, h) + boff + n * 2048 + k * 1024); } while (0)
; #define PG8_MMA(ai, bj, At, Bt) do { __builtin_amdgcn_s_setprio(1); _Pragma("unroll") for (int m = 0; m < 4; ++m) _Pragma("unroll") for (int n = 0; n < 2; ++n) _Pragma("unroll") for (int k = 0; k < 2; ++k) \
;         acc[ai][bj][m][n] = __builtin_amdgcn_mfma_f32_16x16x32_bf16(Bt[n][k], At[m][k], acc[ai][bj][m][n], 0, 0, 0); __builtin_amdgcn_s_setprio(0); } while (0)
; #define PG8_WAIT_V(n) asm volatile("s_waitcnt vmcnt(" #n ")" ::: "memory")
; #define PG8_WAIT_L(n) asm volatile("s_waitcnt lgkmcnt(" #n ")" ::: "memory")
; #define PG8_BAR __builtin_amdgcn_s_barrier()
; #define PG8_SCHED __builtin_amdgcn_sched_barrier(0)
; template <class Epi, class Sched, bool ALIGN_EPI = false, bool SP2 = false>
; __device__ __forceinline__ void gemm_phase(PG8_LAS unsigned char* lds, const Gemm g, const Sched& S, const Epi& E) {
;     ...
;             PG8_LDB(B0, 1, 0); PG8_LDB(B1, 1, 1); PG8_SCHED; PG8_LDA(At, 1, 0); PG8_STAGE(PG8_SA(0, 1), a2 + hstep, voffA);
;             PG8_WAIT_V(8); PG8_WAIT_L(0); PG8_BAR; PG8_MMA(0, 0, At, B0); PG8_MMA(0, 1, At, B1); PG8_BAR; PG8_SCHED;
;             PG8_LDA(At, 1, 1); PG8_STAGE(PG8_SB(1, 0), b3, voffB); PG8_STAGE(PG8_SB(1, 1), b3 + hstep, voffB); PG8_STAGE(PG8_SA(1, 0), a3, voffA);
;             PG8_WAIT_V(8); PG8_WAIT_L(0); PG8_BAR; PG8_MMA(1, 0, At, B0); PG8_MMA(1, 1, At, B1); PG8_BAR; PG8_SCHED;
	ds_read_b128 v[140:143], v254 offset:32768
	ds_read_b128 v[162:165], v254 offset:33792
	ds_read_b128 v[166:169], v254 offset:34816
	ds_read_b128 v[176:179], v254 offset:35840
	ds_read_b128 v[180:183], v254 offset:49152
	ds_read_b128 v[184:187], v254 offset:50176
	ds_read_b128 v[188:191], v254 offset:51200
	ds_read_b128 v[210:213], v254 offset:52224
	s_add_u32 s4, s4, 0x40000
	s_addc_u32 s5, s5, 0
	s_mov_b32 m0, s33
	ds_read_b128 v[214:217], v173 offset:32768
	ds_read_b128 v[218:221], v173 offset:33792
	ds_read_b128 v[222:225], v173 offset:34816
	ds_read_b128 v[226:229], v173 offset:35840
	ds_read_b128 v[230:233], v173 offset:36864
	ds_read_b128 v[234:237], v173 offset:37888
	ds_read_b128 v[238:241], v173 offset:38912
	ds_read_b128 v[242:245], v173 offset:39936
	global_load_lds_dwordx4 v134, s[4:5]
	s_mov_b32 m0, s34
	s_nop 0
	global_load_lds_dwordx4 v130, s[4:5]
	s_waitcnt vmcnt(8)
	s_waitcnt lgkmcnt(0)
	s_barrier
	s_setprio 1
	v_mfma_f32_16x16x32_bf16 v[124:127], v[140:143], v[214:217], v[124:127]
	v_mfma_f32_16x16x32_bf16 v[124:127], v[162:165], v[218:221], v[124:127]
	v_mfma_f32_16x16x32_bf16 v[112:115], v[140:143], v[222:225], v[112:115]
	v_mfma_f32_16x16x32_bf16 v[112:115], v[162:165], v[226:229], v[112:115]
	v_mfma_f32_16x16x32_bf16 v[96:99], v[140:143], v[230:233], v[96:99]
	v_mfma_f32_16x16x32_bf16 v[96:99], v[162:165], v[234:237], v[96:99]
	v_mfma_f32_16x16x32_bf16 v[80:83], v[140:143], v[238:241], v[80:83]
	v_mfma_f32_16x16x32_bf16 v[80:83], v[162:165], v[242:245], v[80:83]
	v_mfma_f32_16x16x32_bf16 v[120:123], v[166:169], v[214:217], v[120:123]
	v_mfma_f32_16x16x32_bf16 v[120:123], v[176:179], v[218:221], v[120:123]
	v_mfma_f32_16x16x32_bf16 v[104:107], v[166:169], v[222:225], v[104:107]
	v_mfma_f32_16x16x32_bf16 v[104:107], v[176:179], v[226:229], v[104:107]
	v_mfma_f32_16x16x32_bf16 v[88:91], v[166:169], v[230:233], v[88:91]
	v_mfma_f32_16x16x32_bf16 v[88:91], v[176:179], v[234:237], v[88:91]
	v_mfma_f32_16x16x32_bf16 v[72:75], v[166:169], v[238:241], v[72:75]
	v_mfma_f32_16x16x32_bf16 v[72:75], v[176:179], v[242:245], v[72:75]
	v_mfma_f32_16x16x32_bf16 v[116:119], v[180:183], v[214:217], v[116:119]
	v_mfma_f32_16x16x32_bf16 v[116:119], v[184:187], v[218:221], v[116:119]
	v_mfma_f32_16x16x32_bf16 v[100:103], v[180:183], v[222:225], v[100:103]
	v_mfma_f32_16x16x32_bf16 v[100:103], v[184:187], v[226:229], v[100:103]
	v_mfma_f32_16x16x32_bf16 v[84:87], v[180:183], v[230:233], v[84:87]
	v_mfma_f32_16x16x32_bf16 v[84:87], v[184:187], v[234:237], v[84:87]
	v_mfma_f32_16x16x32_bf16 v[68:71], v[180:183], v[238:241], v[68:71]
	v_mfma_f32_16x16x32_bf16 v[68:71], v[184:187], v[242:245], v[68:71]
	v_mfma_f32_16x16x32_bf16 v[108:111], v[188:191], v[214:217], v[108:111]
	v_mfma_f32_16x16x32_bf16 v[108:111], v[210:213], v[218:221], v[108:111]
	v_mfma_f32_16x16x32_bf16 v[92:95], v[188:191], v[222:225], v[92:95]
	v_mfma_f32_16x16x32_bf16 v[92:95], v[210:213], v[226:229], v[92:95]
	v_mfma_f32_16x16x32_bf16 v[76:79], v[188:191], v[230:233], v[76:79]
	v_mfma_f32_16x16x32_bf16 v[76:79], v[210:213], v[234:237], v[76:79]
	v_mfma_f32_16x16x32_bf16 v[64:67], v[188:191], v[238:241], v[64:67]
	v_mfma_f32_16x16x32_bf16 v[64:67], v[210:213], v[242:245], v[64:67]
	s_setprio 0
	s_barrier
	s_mov_b32 m0, s37
	s_add_u32 s2, s2, 0x40080
	s_addc_u32 s3, s3, 0
	ds_read_b128 v[214:217], v173 offset:49152
	ds_read_b128 v[218:221], v173 offset:50176
	ds_read_b128 v[222:225], v173 offset:51200
	ds_read_b128 v[226:229], v173 offset:52224
	ds_read_b128 v[230:233], v173 offset:53248
	ds_read_b128 v[234:237], v173 offset:54272
	ds_read_b128 v[238:241], v173 offset:55296
	ds_read_b128 v[242:245], v173 offset:56320
	s_add_u32 s98, s2, 0xfffc0000
	s_addc_u32 s99, s3, -1
	global_load_lds_dwordx4 v132, s[98:99]
	s_mov_b32 m0, s38
	s_nop 0
	global_load_lds_dwordx4 v128, s[98:99]
	s_mov_b32 m0, s41
	s_nop 0
	global_load_lds_dwordx4 v132, s[2:3]
	s_mov_b32 m0, s42
	s_nop 0
	global_load_lds_dwordx4 v128, s[2:3]
	s_mov_b32 m0, s39
	s_nop 0
	s_add_u32 s100, s4, 0xfffc0080
	s_addc_u32 s101, s5, -1
	global_load_lds_dwordx4 v134, s[100:101]
	s_mov_b32 m0, s40
	s_nop 0
	global_load_lds_dwordx4 v130, s[100:101]
	s_waitcnt vmcnt(8)
	s_waitcnt lgkmcnt(0)
	s_barrier
	s_setprio 1
	v_mfma_f32_16x16x32_bf16 v[60:63], v[140:143], v[214:217], v[60:63]
	v_mfma_f32_16x16x32_bf16 v[60:63], v[162:165], v[218:221], v[60:63]
	v_mfma_f32_16x16x32_bf16 v[48:51], v[140:143], v[222:225], v[48:51]
	v_mfma_f32_16x16x32_bf16 v[48:51], v[162:165], v[226:229], v[48:51]
	v_mfma_f32_16x16x32_bf16 v[32:35], v[140:143], v[230:233], v[32:35]
	v_mfma_f32_16x16x32_bf16 v[32:35], v[162:165], v[234:237], v[32:35]
	v_mfma_f32_16x16x32_bf16 v[16:19], v[140:143], v[238:241], v[16:19]
	v_mfma_f32_16x16x32_bf16 v[16:19], v[162:165], v[242:245], v[16:19]
	v_mfma_f32_16x16x32_bf16 v[56:59], v[166:169], v[214:217], v[56:59]
	v_mfma_f32_16x16x32_bf16 v[56:59], v[176:179], v[218:221], v[56:59]
	v_mfma_f32_16x16x32_bf16 v[40:43], v[166:169], v[222:225], v[40:43]
	v_mfma_f32_16x16x32_bf16 v[40:43], v[176:179], v[226:229], v[40:43]
	v_mfma_f32_16x16x32_bf16 v[24:27], v[166:169], v[230:233], v[24:27]
	v_mfma_f32_16x16x32_bf16 v[24:27], v[176:179], v[234:237], v[24:27]
	v_mfma_f32_16x16x32_bf16 v[8:11], v[166:169], v[238:241], v[8:11]
	v_mfma_f32_16x16x32_bf16 v[8:11], v[176:179], v[242:245], v[8:11]
	v_mfma_f32_16x16x32_bf16 v[52:55], v[180:183], v[214:217], v[52:55]
	v_mfma_f32_16x16x32_bf16 v[52:55], v[184:187], v[218:221], v[52:55]
	v_mfma_f32_16x16x32_bf16 v[36:39], v[180:183], v[222:225], v[36:39]
	v_mfma_f32_16x16x32_bf16 v[36:39], v[184:187], v[226:229], v[36:39]
	v_mfma_f32_16x16x32_bf16 v[20:23], v[180:183], v[230:233], v[20:23]
	v_mfma_f32_16x16x32_bf16 v[20:23], v[184:187], v[234:237], v[20:23]
	v_mfma_f32_16x16x32_bf16 v[4:7], v[180:183], v[238:241], v[4:7]
	v_mfma_f32_16x16x32_bf16 v[4:7], v[184:187], v[242:245], v[4:7]
	v_mfma_f32_16x16x32_bf16 v[44:47], v[188:191], v[214:217], v[44:47]
	v_mfma_f32_16x16x32_bf16 v[44:47], v[210:213], v[218:221], v[44:47]
	v_mfma_f32_16x16x32_bf16 v[28:31], v[188:191], v[222:225], v[28:31]
	v_mfma_f32_16x16x32_bf16 v[28:31], v[210:213], v[226:229], v[28:31]
	v_mfma_f32_16x16x32_bf16 v[12:15], v[188:191], v[230:233], v[12:15]
	v_mfma_f32_16x16x32_bf16 v[12:15], v[210:213], v[234:237], v[12:15]
	v_mfma_f32_16x16x32_bf16 v[0:3], v[188:191], v[238:241], v[0:3]
	v_mfma_f32_16x16x32_bf16 v[0:3], v[210:213], v[242:245], v[0:3]
	s_setprio 0
	s_barrier
	s_add_i32 s52, s52, 2
	s_add_u32 s0, s0, 0x100
	s_addc_u32 s1, s1, 0
	s_add_u32 s50, s50, 0x100
	s_addc_u32 s51, s51, 0
	s_cmp_gt_u32 s52, 13
; #define PG8_STAGE(bufoff, gbase, voff) do { _Pragma("unroll") for (int _i = 0; _i < 2; ++_i) \
;         __builtin_amdgcn_global_load_lds((const unsigned*)((const char*)(gbase) + (voff)[_i]), (PG8_LAS unsigned*)(lds + (bufoff) + ldsw + _i * 8192), 16, 0, 0); } while (0)
; #define PG8_LDA(dst, b, h) do { _Pragma("unroll") for (int m = 0; m < 4; ++m) _Pragma("unroll") for (int k = 0; k < 2; ++k) dst[m][k] = *(const PG8_LAS bf16x8*)(lds + PG8_SA(b, h) + aoff + m * 2048 + k * 1024); } while (0)
; #define PG8_LDB(dst, b, h) do { _Pragma("unroll") for (int n = 0; n < 2; ++n) _Pragma("unroll") for (int k = 0; k < 2; ++k) dst[n][k] = *(const PG8_LAS bf16x8*)(lds + PG8_SB(b, h) + boff + n * 2048 + k * 1024); } while (0)
; #define PG8_MMA(ai, bj, At, Bt) do { __builtin_amdgcn_s_setprio(1); _Pragma("unroll") for (int m = 0; m < 4; ++m) _Pragma("unroll") for (int n = 0; n < 2; ++n) _Pragma("unroll") for (int k = 0; k < 2; ++k) \
;         acc[ai][bj][m][n] = __builtin_amdgcn_mfma_f32_16x16x32_bf16(Bt[n][k], At[m][k], acc[ai][bj][m][n], 0, 0, 0); __builtin_amdgcn_s_setprio(0); } while (0)
; #define PG8_WAIT_V(n) asm volatile("s_waitcnt vmcnt(" #n ")" ::: "memory")
; #define PG8_BAR __builtin_amdgcn_s_barrier()
; template <class Epi, class Sched, bool ALIGN_EPI = false, bool SP2 = false>
; __device__ __forceinline__ void gemm_phase(PG8_LAS unsigned char* lds, const Gemm g, const Sched& S, const Epi& E) {
;     ...
;         for (int t = 0; t < nt; t += 2) {
;             const bool last = (t == nt - 2);
;             const char* a1 = cA + (size_t)(t + 1) * kstep;
;             const char* a2 = last ? nA : cA + (size_t)(t + 2) * kstep; const char* b2 = last ? nB : cB + (size_t)(t + 2) * kstep;
;             const char* a3 = a2 + kstep; const char* b3 = b2 + kstep;
;             if (last && has_next) S.a_ready(nxt);
;             if constexpr (SP2) {
;             PG8_LDB(B0, 0, 0); PG8_LDB(B1, 0, 1); PG8_SCHED; PG8_LDA(At, 0, 0); PG8_STAGE(PG8_SA(1, 1), a1 + hstep, voffA);
;             PG8_WAIT_V(8); PG8_WAIT_L(0); PG8_BAR; PG8_MMA(0, 0, At, B0); PG8_MMA(0, 1, At, B1); PG8_BAR; PG8_SCHED;
;             PG8_LDA(At, 0, 1); PG8_STAGE(PG8_SB(0, 0), b2, voffB); PG8_STAGE(PG8_SB(0, 1), b2 + hstep, voffB); PG8_STAGE(PG8_SA(0, 0), a2, voffA);
;             PG8_WAIT_V(8); PG8_WAIT_L(0); PG8_BAR; PG8_MMA(1, 0, At, B0); PG8_MMA(1, 1, At, B1); PG8_BAR; PG8_SCHED;
.LBB0_792:
	s_waitcnt lgkmcnt(0)
	ds_read_b128 v[140:143], v254
	ds_read_b128 v[162:165], v254 offset:1024
	ds_read_b128 v[166:169], v254 offset:2048
	ds_read_b128 v[176:179], v254 offset:3072
	ds_read_b128 v[180:183], v254 offset:16384
	ds_read_b128 v[184:187], v254 offset:17408
	ds_read_b128 v[188:191], v254 offset:18432
	ds_read_b128 v[210:213], v254 offset:19456
	s_add_u32 s2, s0, 0xfffc0080
	s_addc_u32 s3, s1, -1
	s_cmp_eq_u32 s52, 12
	s_cselect_b32 s5, s17, s3
	s_cselect_b32 s4, s48, s2
	s_cselect_b32 s3, s15, s51
	s_cselect_b32 s2, s49, s50
	s_add_i32 m0, s6, 0xc000
	ds_read_b128 v[214:217], v173
	ds_read_b128 v[218:221], v173 offset:1024
	ds_read_b128 v[222:225], v173 offset:2048
	ds_read_b128 v[226:229], v173 offset:3072
	ds_read_b128 v[230:233], v173 offset:4096
	ds_read_b128 v[234:237], v173 offset:5120
	ds_read_b128 v[238:241], v173 offset:6144
	ds_read_b128 v[242:245], v173 offset:7168
	global_load_lds_dwordx4 v136, s[0:1]
	s_add_i32 m0, s6, 0xe000
	s_nop 0
	global_load_lds_dwordx4 v138, s[0:1]
	s_waitcnt vmcnt(8)
	s_waitcnt lgkmcnt(0)
	s_barrier
	s_setprio 1
	v_mfma_f32_16x16x32_bf16 v[124:127], v[140:143], v[214:217], v[124:127]
	v_mfma_f32_16x16x32_bf16 v[124:127], v[162:165], v[218:221], v[124:127]
	v_mfma_f32_16x16x32_bf16 v[112:115], v[140:143], v[222:225], v[112:115]
	v_mfma_f32_16x16x32_bf16 v[112:115], v[162:165], v[226:229], v[112:115]
	v_mfma_f32_16x16x32_bf16 v[96:99], v[140:143], v[230:233], v[96:99]
	v_mfma_f32_16x16x32_bf16 v[96:99], v[162:165], v[234:237], v[96:99]
	v_mfma_f32_16x16x32_bf16 v[80:83], v[140:143], v[238:241], v[80:83]
	v_mfma_f32_16x16x32_bf16 v[80:83], v[162:165], v[242:245], v[80:83]
	v_mfma_f32_16x16x32_bf16 v[120:123], v[166:169], v[214:217], v[120:123]
	v_mfma_f32_16x16x32_bf16 v[120:123], v[176:179], v[218:221], v[120:123]
	v_mfma_f32_16x16x32_bf16 v[104:107], v[166:169], v[222:225], v[104:107]
	v_mfma_f32_16x16x32_bf16 v[104:107], v[176:179], v[226:229], v[104:107]
	v_mfma_f32_16x16x32_bf16 v[88:91], v[166:169], v[230:233], v[88:91]
	v_mfma_f32_16x16x32_bf16 v[88:91], v[176:179], v[234:237], v[88:91]
	v_mfma_f32_16x16x32_bf16 v[72:75], v[166:169], v[238:241], v[72:75]
	v_mfma_f32_16x16x32_bf16 v[72:75], v[176:179], v[242:245], v[72:75]
	v_mfma_f32_16x16x32_bf16 v[116:119], v[180:183], v[214:217], v[116:119]
	v_mfma_f32_16x16x32_bf16 v[116:119], v[184:187], v[218:221], v[116:119]
	v_mfma_f32_16x16x32_bf16 v[100:103], v[180:183], v[222:225], v[100:103]
	v_mfma_f32_16x16x32_bf16 v[100:103], v[184:187], v[226:229], v[100:103]
	v_mfma_f32_16x16x32_bf16 v[84:87], v[180:183], v[230:233], v[84:87]
	v_mfma_f32_16x16x32_bf16 v[84:87], v[184:187], v[234:237], v[84:87]
	v_mfma_f32_16x16x32_bf16 v[68:71], v[180:183], v[238:241], v[68:71]
	v_mfma_f32_16x16x32_bf16 v[68:71], v[184:187], v[242:245], v[68:71]
	v_mfma_f32_16x16x32_bf16 v[108:111], v[188:191], v[214:217], v[108:111]
	v_mfma_f32_16x16x32_bf16 v[108:111], v[210:213], v[218:221], v[108:111]
	v_mfma_f32_16x16x32_bf16 v[92:95], v[188:191], v[222:225], v[92:95]
	v_mfma_f32_16x16x32_bf16 v[92:95], v[210:213], v[226:229], v[92:95]
	v_mfma_f32_16x16x32_bf16 v[76:79], v[188:191], v[230:233], v[76:79]
	v_mfma_f32_16x16x32_bf16 v[76:79], v[210:213], v[234:237], v[76:79]
	v_mfma_f32_16x16x32_bf16 v[64:67], v[188:191], v[238:241], v[64:67]
	v_mfma_f32_16x16x32_bf16 v[64:67], v[210:213], v[242:245], v[64:67]
	s_setprio 0
	s_barrier
	s_mov_b32 m0, s27
	s_add_u32 s54, s2, 0x40000
	s_addc_u32 s55, s3, 0
	ds_read_b128 v[214:217], v173 offset:16384
	ds_read_b128 v[218:221], v173 offset:17408
	ds_read_b128 v[222:225], v173 offset:18432
	ds_read_b128 v[226:229], v173 offset:19456
	ds_read_b128 v[230:233], v173 offset:20480
	ds_read_b128 v[234:237], v173 offset:21504
	ds_read_b128 v[238:241], v173 offset:22528
	ds_read_b128 v[242:245], v173 offset:23552
	global_load_lds_dwordx4 v132, s[2:3]
	s_mov_b32 m0, s28
	s_nop 0
	global_load_lds_dwordx4 v128, s[2:3]
	s_mov_b32 m0, s29
	s_nop 0
	global_load_lds_dwordx4 v132, s[54:55]
	s_mov_b32 m0, s30
	s_nop 0
	global_load_lds_dwordx4 v128, s[54:55]
	s_mov_b32 m0, s6
	s_nop 0
	global_load_lds_dwordx4 v134, s[4:5]
	s_mov_b32 m0, s31
	s_nop 0
	global_load_lds_dwordx4 v130, s[4:5]
	s_waitcnt vmcnt(8)
	s_waitcnt lgkmcnt(0)
	s_barrier
	s_setprio 1
	v_mfma_f32_16x16x32_bf16 v[60:63], v[140:143], v[214:217], v[60:63]
	v_mfma_f32_16x16x32_bf16 v[60:63], v[162:165], v[218:221], v[60:63]
	v_mfma_f32_16x16x32_bf16 v[48:51], v[140:143], v[222:225], v[48:51]
	v_mfma_f32_16x16x32_bf16 v[48:51], v[162:165], v[226:229], v[48:51]
	v_mfma_f32_16x16x32_bf16 v[32:35], v[140:143], v[230:233], v[32:35]
	v_mfma_f32_16x16x32_bf16 v[32:35], v[162:165], v[234:237], v[32:35]
	v_mfma_f32_16x16x32_bf16 v[16:19], v[140:143], v[238:241], v[16:19]
	v_mfma_f32_16x16x32_bf16 v[16:19], v[162:165], v[242:245], v[16:19]
	v_mfma_f32_16x16x32_bf16 v[56:59], v[166:169], v[214:217], v[56:59]
	v_mfma_f32_16x16x32_bf16 v[56:59], v[176:179], v[218:221], v[56:59]
	v_mfma_f32_16x16x32_bf16 v[40:43], v[166:169], v[222:225], v[40:43]
	v_mfma_f32_16x16x32_bf16 v[40:43], v[176:179], v[226:229], v[40:43]
	v_mfma_f32_16x16x32_bf16 v[24:27], v[166:169], v[230:233], v[24:27]
	v_mfma_f32_16x16x32_bf16 v[24:27], v[176:179], v[234:237], v[24:27]
	v_mfma_f32_16x16x32_bf16 v[8:11], v[166:169], v[238:241], v[8:11]
	v_mfma_f32_16x16x32_bf16 v[8:11], v[176:179], v[242:245], v[8:11]
	v_mfma_f32_16x16x32_bf16 v[52:55], v[180:183], v[214:217], v[52:55]
	v_mfma_f32_16x16x32_bf16 v[52:55], v[184:187], v[218:221], v[52:55]
	v_mfma_f32_16x16x32_bf16 v[36:39], v[180:183], v[222:225], v[36:39]
	v_mfma_f32_16x16x32_bf16 v[36:39], v[184:187], v[226:229], v[36:39]
	v_mfma_f32_16x16x32_bf16 v[20:23], v[180:183], v[230:233], v[20:23]
	v_mfma_f32_16x16x32_bf16 v[20:23], v[184:187], v[234:237], v[20:23]
	v_mfma_f32_16x16x32_bf16 v[4:7], v[180:183], v[238:241], v[4:7]
	v_mfma_f32_16x16x32_bf16 v[4:7], v[184:187], v[242:245], v[4:7]
	v_mfma_f32_16x16x32_bf16 v[44:47], v[188:191], v[214:217], v[44:47]
	v_mfma_f32_16x16x32_bf16 v[44:47], v[210:213], v[218:221], v[44:47]
	v_mfma_f32_16x16x32_bf16 v[28:31], v[188:191], v[222:225], v[28:31]
	v_mfma_f32_16x16x32_bf16 v[28:31], v[210:213], v[226:229], v[28:31]
	v_mfma_f32_16x16x32_bf16 v[12:15], v[188:191], v[230:233], v[12:15]
	v_mfma_f32_16x16x32_bf16 v[12:15], v[210:213], v[234:237], v[12:15]
	v_mfma_f32_16x16x32_bf16 v[0:3], v[188:191], v[238:241], v[0:3]
	v_mfma_f32_16x16x32_bf16 v[0:3], v[210:213], v[242:245], v[0:3]
	s_setprio 0
	s_barrier
; #define PG8_STAGE(bufoff, gbase, voff) do { _Pragma("unroll") for (int _i = 0; _i < 2; ++_i) \
;         __builtin_amdgcn_global_load_lds((const unsigned*)((const char*)(gbase) + (voff)[_i]), (PG8_LAS unsigned*)(lds + (bufoff) + ldsw + _i * 8192), 16, 0, 0); } while (0)
; #define PG8_LDA(dst, b, h) do { _Pragma("unroll") for (int m = 0; m < 4; ++m) _Pragma("unroll") for (int k = 0; k < 2; ++k) dst[m][k] = *(const PG8_LAS bf16x8*)(lds + PG8_SA(b, h) + aoff + m * 2048 + k * 1024); } while (0)
; #define PG8_LDB(dst, b, h) do { _Pragma("unroll") for (int n = 0; n < 2; ++n) _Pragma("unroll") for (int k = 0; k < 2; ++k) dst[n][k] = *(const PG8_LAS bf16x8*)(lds + PG8_SB(b, h) + boff + n * 2048 + k * 1024); } while (0)
; #define PG8_MMA(ai, bj, At, Bt) do { __builtin_amdgcn_s_setprio(1); _Pragma("unroll") for (int m = 0; m < 4; ++m) _Pragma("unroll") for (int n = 0; n < 2; ++n) _Pragma("unroll") for (int k = 0; k < 2; ++k) \
;         acc[ai][bj][m][n] = __builtin_amdgcn_mfma_f32_16x16x32_bf16(Bt[n][k], At[m][k], acc[ai][bj][m][n], 0, 0, 0); __builtin_amdgcn_s_setprio(0); } while (0)
; #define PG8_WAIT_V(n) asm volatile("s_waitcnt vmcnt(" #n ")" ::: "memory")
; #define PG8_WAIT_L(n) asm volatile("s_waitcnt lgkmcnt(" #n ")" ::: "memory")
; #define PG8_BAR __builtin_amdgcn_s_barrier()
; #define PG8_SCHED __builtin_amdgcn_sched_barrier(0)
; template <class Epi, class Sched, bool ALIGN_EPI = false, bool SP2 = false>
; __device__ __forceinline__ void gemm_phase(PG8_LAS unsigned char* lds, const Gemm g, const Sched& S, const Epi& E) {
;     ...
;         for (int t = 0; t < nt; t += 2) {
;             const bool last = (t == nt - 2);
;             const char* a1 = cA + (size_t)(t + 1) * kstep;
;             const char* a2 = last ? nA : cA + (size_t)(t + 2) * kstep; const char* b2 = last ? nB : cB + (size_t)(t + 2) * kstep;
;     ...
;             PG8_LDB(B0, 1, 0); PG8_LDB(B1, 1, 1); PG8_SCHED; PG8_LDA(At, 1, 0); PG8_STAGE(PG8_SA(0, 1), a2 + hstep, voffA);
;             PG8_WAIT_V(8); PG8_WAIT_L(0); PG8_BAR; PG8_MMA(0, 0, At, B0); PG8_MMA(0, 1, At, B1); PG8_BAR; PG8_SCHED;
;             PG8_LDA(At, 1, 1); PG8_STAGE(PG8_SB(1, 0), b3, voffB); PG8_STAGE(PG8_SB(1, 1), b3 + hstep, voffB); PG8_STAGE(PG8_SA(1, 0), a3, voffA);
;             PG8_WAIT_V(8); PG8_WAIT_L(0); PG8_BAR; PG8_MMA(1, 0, At, B0); PG8_MMA(1, 1, At, B1); PG8_BAR; PG8_SCHED;
	ds_read_b128 v[140:143], v254 offset:32768
	ds_read_b128 v[162:165], v254 offset:33792
	ds_read_b128 v[166:169], v254 offset:34816
	ds_read_b128 v[176:179], v254 offset:35840
	ds_read_b128 v[180:183], v254 offset:49152
	ds_read_b128 v[184:187], v254 offset:50176
	ds_read_b128 v[188:191], v254 offset:51200
	ds_read_b128 v[210:213], v254 offset:52224
	s_add_u32 s4, s4, 0x40000
	s_addc_u32 s5, s5, 0
	s_mov_b32 m0, s33
	ds_read_b128 v[214:217], v173 offset:32768
	ds_read_b128 v[218:221], v173 offset:33792
	ds_read_b128 v[222:225], v173 offset:34816
	ds_read_b128 v[226:229], v173 offset:35840
	ds_read_b128 v[230:233], v173 offset:36864
	ds_read_b128 v[234:237], v173 offset:37888
	ds_read_b128 v[238:241], v173 offset:38912
	ds_read_b128 v[242:245], v173 offset:39936
	global_load_lds_dwordx4 v134, s[4:5]
	s_mov_b32 m0, s34
	s_nop 0
	global_load_lds_dwordx4 v130, s[4:5]
	s_waitcnt vmcnt(8)
	s_waitcnt lgkmcnt(0)
	s_barrier
	s_setprio 1
	v_mfma_f32_16x16x32_bf16 v[124:127], v[140:143], v[214:217], v[124:127]
	v_mfma_f32_16x16x32_bf16 v[124:127], v[162:165], v[218:221], v[124:127]
	v_mfma_f32_16x16x32_bf16 v[112:115], v[140:143], v[222:225], v[112:115]
	v_mfma_f32_16x16x32_bf16 v[112:115], v[162:165], v[226:229], v[112:115]
	v_mfma_f32_16x16x32_bf16 v[96:99], v[140:143], v[230:233], v[96:99]
	v_mfma_f32_16x16x32_bf16 v[96:99], v[162:165], v[234:237], v[96:99]
	v_mfma_f32_16x16x32_bf16 v[80:83], v[140:143], v[238:241], v[80:83]
	v_mfma_f32_16x16x32_bf16 v[80:83], v[162:165], v[242:245], v[80:83]
	v_mfma_f32_16x16x32_bf16 v[120:123], v[166:169], v[214:217], v[120:123]
	v_mfma_f32_16x16x32_bf16 v[120:123], v[176:179], v[218:221], v[120:123]
	v_mfma_f32_16x16x32_bf16 v[104:107], v[166:169], v[222:225], v[104:107]
	v_mfma_f32_16x16x32_bf16 v[104:107], v[176:179], v[226:229], v[104:107]
	v_mfma_f32_16x16x32_bf16 v[88:91], v[166:169], v[230:233], v[88:91]
	v_mfma_f32_16x16x32_bf16 v[88:91], v[176:179], v[234:237], v[88:91]
	v_mfma_f32_16x16x32_bf16 v[72:75], v[166:169], v[238:241], v[72:75]
	v_mfma_f32_16x16x32_bf16 v[72:75], v[176:179], v[242:245], v[72:75]
	v_mfma_f32_16x16x32_bf16 v[116:119], v[180:183], v[214:217], v[116:119]
	v_mfma_f32_16x16x32_bf16 v[116:119], v[184:187], v[218:221], v[116:119]
	v_mfma_f32_16x16x32_bf16 v[100:103], v[180:183], v[222:225], v[100:103]
	v_mfma_f32_16x16x32_bf16 v[100:103], v[184:187], v[226:229], v[100:103]
	v_mfma_f32_16x16x32_bf16 v[84:87], v[180:183], v[230:233], v[84:87]
	v_mfma_f32_16x16x32_bf16 v[84:87], v[184:187], v[234:237], v[84:87]
	v_mfma_f32_16x16x32_bf16 v[68:71], v[180:183], v[238:241], v[68:71]
	v_mfma_f32_16x16x32_bf16 v[68:71], v[184:187], v[242:245], v[68:71]
	v_mfma_f32_16x16x32_bf16 v[108:111], v[188:191], v[214:217], v[108:111]
	v_mfma_f32_16x16x32_bf16 v[108:111], v[210:213], v[218:221], v[108:111]
	v_mfma_f32_16x16x32_bf16 v[92:95], v[188:191], v[222:225], v[92:95]
	v_mfma_f32_16x16x32_bf16 v[92:95], v[210:213], v[226:229], v[92:95]
	v_mfma_f32_16x16x32_bf16 v[76:79], v[188:191], v[230:233], v[76:79]
	v_mfma_f32_16x16x32_bf16 v[76:79], v[210:213], v[234:237], v[76:79]
	v_mfma_f32_16x16x32_bf16 v[64:67], v[188:191], v[238:241], v[64:67]
	v_mfma_f32_16x16x32_bf16 v[64:67], v[210:213], v[242:245], v[64:67]
	s_setprio 0
	s_barrier
	s_mov_b32 m0, s37
	s_add_u32 s2, s2, 0x40080
	s_addc_u32 s3, s3, 0
	ds_read_b128 v[214:217], v173 offset:49152
	ds_read_b128 v[218:221], v173 offset:50176
	ds_read_b128 v[222:225], v173 offset:51200
	ds_read_b128 v[226:229], v173 offset:52224
	ds_read_b128 v[230:233], v173 offset:53248
	ds_read_b128 v[234:237], v173 offset:54272
	ds_read_b128 v[238:241], v173 offset:55296
	ds_read_b128 v[242:245], v173 offset:56320
	s_add_u32 s98, s2, 0xfffc0000
	s_addc_u32 s99, s3, -1
	global_load_lds_dwordx4 v132, s[98:99]
	s_mov_b32 m0, s38
	s_nop 0
	global_load_lds_dwordx4 v128, s[98:99]
	s_mov_b32 m0, s41
	s_nop 0
	global_load_lds_dwordx4 v132, s[2:3]
	s_mov_b32 m0, s42
	s_nop 0
	global_load_lds_dwordx4 v128, s[2:3]
	s_mov_b32 m0, s39
	s_nop 0
	s_add_u32 s100, s4, 0xfffc0080
	s_addc_u32 s101, s5, -1
	global_load_lds_dwordx4 v134, s[100:101]
	s_mov_b32 m0, s40
	s_nop 0
	global_load_lds_dwordx4 v130, s[100:101]
	s_waitcnt vmcnt(8)
	s_waitcnt lgkmcnt(0)
	s_barrier
	s_setprio 1
	v_mfma_f32_16x16x32_bf16 v[60:63], v[140:143], v[214:217], v[60:63]
	v_mfma_f32_16x16x32_bf16 v[60:63], v[162:165], v[218:221], v[60:63]
	v_mfma_f32_16x16x32_bf16 v[48:51], v[140:143], v[222:225], v[48:51]
	v_mfma_f32_16x16x32_bf16 v[48:51], v[162:165], v[226:229], v[48:51]
	v_mfma_f32_16x16x32_bf16 v[32:35], v[140:143], v[230:233], v[32:35]
	v_mfma_f32_16x16x32_bf16 v[32:35], v[162:165], v[234:237], v[32:35]
	v_mfma_f32_16x16x32_bf16 v[16:19], v[140:143], v[238:241], v[16:19]
	v_mfma_f32_16x16x32_bf16 v[16:19], v[162:165], v[242:245], v[16:19]
	v_mfma_f32_16x16x32_bf16 v[56:59], v[166:169], v[214:217], v[56:59]
	v_mfma_f32_16x16x32_bf16 v[56:59], v[176:179], v[218:221], v[56:59]
	v_mfma_f32_16x16x32_bf16 v[40:43], v[166:169], v[222:225], v[40:43]
	v_mfma_f32_16x16x32_bf16 v[40:43], v[176:179], v[226:229], v[40:43]
	v_mfma_f32_16x16x32_bf16 v[24:27], v[166:169], v[230:233], v[24:27]
	v_mfma_f32_16x16x32_bf16 v[24:27], v[176:179], v[234:237], v[24:27]
	v_mfma_f32_16x16x32_bf16 v[8:11], v[166:169], v[238:241], v[8:11]
	v_mfma_f32_16x16x32_bf16 v[8:11], v[176:179], v[242:245], v[8:11]
	v_mfma_f32_16x16x32_bf16 v[52:55], v[180:183], v[214:217], v[52:55]
	v_mfma_f32_16x16x32_bf16 v[52:55], v[184:187], v[218:221], v[52:55]
	v_mfma_f32_16x16x32_bf16 v[36:39], v[180:183], v[222:225], v[36:39]
	v_mfma_f32_16x16x32_bf16 v[36:39], v[184:187], v[226:229], v[36:39]
	v_mfma_f32_16x16x32_bf16 v[20:23], v[180:183], v[230:233], v[20:23]
	v_mfma_f32_16x16x32_bf16 v[20:23], v[184:187], v[234:237], v[20:23]
	v_mfma_f32_16x16x32_bf16 v[4:7], v[180:183], v[238:241], v[4:7]
	v_mfma_f32_16x16x32_bf16 v[4:7], v[184:187], v[242:245], v[4:7]
	v_mfma_f32_16x16x32_bf16 v[44:47], v[188:191], v[214:217], v[44:47]
	v_mfma_f32_16x16x32_bf16 v[44:47], v[210:213], v[218:221], v[44:47]
	v_mfma_f32_16x16x32_bf16 v[28:31], v[188:191], v[222:225], v[28:31]
	v_mfma_f32_16x16x32_bf16 v[28:31], v[210:213], v[226:229], v[28:31]
	v_mfma_f32_16x16x32_bf16 v[12:15], v[188:191], v[230:233], v[12:15]
	v_mfma_f32_16x16x32_bf16 v[12:15], v[210:213], v[234:237], v[12:15]
	v_mfma_f32_16x16x32_bf16 v[0:3], v[188:191], v[238:241], v[0:3]
	v_mfma_f32_16x16x32_bf16 v[0:3], v[210:213], v[242:245], v[0:3]
	s_setprio 0
	s_barrier
	s_add_i32 s52, s52, 2
	s_add_u32 s0, s0, 0x100
	s_addc_u32 s1, s1, 0
	s_add_u32 s50, s50, 0x100
	s_addc_u32 s51, s51, 0
	s_cmp_gt_u32 s52, 13
	s_cbranch_scc0 .LBB0_792
	s_and_b64 vcc, exec, s[12:13]
	s_cbranch_vccz .LBB0_795
	s_barrier

; #define PG8_STAGE(bufoff, gbase, voff) do { _Pragma("unroll") for (int _i = 0; _i < 2; ++_i) \
;         __builtin_amdgcn_global_load_lds((const unsigned*)((const char*)(gbase) + (voff)[_i]), (PG8_LAS unsigned*)(lds + (bufoff) + ldsw + _i * 8192), 16, 0, 0); } while (0)
; #define PG8_LDA(dst, b, h) do { _Pragma("unroll") for (int m = 0; m < 4; ++m) _Pragma("unroll") for (int k = 0; k < 2; ++k) dst[m][k] = *(const PG8_LAS bf16x8*)(lds + PG8_SA(b, h) + aoff + m * 2048 + k * 1024); } while (0)
; #define PG8_LDB(dst, b, h) do { _Pragma("unroll") for (int n = 0; n < 2; ++n) _Pragma("unroll") for (int k = 0; k < 2; ++k) dst[n][k] = *(const PG8_LAS bf16x8*)(lds + PG8_SB(b, h) + boff + n * 2048 + k * 1024); } while (0)
; #define PG8_MMA(ai, bj, At, Bt) do { __builtin_amdgcn_s_setprio(1); _Pragma("unroll") for (int m = 0; m < 4; ++m) _Pragma("unroll") for (int n = 0; n < 2; ++n) _Pragma("unroll") for (int k = 0; k < 2; ++k) \
;         acc[ai][bj][m][n] = __builtin_amdgcn_mfma_f32_16x16x32_bf16(Bt[n][k], At[m][k], acc[ai][bj][m][n], 0, 0, 0); __builtin_amdgcn_s_setprio(0); } while (0)
; #define PG8_WAIT_V(n) asm volatile("s_waitcnt vmcnt(" #n ")" ::: "memory")
; #define PG8_WAIT_L(n) asm volatile("s_waitcnt lgkmcnt(" #n ")" ::: "memory")
; template <class Epi, class Sched, bool ALIGN_EPI = false, bool SP2 = false>
; __device__ __forceinline__ void gemm_phase(PG8_LAS unsigned char* lds, const Gemm g, const Sched& S, const Epi& E) {
;     ...
;             const bool last = (t == nt - 2);
;             const char* a1 = cA + (size_t)(t + 1) * kstep;
;             const char* a2 = last ? nA : cA + (size_t)(t + 2) * kstep; const char* b2 = last ? nB : cB + (size_t)(t + 2) * kstep;
;             const char* a3 = a2 + kstep; const char* b3 = b2 + kstep;
;             if (last && has_next) S.a_ready(nxt);
;             if constexpr (SP2) {
;             PG8_LDB(B0, 0, 0); PG8_LDB(B1, 0, 1); PG8_SCHED; PG8_LDA(At, 0, 0); PG8_STAGE(PG8_SA(1, 1), a1 + hstep, voffA);
;             PG8_WAIT_V(8); PG8_WAIT_L(0); PG8_BAR; PG8_MMA(0, 0, At, B0); PG8_MMA(0, 1, At, B1); PG8_BAR; PG8_SCHED;
;             PG8_LDA(At, 0, 1); PG8_STAGE(PG8_SB(0, 0), b2, voffB); PG8_STAGE(PG8_SB(0, 1), b2 + hstep, voffB); PG8_STAGE(PG8_SA(0, 0), a2, voffA);
;             PG8_WAIT_V(8); PG8_WAIT_L(0); PG8_BAR; PG8_MMA(1, 0, At, B0); PG8_MMA(1, 1, At, B1); PG8_BAR; PG8_SCHED;
.Lsgo_peel:
	ds_read_b128 v[140:143], v254
	ds_read_b128 v[166:169], v254 offset:1024
	ds_read_b128 v[170:173], v254 offset:2048
	ds_read_b128 v[174:177], v254 offset:3072
	ds_read_b128 v[178:181], v254 offset:16384
	ds_read_b128 v[182:185], v254 offset:17408
	ds_read_b128 v[186:189], v254 offset:18432
	ds_read_b128 v[210:213], v254 offset:19456
	s_add_u32 s2, s0, 0xfffc0080
	s_addc_u32 s3, s1, -1
	s_cmp_eq_u32 s55, 12
	s_cselect_b32 s5, s23, s3
	s_cselect_b32 s4, s51, s2
	s_cselect_b32 s3, s21, s54
	s_cselect_b32 s2, s52, s53
	s_add_i32 m0, s31, 0xc000
	ds_read_b128 v[214:217], v163
	ds_read_b128 v[218:221], v163 offset:1024
	ds_read_b128 v[222:225], v163 offset:2048
	ds_read_b128 v[226:229], v163 offset:3072
	ds_read_b128 v[230:233], v163 offset:4096
	ds_read_b128 v[234:237], v163 offset:5120
	ds_read_b128 v[238:241], v163 offset:6144
	ds_read_b128 v[242:245], v163 offset:7168
	global_load_lds_dwordx4 v136, s[0:1]
	s_add_i32 m0, s31, 0xe000
	s_nop 0
	global_load_lds_dwordx4 v138, s[0:1]
	s_waitcnt vmcnt(8)
	s_waitcnt lgkmcnt(0)
	s_barrier
	s_setprio 1
	v_mfma_f32_16x16x32_bf16 v[124:127], v[140:143], v[214:217], 0
	v_mfma_f32_16x16x32_bf16 v[124:127], v[166:169], v[218:221], v[124:127]
	v_mfma_f32_16x16x32_bf16 v[108:111], v[140:143], v[222:225], 0
	v_mfma_f32_16x16x32_bf16 v[108:111], v[166:169], v[226:229], v[108:111]
	v_mfma_f32_16x16x32_bf16 v[92:95], v[140:143], v[230:233], 0
	v_mfma_f32_16x16x32_bf16 v[92:95], v[166:169], v[234:237], v[92:95]
	v_mfma_f32_16x16x32_bf16 v[76:79], v[140:143], v[238:241], 0
	v_mfma_f32_16x16x32_bf16 v[76:79], v[166:169], v[242:245], v[76:79]
	v_mfma_f32_16x16x32_bf16 v[120:123], v[170:173], v[214:217], 0
	v_mfma_f32_16x16x32_bf16 v[120:123], v[174:177], v[218:221], v[120:123]
	v_mfma_f32_16x16x32_bf16 v[104:107], v[170:173], v[222:225], 0
	v_mfma_f32_16x16x32_bf16 v[104:107], v[174:177], v[226:229], v[104:107]
	v_mfma_f32_16x16x32_bf16 v[88:91], v[170:173], v[230:233], 0
	v_mfma_f32_16x16x32_bf16 v[88:91], v[174:177], v[234:237], v[88:91]
	v_mfma_f32_16x16x32_bf16 v[72:75], v[170:173], v[238:241], 0
	v_mfma_f32_16x16x32_bf16 v[72:75], v[174:177], v[242:245], v[72:75]
	v_mfma_f32_16x16x32_bf16 v[116:119], v[178:181], v[214:217], 0
	v_mfma_f32_16x16x32_bf16 v[116:119], v[182:185], v[218:221], v[116:119]
	v_mfma_f32_16x16x32_bf16 v[100:103], v[178:181], v[222:225], 0
	v_mfma_f32_16x16x32_bf16 v[100:103], v[182:185], v[226:229], v[100:103]
	v_mfma_f32_16x16x32_bf16 v[84:87], v[178:181], v[230:233], 0
	v_mfma_f32_16x16x32_bf16 v[84:87], v[182:185], v[234:237], v[84:87]
	v_mfma_f32_16x16x32_bf16 v[68:71], v[178:181], v[238:241], 0
	v_mfma_f32_16x16x32_bf16 v[68:71], v[182:185], v[242:245], v[68:71]
	v_mfma_f32_16x16x32_bf16 v[112:115], v[186:189], v[214:217], 0
	v_mfma_f32_16x16x32_bf16 v[112:115], v[210:213], v[218:221], v[112:115]
	v_mfma_f32_16x16x32_bf16 v[96:99], v[186:189], v[222:225], 0
	v_mfma_f32_16x16x32_bf16 v[96:99], v[210:213], v[226:229], v[96:99]
	v_mfma_f32_16x16x32_bf16 v[80:83], v[186:189], v[230:233], 0
	v_mfma_f32_16x16x32_bf16 v[80:83], v[210:213], v[234:237], v[80:83]
	v_mfma_f32_16x16x32_bf16 v[64:67], v[186:189], v[238:241], 0
	v_mfma_f32_16x16x32_bf16 v[64:67], v[210:213], v[242:245], v[64:67]
	s_setprio 0
	s_barrier
	s_mov_b32 m0, s33
	s_add_u32 s56, s2, 0x40000
	s_addc_u32 s57, s3, 0
	ds_read_b128 v[214:217], v163 offset:16384
	ds_read_b128 v[218:221], v163 offset:17408
	ds_read_b128 v[222:225], v163 offset:18432
	ds_read_b128 v[226:229], v163 offset:19456
	ds_read_b128 v[230:233], v163 offset:20480
	ds_read_b128 v[234:237], v163 offset:21504
	ds_read_b128 v[238:241], v163 offset:22528
	ds_read_b128 v[242:245], v163 offset:23552
	global_load_lds_dwordx4 v132, s[2:3]
	s_mov_b32 m0, s34
	s_nop 0
	global_load_lds_dwordx4 v128, s[2:3]
	s_mov_b32 m0, s35
	s_nop 0
	global_load_lds_dwordx4 v132, s[56:57]
	s_mov_b32 m0, s36
	s_nop 0
	global_load_lds_dwordx4 v128, s[56:57]
	s_mov_b32 m0, s31
	s_nop 0
	global_load_lds_dwordx4 v134, s[4:5]
	s_mov_b32 m0, s37
	s_nop 0
	global_load_lds_dwordx4 v130, s[4:5]
	s_waitcnt vmcnt(8)
	s_waitcnt lgkmcnt(0)
	s_barrier
	s_setprio 1
	v_mfma_f32_16x16x32_bf16 v[60:63], v[140:143], v[214:217], 0
	v_mfma_f32_16x16x32_bf16 v[60:63], v[166:169], v[218:221], v[60:63]
	v_mfma_f32_16x16x32_bf16 v[44:47], v[140:143], v[222:225], 0
	v_mfma_f32_16x16x32_bf16 v[44:47], v[166:169], v[226:229], v[44:47]
	v_mfma_f32_16x16x32_bf16 v[28:31], v[140:143], v[230:233], 0
	v_mfma_f32_16x16x32_bf16 v[28:31], v[166:169], v[234:237], v[28:31]
	v_mfma_f32_16x16x32_bf16 v[12:15], v[140:143], v[238:241], 0
	v_mfma_f32_16x16x32_bf16 v[12:15], v[166:169], v[242:245], v[12:15]
	v_mfma_f32_16x16x32_bf16 v[56:59], v[170:173], v[214:217], 0
	v_mfma_f32_16x16x32_bf16 v[56:59], v[174:177], v[218:221], v[56:59]
	v_mfma_f32_16x16x32_bf16 v[40:43], v[170:173], v[222:225], 0
	v_mfma_f32_16x16x32_bf16 v[40:43], v[174:177], v[226:229], v[40:43]
	v_mfma_f32_16x16x32_bf16 v[24:27], v[170:173], v[230:233], 0
	v_mfma_f32_16x16x32_bf16 v[24:27], v[174:177], v[234:237], v[24:27]
	v_mfma_f32_16x16x32_bf16 v[8:11], v[170:173], v[238:241], 0
	v_mfma_f32_16x16x32_bf16 v[8:11], v[174:177], v[242:245], v[8:11]
	v_mfma_f32_16x16x32_bf16 v[52:55], v[178:181], v[214:217], 0
	v_mfma_f32_16x16x32_bf16 v[52:55], v[182:185], v[218:221], v[52:55]
	v_mfma_f32_16x16x32_bf16 v[36:39], v[178:181], v[222:225], 0
	v_mfma_f32_16x16x32_bf16 v[36:39], v[182:185], v[226:229], v[36:39]
	v_mfma_f32_16x16x32_bf16 v[20:23], v[178:181], v[230:233], 0
	v_mfma_f32_16x16x32_bf16 v[20:23], v[182:185], v[234:237], v[20:23]
	v_mfma_f32_16x16x32_bf16 v[4:7], v[178:181], v[238:241], 0
	v_mfma_f32_16x16x32_bf16 v[4:7], v[182:185], v[242:245], v[4:7]
	v_mfma_f32_16x16x32_bf16 v[48:51], v[186:189], v[214:217], 0
	v_mfma_f32_16x16x32_bf16 v[48:51], v[210:213], v[218:221], v[48:51]
	v_mfma_f32_16x16x32_bf16 v[32:35], v[186:189], v[222:225], 0
	v_mfma_f32_16x16x32_bf16 v[32:35], v[210:213], v[226:229], v[32:35]
	v_mfma_f32_16x16x32_bf16 v[16:19], v[186:189], v[230:233], 0
	v_mfma_f32_16x16x32_bf16 v[16:19], v[210:213], v[234:237], v[16:19]
	v_mfma_f32_16x16x32_bf16 v[0:3], v[186:189], v[238:241], 0
	v_mfma_f32_16x16x32_bf16 v[0:3], v[210:213], v[242:245], v[0:3]
	s_setprio 0
	s_barrier
; #define PG8_STAGE(bufoff, gbase, voff) do { _Pragma("unroll") for (int _i = 0; _i < 2; ++_i) \
;         __builtin_amdgcn_global_load_lds((const unsigned*)((const char*)(gbase) + (voff)[_i]), (PG8_LAS unsigned*)(lds + (bufoff) + ldsw + _i * 8192), 16, 0, 0); } while (0)
; #define PG8_LDA(dst, b, h) do { _Pragma("unroll") for (int m = 0; m < 4; ++m) _Pragma("unroll") for (int k = 0; k < 2; ++k) dst[m][k] = *(const PG8_LAS bf16x8*)(lds + PG8_SA(b, h) + aoff + m * 2048 + k * 1024); } while (0)
; #define PG8_LDB(dst, b, h) do { _Pragma("unroll") for (int n = 0; n < 2; ++n) _Pragma("unroll") for (int k = 0; k < 2; ++k) dst[n][k] = *(const PG8_LAS bf16x8*)(lds + PG8_SB(b, h) + boff + n * 2048 + k * 1024); } while (0)
; #define PG8_MMA(ai, bj, At, Bt) do { __builtin_amdgcn_s_setprio(1); _Pragma("unroll") for (int m = 0; m < 4; ++m) _Pragma("unroll") for (int n = 0; n < 2; ++n) _Pragma("unroll") for (int k = 0; k < 2; ++k) \
;         acc[ai][bj][m][n] = __builtin_amdgcn_mfma_f32_16x16x32_bf16(Bt[n][k], At[m][k], acc[ai][bj][m][n], 0, 0, 0); __builtin_amdgcn_s_setprio(0); } while (0)
; #define PG8_WAIT_V(n) asm volatile("s_waitcnt vmcnt(" #n ")" ::: "memory")
; #define PG8_WAIT_L(n) asm volatile("s_waitcnt lgkmcnt(" #n ")" ::: "memory")
; #define PG8_BAR __builtin_amdgcn_s_barrier()
; #define PG8_SCHED __builtin_amdgcn_sched_barrier(0)
; template <class Epi, class Sched, bool ALIGN_EPI = false, bool SP2 = false>
; __device__ __forceinline__ void gemm_phase(PG8_LAS unsigned char* lds, const Gemm g, const Sched& S, const Epi& E) {
;     ...
;             PG8_LDB(B0, 1, 0); PG8_LDB(B1, 1, 1); PG8_SCHED; PG8_LDA(At, 1, 0); PG8_STAGE(PG8_SA(0, 1), a2 + hstep, voffA);
;             PG8_WAIT_V(8); PG8_WAIT_L(0); PG8_BAR; PG8_MMA(0, 0, At, B0); PG8_MMA(0, 1, At, B1); PG8_BAR; PG8_SCHED;
;             PG8_LDA(At, 1, 1); PG8_STAGE(PG8_SB(1, 0), b3, voffB); PG8_STAGE(PG8_SB(1, 1), b3 + hstep, voffB); PG8_STAGE(PG8_SA(1, 0), a3, voffA);
;             PG8_WAIT_V(8); PG8_WAIT_L(0); PG8_BAR; PG8_MMA(1, 0, At, B0); PG8_MMA(1, 1, At, B1); PG8_BAR; PG8_SCHED;
	ds_read_b128 v[140:143], v254 offset:32768
	ds_read_b128 v[166:169], v254 offset:33792
	ds_read_b128 v[170:173], v254 offset:34816
	ds_read_b128 v[174:177], v254 offset:35840
	ds_read_b128 v[178:181], v254 offset:49152
	ds_read_b128 v[182:185], v254 offset:50176
	ds_read_b128 v[186:189], v254 offset:51200
	ds_read_b128 v[210:213], v254 offset:52224
	s_add_u32 s4, s4, 0x40000
	s_addc_u32 s5, s5, 0
	s_mov_b32 m0, s38
	ds_read_b128 v[214:217], v163 offset:32768
	ds_read_b128 v[218:221], v163 offset:33792
	ds_read_b128 v[222:225], v163 offset:34816
	ds_read_b128 v[226:229], v163 offset:35840
	ds_read_b128 v[230:233], v163 offset:36864
	ds_read_b128 v[234:237], v163 offset:37888
	ds_read_b128 v[238:241], v163 offset:38912
	ds_read_b128 v[242:245], v163 offset:39936
	global_load_lds_dwordx4 v134, s[4:5]
	s_mov_b32 m0, s39
	s_nop 0
	global_load_lds_dwordx4 v130, s[4:5]
	s_waitcnt vmcnt(8)
	s_waitcnt lgkmcnt(0)
	s_barrier
	s_setprio 1
	v_mfma_f32_16x16x32_bf16 v[124:127], v[140:143], v[214:217], v[124:127]
	v_mfma_f32_16x16x32_bf16 v[124:127], v[166:169], v[218:221], v[124:127]
	v_mfma_f32_16x16x32_bf16 v[108:111], v[140:143], v[222:225], v[108:111]
	v_mfma_f32_16x16x32_bf16 v[108:111], v[166:169], v[226:229], v[108:111]
	v_mfma_f32_16x16x32_bf16 v[92:95], v[140:143], v[230:233], v[92:95]
	v_mfma_f32_16x16x32_bf16 v[92:95], v[166:169], v[234:237], v[92:95]
	v_mfma_f32_16x16x32_bf16 v[76:79], v[140:143], v[238:241], v[76:79]
	v_mfma_f32_16x16x32_bf16 v[76:79], v[166:169], v[242:245], v[76:79]
	v_mfma_f32_16x16x32_bf16 v[120:123], v[170:173], v[214:217], v[120:123]
	v_mfma_f32_16x16x32_bf16 v[120:123], v[174:177], v[218:221], v[120:123]
	v_mfma_f32_16x16x32_bf16 v[104:107], v[170:173], v[222:225], v[104:107]
	v_mfma_f32_16x16x32_bf16 v[104:107], v[174:177], v[226:229], v[104:107]
	v_mfma_f32_16x16x32_bf16 v[88:91], v[170:173], v[230:233], v[88:91]
	v_mfma_f32_16x16x32_bf16 v[88:91], v[174:177], v[234:237], v[88:91]
	v_mfma_f32_16x16x32_bf16 v[72:75], v[170:173], v[238:241], v[72:75]
	v_mfma_f32_16x16x32_bf16 v[72:75], v[174:177], v[242:245], v[72:75]
	v_mfma_f32_16x16x32_bf16 v[116:119], v[178:181], v[214:217], v[116:119]
	v_mfma_f32_16x16x32_bf16 v[116:119], v[182:185], v[218:221], v[116:119]
	v_mfma_f32_16x16x32_bf16 v[100:103], v[178:181], v[222:225], v[100:103]
	v_mfma_f32_16x16x32_bf16 v[100:103], v[182:185], v[226:229], v[100:103]
	v_mfma_f32_16x16x32_bf16 v[84:87], v[178:181], v[230:233], v[84:87]
	v_mfma_f32_16x16x32_bf16 v[84:87], v[182:185], v[234:237], v[84:87]
	v_mfma_f32_16x16x32_bf16 v[68:71], v[178:181], v[238:241], v[68:71]
	v_mfma_f32_16x16x32_bf16 v[68:71], v[182:185], v[242:245], v[68:71]
	v_mfma_f32_16x16x32_bf16 v[112:115], v[186:189], v[214:217], v[112:115]
	v_mfma_f32_16x16x32_bf16 v[112:115], v[210:213], v[218:221], v[112:115]
	v_mfma_f32_16x16x32_bf16 v[96:99], v[186:189], v[222:225], v[96:99]
	v_mfma_f32_16x16x32_bf16 v[96:99], v[210:213], v[226:229], v[96:99]
	v_mfma_f32_16x16x32_bf16 v[80:83], v[186:189], v[230:233], v[80:83]
	v_mfma_f32_16x16x32_bf16 v[80:83], v[210:213], v[234:237], v[80:83]
	v_mfma_f32_16x16x32_bf16 v[64:67], v[186:189], v[238:241], v[64:67]
	v_mfma_f32_16x16x32_bf16 v[64:67], v[210:213], v[242:245], v[64:67]
	s_setprio 0
	s_barrier
	s_mov_b32 m0, s43
	s_add_u32 s2, s2, 0x40080
	s_addc_u32 s3, s3, 0
	ds_read_b128 v[214:217], v163 offset:49152
	ds_read_b128 v[218:221], v163 offset:50176
	ds_read_b128 v[222:225], v163 offset:51200
	ds_read_b128 v[226:229], v163 offset:52224
	ds_read_b128 v[230:233], v163 offset:53248
	ds_read_b128 v[234:237], v163 offset:54272
	ds_read_b128 v[238:241], v163 offset:55296
	ds_read_b128 v[242:245], v163 offset:56320
	s_add_u32 s98, s2, 0xfffc0000
	s_addc_u32 s99, s3, -1
	global_load_lds_dwordx4 v132, s[98:99]
	s_mov_b32 m0, s44
	s_nop 0
	global_load_lds_dwordx4 v128, s[98:99]
	s_mov_b32 m0, s48
	s_nop 0
	global_load_lds_dwordx4 v132, s[2:3]
	s_mov_b32 m0, s49
	s_nop 0
	global_load_lds_dwordx4 v128, s[2:3]
	s_mov_b32 m0, s45
	s_nop 0
	s_add_u32 s100, s4, 0xfffc0080
	s_addc_u32 s101, s5, -1
	global_load_lds_dwordx4 v134, s[100:101]
	s_mov_b32 m0, s47
	s_nop 0
	global_load_lds_dwordx4 v130, s[100:101]
	s_waitcnt vmcnt(8)
	s_waitcnt lgkmcnt(0)
	s_barrier
	s_setprio 1
	v_mfma_f32_16x16x32_bf16 v[60:63], v[140:143], v[214:217], v[60:63]
	v_mfma_f32_16x16x32_bf16 v[60:63], v[166:169], v[218:221], v[60:63]
	v_mfma_f32_16x16x32_bf16 v[44:47], v[140:143], v[222:225], v[44:47]
	v_mfma_f32_16x16x32_bf16 v[44:47], v[166:169], v[226:229], v[44:47]
	v_mfma_f32_16x16x32_bf16 v[28:31], v[140:143], v[230:233], v[28:31]
	v_mfma_f32_16x16x32_bf16 v[28:31], v[166:169], v[234:237], v[28:31]
	v_mfma_f32_16x16x32_bf16 v[12:15], v[140:143], v[238:241], v[12:15]
	v_mfma_f32_16x16x32_bf16 v[12:15], v[166:169], v[242:245], v[12:15]
	v_mfma_f32_16x16x32_bf16 v[56:59], v[170:173], v[214:217], v[56:59]
	v_mfma_f32_16x16x32_bf16 v[56:59], v[174:177], v[218:221], v[56:59]
	v_mfma_f32_16x16x32_bf16 v[40:43], v[170:173], v[222:225], v[40:43]
	v_mfma_f32_16x16x32_bf16 v[40:43], v[174:177], v[226:229], v[40:43]
	v_mfma_f32_16x16x32_bf16 v[24:27], v[170:173], v[230:233], v[24:27]
	v_mfma_f32_16x16x32_bf16 v[24:27], v[174:177], v[234:237], v[24:27]
	v_mfma_f32_16x16x32_bf16 v[8:11], v[170:173], v[238:241], v[8:11]
	v_mfma_f32_16x16x32_bf16 v[8:11], v[174:177], v[242:245], v[8:11]
	v_mfma_f32_16x16x32_bf16 v[52:55], v[178:181], v[214:217], v[52:55]
	v_mfma_f32_16x16x32_bf16 v[52:55], v[182:185], v[218:221], v[52:55]
	v_mfma_f32_16x16x32_bf16 v[36:39], v[178:181], v[222:225], v[36:39]
	v_mfma_f32_16x16x32_bf16 v[36:39], v[182:185], v[226:229], v[36:39]
	v_mfma_f32_16x16x32_bf16 v[20:23], v[178:181], v[230:233], v[20:23]
	v_mfma_f32_16x16x32_bf16 v[20:23], v[182:185], v[234:237], v[20:23]
	v_mfma_f32_16x16x32_bf16 v[4:7], v[178:181], v[238:241], v[4:7]
	v_mfma_f32_16x16x32_bf16 v[4:7], v[182:185], v[242:245], v[4:7]
	v_mfma_f32_16x16x32_bf16 v[48:51], v[186:189], v[214:217], v[48:51]
	v_mfma_f32_16x16x32_bf16 v[48:51], v[210:213], v[218:221], v[48:51]
	v_mfma_f32_16x16x32_bf16 v[32:35], v[186:189], v[222:225], v[32:35]
	v_mfma_f32_16x16x32_bf16 v[32:35], v[210:213], v[226:229], v[32:35]
	v_mfma_f32_16x16x32_bf16 v[16:19], v[186:189], v[230:233], v[16:19]
	v_mfma_f32_16x16x32_bf16 v[16:19], v[210:213], v[234:237], v[16:19]
	v_mfma_f32_16x16x32_bf16 v[0:3], v[186:189], v[238:241], v[0:3]
	v_mfma_f32_16x16x32_bf16 v[0:3], v[210:213], v[242:245], v[0:3]
	s_setprio 0
	s_barrier
	s_add_i32 s55, s55, 2
	s_add_u32 s0, s0, 0x100
	s_addc_u32 s1, s1, 0
	s_add_u32 s53, s53, 0x100
	s_addc_u32 s54, s54, 0
	s_cmp_gt_u32 s55, 13
; #define PG8_STAGE(bufoff, gbase, voff) do { _Pragma("unroll") for (int _i = 0; _i < 2; ++_i) \
;         __builtin_amdgcn_global_load_lds((const unsigned*)((const char*)(gbase) + (voff)[_i]), (PG8_LAS unsigned*)(lds + (bufoff) + ldsw + _i * 8192), 16, 0, 0); } while (0)
; #define PG8_LDA(dst, b, h) do { _Pragma("unroll") for (int m = 0; m < 4; ++m) _Pragma("unroll") for (int k = 0; k < 2; ++k) dst[m][k] = *(const PG8_LAS bf16x8*)(lds + PG8_SA(b, h) + aoff + m * 2048 + k * 1024); } while (0)
; #define PG8_LDB(dst, b, h) do { _Pragma("unroll") for (int n = 0; n < 2; ++n) _Pragma("unroll") for (int k = 0; k < 2; ++k) dst[n][k] = *(const PG8_LAS bf16x8*)(lds + PG8_SB(b, h) + boff + n * 2048 + k * 1024); } while (0)
; #define PG8_MMA(ai, bj, At, Bt) do { __builtin_amdgcn_s_setprio(1); _Pragma("unroll") for (int m = 0; m < 4; ++m) _Pragma("unroll") for (int n = 0; n < 2; ++n) _Pragma("unroll") for (int k = 0; k < 2; ++k) \
;         acc[ai][bj][m][n] = __builtin_amdgcn_mfma_f32_16x16x32_bf16(Bt[n][k], At[m][k], acc[ai][bj][m][n], 0, 0, 0); __builtin_amdgcn_s_setprio(0); } while (0)
; #define PG8_WAIT_V(n) asm volatile("s_waitcnt vmcnt(" #n ")" ::: "memory")
; #define PG8_WAIT_L(n) asm volatile("s_waitcnt lgkmcnt(" #n ")" ::: "memory")
; template <class Epi, class Sched, bool ALIGN_EPI = false, bool SP2 = false>
; __device__ __forceinline__ void gemm_phase(PG8_LAS unsigned char* lds, const Gemm g, const Sched& S, const Epi& E) {
;     ...
;             const bool last = (t == nt - 2);
;             const char* a1 = cA + (size_t)(t + 1) * kstep;
;             const char* a2 = last ? nA : cA + (size_t)(t + 2) * kstep; const char* b2 = last ? nB : cB + (size_t)(t + 2) * kstep;
;             const char* a3 = a2 + kstep; const char* b3 = b2 + kstep;
;             if (last && has_next) S.a_ready(nxt);
;             if constexpr (SP2) {
;             PG8_LDB(B0, 0, 0); PG8_LDB(B1, 0, 1); PG8_SCHED; PG8_LDA(At, 0, 0); PG8_STAGE(PG8_SA(1, 1), a1 + hstep, voffA);
;             PG8_WAIT_V(8); PG8_WAIT_L(0); PG8_BAR; PG8_MMA(0, 0, At, B0); PG8_MMA(0, 1, At, B1); PG8_BAR; PG8_SCHED;
;             PG8_LDA(At, 0, 1); PG8_STAGE(PG8_SB(0, 0), b2, voffB); PG8_STAGE(PG8_SB(0, 1), b2 + hstep, voffB); PG8_STAGE(PG8_SA(0, 0), a2, voffA);
;             PG8_WAIT_V(8); PG8_WAIT_L(0); PG8_BAR; PG8_MMA(1, 0, At, B0); PG8_MMA(1, 1, At, B1); PG8_BAR; PG8_SCHED;
.LBB0_1042:
	ds_read_b128 v[140:143], v254
	ds_read_b128 v[166:169], v254 offset:1024
	ds_read_b128 v[170:173], v254 offset:2048
	ds_read_b128 v[174:177], v254 offset:3072
	ds_read_b128 v[178:181], v254 offset:16384
	ds_read_b128 v[182:185], v254 offset:17408
	ds_read_b128 v[186:189], v254 offset:18432
	ds_read_b128 v[210:213], v254 offset:19456
	s_add_u32 s2, s0, 0xfffc0080
	s_addc_u32 s3, s1, -1
	s_cmp_eq_u32 s55, 12
	s_cselect_b32 s5, s23, s3
	s_cselect_b32 s4, s51, s2
	s_cselect_b32 s3, s21, s54
	s_cselect_b32 s2, s52, s53
	s_add_i32 m0, s31, 0xc000
	ds_read_b128 v[214:217], v163
	ds_read_b128 v[218:221], v163 offset:1024
	ds_read_b128 v[222:225], v163 offset:2048
	ds_read_b128 v[226:229], v163 offset:3072
	ds_read_b128 v[230:233], v163 offset:4096
	ds_read_b128 v[234:237], v163 offset:5120
	ds_read_b128 v[238:241], v163 offset:6144
	ds_read_b128 v[242:245], v163 offset:7168
	global_load_lds_dwordx4 v136, s[0:1]
	s_add_i32 m0, s31, 0xe000
	s_nop 0
	global_load_lds_dwordx4 v138, s[0:1]
	s_waitcnt vmcnt(8)
	s_waitcnt lgkmcnt(0)
	s_barrier
	s_setprio 1
	v_mfma_f32_16x16x32_bf16 v[124:127], v[140:143], v[214:217], v[124:127]
	v_mfma_f32_16x16x32_bf16 v[124:127], v[166:169], v[218:221], v[124:127]
	v_mfma_f32_16x16x32_bf16 v[108:111], v[140:143], v[222:225], v[108:111]
	v_mfma_f32_16x16x32_bf16 v[108:111], v[166:169], v[226:229], v[108:111]
	v_mfma_f32_16x16x32_bf16 v[92:95], v[140:143], v[230:233], v[92:95]
	v_mfma_f32_16x16x32_bf16 v[92:95], v[166:169], v[234:237], v[92:95]
	v_mfma_f32_16x16x32_bf16 v[76:79], v[140:143], v[238:241], v[76:79]
	v_mfma_f32_16x16x32_bf16 v[76:79], v[166:169], v[242:245], v[76:79]
	v_mfma_f32_16x16x32_bf16 v[120:123], v[170:173], v[214:217], v[120:123]
	v_mfma_f32_16x16x32_bf16 v[120:123], v[174:177], v[218:221], v[120:123]
	v_mfma_f32_16x16x32_bf16 v[104:107], v[170:173], v[222:225], v[104:107]
	v_mfma_f32_16x16x32_bf16 v[104:107], v[174:177], v[226:229], v[104:107]
	v_mfma_f32_16x16x32_bf16 v[88:91], v[170:173], v[230:233], v[88:91]
	v_mfma_f32_16x16x32_bf16 v[88:91], v[174:177], v[234:237], v[88:91]
	v_mfma_f32_16x16x32_bf16 v[72:75], v[170:173], v[238:241], v[72:75]
	v_mfma_f32_16x16x32_bf16 v[72:75], v[174:177], v[242:245], v[72:75]
	v_mfma_f32_16x16x32_bf16 v[116:119], v[178:181], v[214:217], v[116:119]
	v_mfma_f32_16x16x32_bf16 v[116:119], v[182:185], v[218:221], v[116:119]
	v_mfma_f32_16x16x32_bf16 v[100:103], v[178:181], v[222:225], v[100:103]
	v_mfma_f32_16x16x32_bf16 v[100:103], v[182:185], v[226:229], v[100:103]
	v_mfma_f32_16x16x32_bf16 v[84:87], v[178:181], v[230:233], v[84:87]
	v_mfma_f32_16x16x32_bf16 v[84:87], v[182:185], v[234:237], v[84:87]
	v_mfma_f32_16x16x32_bf16 v[68:71], v[178:181], v[238:241], v[68:71]
	v_mfma_f32_16x16x32_bf16 v[68:71], v[182:185], v[242:245], v[68:71]
	v_mfma_f32_16x16x32_bf16 v[112:115], v[186:189], v[214:217], v[112:115]
	v_mfma_f32_16x16x32_bf16 v[112:115], v[210:213], v[218:221], v[112:115]
	v_mfma_f32_16x16x32_bf16 v[96:99], v[186:189], v[222:225], v[96:99]
	v_mfma_f32_16x16x32_bf16 v[96:99], v[210:213], v[226:229], v[96:99]
	v_mfma_f32_16x16x32_bf16 v[80:83], v[186:189], v[230:233], v[80:83]
	v_mfma_f32_16x16x32_bf16 v[80:83], v[210:213], v[234:237], v[80:83]
	v_mfma_f32_16x16x32_bf16 v[64:67], v[186:189], v[238:241], v[64:67]
	v_mfma_f32_16x16x32_bf16 v[64:67], v[210:213], v[242:245], v[64:67]
	s_setprio 0
	s_barrier
	s_mov_b32 m0, s33
	s_add_u32 s56, s2, 0x40000
	s_addc_u32 s57, s3, 0
	ds_read_b128 v[214:217], v163 offset:16384
	ds_read_b128 v[218:221], v163 offset:17408
	ds_read_b128 v[222:225], v163 offset:18432
	ds_read_b128 v[226:229], v163 offset:19456
	ds_read_b128 v[230:233], v163 offset:20480
	ds_read_b128 v[234:237], v163 offset:21504
	ds_read_b128 v[238:241], v163 offset:22528
	ds_read_b128 v[242:245], v163 offset:23552
	global_load_lds_dwordx4 v132, s[2:3]
	s_mov_b32 m0, s34
	s_nop 0
	global_load_lds_dwordx4 v128, s[2:3]
	s_mov_b32 m0, s35
	s_nop 0
	global_load_lds_dwordx4 v132, s[56:57]
	s_mov_b32 m0, s36
	s_nop 0
	global_load_lds_dwordx4 v128, s[56:57]
	s_mov_b32 m0, s31
	s_nop 0
	global_load_lds_dwordx4 v134, s[4:5]
	s_mov_b32 m0, s37
	s_nop 0
	global_load_lds_dwordx4 v130, s[4:5]
	s_waitcnt vmcnt(8)
	s_waitcnt lgkmcnt(0)
	s_barrier
	s_setprio 1
	v_mfma_f32_16x16x32_bf16 v[60:63], v[140:143], v[214:217], v[60:63]
	v_mfma_f32_16x16x32_bf16 v[60:63], v[166:169], v[218:221], v[60:63]
	v_mfma_f32_16x16x32_bf16 v[44:47], v[140:143], v[222:225], v[44:47]
	v_mfma_f32_16x16x32_bf16 v[44:47], v[166:169], v[226:229], v[44:47]
	v_mfma_f32_16x16x32_bf16 v[28:31], v[140:143], v[230:233], v[28:31]
	v_mfma_f32_16x16x32_bf16 v[28:31], v[166:169], v[234:237], v[28:31]
	v_mfma_f32_16x16x32_bf16 v[12:15], v[140:143], v[238:241], v[12:15]
	v_mfma_f32_16x16x32_bf16 v[12:15], v[166:169], v[242:245], v[12:15]
	v_mfma_f32_16x16x32_bf16 v[56:59], v[170:173], v[214:217], v[56:59]
	v_mfma_f32_16x16x32_bf16 v[56:59], v[174:177], v[218:221], v[56:59]
	v_mfma_f32_16x16x32_bf16 v[40:43], v[170:173], v[222:225], v[40:43]
	v_mfma_f32_16x16x32_bf16 v[40:43], v[174:177], v[226:229], v[40:43]
	v_mfma_f32_16x16x32_bf16 v[24:27], v[170:173], v[230:233], v[24:27]
	v_mfma_f32_16x16x32_bf16 v[24:27], v[174:177], v[234:237], v[24:27]
	v_mfma_f32_16x16x32_bf16 v[8:11], v[170:173], v[238:241], v[8:11]
	v_mfma_f32_16x16x32_bf16 v[8:11], v[174:177], v[242:245], v[8:11]
	v_mfma_f32_16x16x32_bf16 v[52:55], v[178:181], v[214:217], v[52:55]
	v_mfma_f32_16x16x32_bf16 v[52:55], v[182:185], v[218:221], v[52:55]
	v_mfma_f32_16x16x32_bf16 v[36:39], v[178:181], v[222:225], v[36:39]
	v_mfma_f32_16x16x32_bf16 v[36:39], v[182:185], v[226:229], v[36:39]
	v_mfma_f32_16x16x32_bf16 v[20:23], v[178:181], v[230:233], v[20:23]
	v_mfma_f32_16x16x32_bf16 v[20:23], v[182:185], v[234:237], v[20:23]
	v_mfma_f32_16x16x32_bf16 v[4:7], v[178:181], v[238:241], v[4:7]
	v_mfma_f32_16x16x32_bf16 v[4:7], v[182:185], v[242:245], v[4:7]
	v_mfma_f32_16x16x32_bf16 v[48:51], v[186:189], v[214:217], v[48:51]
	v_mfma_f32_16x16x32_bf16 v[48:51], v[210:213], v[218:221], v[48:51]
	v_mfma_f32_16x16x32_bf16 v[32:35], v[186:189], v[222:225], v[32:35]
	v_mfma_f32_16x16x32_bf16 v[32:35], v[210:213], v[226:229], v[32:35]
	v_mfma_f32_16x16x32_bf16 v[16:19], v[186:189], v[230:233], v[16:19]
	v_mfma_f32_16x16x32_bf16 v[16:19], v[210:213], v[234:237], v[16:19]
	v_mfma_f32_16x16x32_bf16 v[0:3], v[186:189], v[238:241], v[0:3]
	v_mfma_f32_16x16x32_bf16 v[0:3], v[210:213], v[242:245], v[0:3]
	s_setprio 0
	s_barrier
; #define PG8_STAGE(bufoff, gbase, voff) do { _Pragma("unroll") for (int _i = 0; _i < 2; ++_i) \
;         __builtin_amdgcn_global_load_lds((const unsigned*)((const char*)(gbase) + (voff)[_i]), (PG8_LAS unsigned*)(lds + (bufoff) + ldsw + _i * 8192), 16, 0, 0); } while (0)
; #define PG8_LDA(dst, b, h) do { _Pragma("unroll") for (int m = 0; m < 4; ++m) _Pragma("unroll") for (int k = 0; k < 2; ++k) dst[m][k] = *(const PG8_LAS bf16x8*)(lds + PG8_SA(b, h) + aoff + m * 2048 + k * 1024); } while (0)
; #define PG8_LDB(dst, b, h) do { _Pragma("unroll") for (int n = 0; n < 2; ++n) _Pragma("unroll") for (int k = 0; k < 2; ++k) dst[n][k] = *(const PG8_LAS bf16x8*)(lds + PG8_SB(b, h) + boff + n * 2048 + k * 1024); } while (0)
; #define PG8_MMA(ai, bj, At, Bt) do { __builtin_amdgcn_s_setprio(1); _Pragma("unroll") for (int m = 0; m < 4; ++m) _Pragma("unroll") for (int n = 0; n < 2; ++n) _Pragma("unroll") for (int k = 0; k < 2; ++k) \
;         acc[ai][bj][m][n] = __builtin_amdgcn_mfma_f32_16x16x32_bf16(Bt[n][k], At[m][k], acc[ai][bj][m][n], 0, 0, 0); __builtin_amdgcn_s_setprio(0); } while (0)
; #define PG8_WAIT_V(n) asm volatile("s_waitcnt vmcnt(" #n ")" ::: "memory")
; #define PG8_WAIT_L(n) asm volatile("s_waitcnt lgkmcnt(" #n ")" ::: "memory")
; #define PG8_BAR __builtin_amdgcn_s_barrier()
; #define PG8_SCHED __builtin_amdgcn_sched_barrier(0)
; template <class Epi, class Sched, bool ALIGN_EPI = false, bool SP2 = false>
; __device__ __forceinline__ void gemm_phase(PG8_LAS unsigned char* lds, const Gemm g, const Sched& S, const Epi& E) {
;     ...
;             PG8_LDB(B0, 1, 0); PG8_LDB(B1, 1, 1); PG8_SCHED; PG8_LDA(At, 1, 0); PG8_STAGE(PG8_SA(0, 1), a2 + hstep, voffA);
;             PG8_WAIT_V(8); PG8_WAIT_L(0); PG8_BAR; PG8_MMA(0, 0, At, B0); PG8_MMA(0, 1, At, B1); PG8_BAR; PG8_SCHED;
;             PG8_LDA(At, 1, 1); PG8_STAGE(PG8_SB(1, 0), b3, voffB); PG8_STAGE(PG8_SB(1, 1), b3 + hstep, voffB); PG8_STAGE(PG8_SA(1, 0), a3, voffA);
;             PG8_WAIT_V(8); PG8_WAIT_L(0); PG8_BAR; PG8_MMA(1, 0, At, B0); PG8_MMA(1, 1, At, B1); PG8_BAR; PG8_SCHED;
	ds_read_b128 v[140:143], v254 offset:32768
	ds_read_b128 v[166:169], v254 offset:33792
	ds_read_b128 v[170:173], v254 offset:34816
	ds_read_b128 v[174:177], v254 offset:35840
	ds_read_b128 v[178:181], v254 offset:49152
	ds_read_b128 v[182:185], v254 offset:50176
	ds_read_b128 v[186:189], v254 offset:51200
	ds_read_b128 v[210:213], v254 offset:52224
	s_add_u32 s4, s4, 0x40000
	s_addc_u32 s5, s5, 0
	s_mov_b32 m0, s38
	ds_read_b128 v[214:217], v163 offset:32768
	ds_read_b128 v[218:221], v163 offset:33792
	ds_read_b128 v[222:225], v163 offset:34816
	ds_read_b128 v[226:229], v163 offset:35840
	ds_read_b128 v[230:233], v163 offset:36864
	ds_read_b128 v[234:237], v163 offset:37888
	ds_read_b128 v[238:241], v163 offset:38912
	ds_read_b128 v[242:245], v163 offset:39936
	global_load_lds_dwordx4 v134, s[4:5]
	s_mov_b32 m0, s39
	s_nop 0
	global_load_lds_dwordx4 v130, s[4:5]
	s_waitcnt vmcnt(8)
	s_waitcnt lgkmcnt(0)
	s_barrier
	s_setprio 1
	v_mfma_f32_16x16x32_bf16 v[124:127], v[140:143], v[214:217], v[124:127]
	v_mfma_f32_16x16x32_bf16 v[124:127], v[166:169], v[218:221], v[124:127]
	v_mfma_f32_16x16x32_bf16 v[108:111], v[140:143], v[222:225], v[108:111]
	v_mfma_f32_16x16x32_bf16 v[108:111], v[166:169], v[226:229], v[108:111]
	v_mfma_f32_16x16x32_bf16 v[92:95], v[140:143], v[230:233], v[92:95]
	v_mfma_f32_16x16x32_bf16 v[92:95], v[166:169], v[234:237], v[92:95]
	v_mfma_f32_16x16x32_bf16 v[76:79], v[140:143], v[238:241], v[76:79]
	v_mfma_f32_16x16x32_bf16 v[76:79], v[166:169], v[242:245], v[76:79]
	v_mfma_f32_16x16x32_bf16 v[120:123], v[170:173], v[214:217], v[120:123]
	v_mfma_f32_16x16x32_bf16 v[120:123], v[174:177], v[218:221], v[120:123]
	v_mfma_f32_16x16x32_bf16 v[104:107], v[170:173], v[222:225], v[104:107]
	v_mfma_f32_16x16x32_bf16 v[104:107], v[174:177], v[226:229], v[104:107]
	v_mfma_f32_16x16x32_bf16 v[88:91], v[170:173], v[230:233], v[88:91]
	v_mfma_f32_16x16x32_bf16 v[88:91], v[174:177], v[234:237], v[88:91]
	v_mfma_f32_16x16x32_bf16 v[72:75], v[170:173], v[238:241], v[72:75]
	v_mfma_f32_16x16x32_bf16 v[72:75], v[174:177], v[242:245], v[72:75]
	v_mfma_f32_16x16x32_bf16 v[116:119], v[178:181], v[214:217], v[116:119]
	v_mfma_f32_16x16x32_bf16 v[116:119], v[182:185], v[218:221], v[116:119]
	v_mfma_f32_16x16x32_bf16 v[100:103], v[178:181], v[222:225], v[100:103]
	v_mfma_f32_16x16x32_bf16 v[100:103], v[182:185], v[226:229], v[100:103]
	v_mfma_f32_16x16x32_bf16 v[84:87], v[178:181], v[230:233], v[84:87]
	v_mfma_f32_16x16x32_bf16 v[84:87], v[182:185], v[234:237], v[84:87]
	v_mfma_f32_16x16x32_bf16 v[68:71], v[178:181], v[238:241], v[68:71]
	v_mfma_f32_16x16x32_bf16 v[68:71], v[182:185], v[242:245], v[68:71]
	v_mfma_f32_16x16x32_bf16 v[112:115], v[186:189], v[214:217], v[112:115]
	v_mfma_f32_16x16x32_bf16 v[112:115], v[210:213], v[218:221], v[112:115]
	v_mfma_f32_16x16x32_bf16 v[96:99], v[186:189], v[222:225], v[96:99]
	v_mfma_f32_16x16x32_bf16 v[96:99], v[210:213], v[226:229], v[96:99]
	v_mfma_f32_16x16x32_bf16 v[80:83], v[186:189], v[230:233], v[80:83]
	v_mfma_f32_16x16x32_bf16 v[80:83], v[210:213], v[234:237], v[80:83]
	v_mfma_f32_16x16x32_bf16 v[64:67], v[186:189], v[238:241], v[64:67]
	v_mfma_f32_16x16x32_bf16 v[64:67], v[210:213], v[242:245], v[64:67]
	s_setprio 0
	s_barrier
	s_mov_b32 m0, s43
	s_add_u32 s2, s2, 0x40080
	s_addc_u32 s3, s3, 0
	ds_read_b128 v[214:217], v163 offset:49152
	ds_read_b128 v[218:221], v163 offset:50176
	ds_read_b128 v[222:225], v163 offset:51200
	ds_read_b128 v[226:229], v163 offset:52224
	ds_read_b128 v[230:233], v163 offset:53248
	ds_read_b128 v[234:237], v163 offset:54272
	ds_read_b128 v[238:241], v163 offset:55296
	ds_read_b128 v[242:245], v163 offset:56320
	s_add_u32 s98, s2, 0xfffc0000
	s_addc_u32 s99, s3, -1
	global_load_lds_dwordx4 v132, s[98:99]
	s_mov_b32 m0, s44
	s_nop 0
	global_load_lds_dwordx4 v128, s[98:99]
	s_mov_b32 m0, s48
	s_nop 0
	global_load_lds_dwordx4 v132, s[2:3]
	s_mov_b32 m0, s49
	s_nop 0
	global_load_lds_dwordx4 v128, s[2:3]
	s_mov_b32 m0, s45
	s_nop 0
	s_add_u32 s100, s4, 0xfffc0080
	s_addc_u32 s101, s5, -1
	global_load_lds_dwordx4 v134, s[100:101]
	s_mov_b32 m0, s47
	s_nop 0
	global_load_lds_dwordx4 v130, s[100:101]
	s_waitcnt vmcnt(8)
	s_waitcnt lgkmcnt(0)
	s_barrier
	s_setprio 1
	v_mfma_f32_16x16x32_bf16 v[60:63], v[140:143], v[214:217], v[60:63]
	v_mfma_f32_16x16x32_bf16 v[60:63], v[166:169], v[218:221], v[60:63]
	v_mfma_f32_16x16x32_bf16 v[44:47], v[140:143], v[222:225], v[44:47]
	v_mfma_f32_16x16x32_bf16 v[44:47], v[166:169], v[226:229], v[44:47]
	v_mfma_f32_16x16x32_bf16 v[28:31], v[140:143], v[230:233], v[28:31]
	v_mfma_f32_16x16x32_bf16 v[28:31], v[166:169], v[234:237], v[28:31]
	v_mfma_f32_16x16x32_bf16 v[12:15], v[140:143], v[238:241], v[12:15]
	v_mfma_f32_16x16x32_bf16 v[12:15], v[166:169], v[242:245], v[12:15]
	v_mfma_f32_16x16x32_bf16 v[56:59], v[170:173], v[214:217], v[56:59]
	v_mfma_f32_16x16x32_bf16 v[56:59], v[174:177], v[218:221], v[56:59]
	v_mfma_f32_16x16x32_bf16 v[40:43], v[170:173], v[222:225], v[40:43]
	v_mfma_f32_16x16x32_bf16 v[40:43], v[174:177], v[226:229], v[40:43]
	v_mfma_f32_16x16x32_bf16 v[24:27], v[170:173], v[230:233], v[24:27]
	v_mfma_f32_16x16x32_bf16 v[24:27], v[174:177], v[234:237], v[24:27]
	v_mfma_f32_16x16x32_bf16 v[8:11], v[170:173], v[238:241], v[8:11]
	v_mfma_f32_16x16x32_bf16 v[8:11], v[174:177], v[242:245], v[8:11]
	v_mfma_f32_16x16x32_bf16 v[52:55], v[178:181], v[214:217], v[52:55]
	v_mfma_f32_16x16x32_bf16 v[52:55], v[182:185], v[218:221], v[52:55]
	v_mfma_f32_16x16x32_bf16 v[36:39], v[178:181], v[222:225], v[36:39]
	v_mfma_f32_16x16x32_bf16 v[36:39], v[182:185], v[226:229], v[36:39]
	v_mfma_f32_16x16x32_bf16 v[20:23], v[178:181], v[230:233], v[20:23]
	v_mfma_f32_16x16x32_bf16 v[20:23], v[182:185], v[234:237], v[20:23]
	v_mfma_f32_16x16x32_bf16 v[4:7], v[178:181], v[238:241], v[4:7]
	v_mfma_f32_16x16x32_bf16 v[4:7], v[182:185], v[242:245], v[4:7]
	v_mfma_f32_16x16x32_bf16 v[48:51], v[186:189], v[214:217], v[48:51]
	v_mfma_f32_16x16x32_bf16 v[48:51], v[210:213], v[218:221], v[48:51]
	v_mfma_f32_16x16x32_bf16 v[32:35], v[186:189], v[222:225], v[32:35]
	v_mfma_f32_16x16x32_bf16 v[32:35], v[210:213], v[226:229], v[32:35]
	v_mfma_f32_16x16x32_bf16 v[16:19], v[186:189], v[230:233], v[16:19]
	v_mfma_f32_16x16x32_bf16 v[16:19], v[210:213], v[234:237], v[16:19]
	v_mfma_f32_16x16x32_bf16 v[0:3], v[186:189], v[238:241], v[0:3]
	v_mfma_f32_16x16x32_bf16 v[0:3], v[210:213], v[242:245], v[0:3]
	s_setprio 0
	s_barrier
	s_add_i32 s55, s55, 2
	s_add_u32 s0, s0, 0x100
	s_addc_u32 s1, s1, 0
	s_add_u32 s53, s53, 0x100
	s_addc_u32 s54, s54, 0
	s_cmp_gt_u32 s55, 13
	s_cbranch_scc0 .LBB0_1042
	s_and_b64 vcc, exec, s[18:19]
	s_cbranch_vccz .LBB0_1045
	s_barrier
